# 3-stage LDS ring fed by direct global->LDS loads (no VGPR staging, no LDS stores) for MLP1 x2, P6, MLP2-L1 GEMM loops; tile stream continues across items
# speedup vs baseline: 1.0791x; 1.0166x over previous
.LBB0_626:
	s_or_b64 exec, exec, s[0:1]
	s_add_u32 s60, s76, 0x200000
	s_mul_i32 s0, s56, 0x210
	s_addc_u32 s61, s77, 0
	s_addk_i32 s0, 0x210
	s_mul_i32 s29, s56, 0x42
	s_lshr_b32 s0, s0, 3
	s_sub_i32 s33, s0, s29
	v_mov_b32_e32 v0, v170
	s_cmp_ge_i32 s62, s33
	s_mul_i32 s28, s56, 0x840
	s_waitcnt lgkmcnt(0)
	s_barrier
	s_cbranch_scc1 .LBB0_650
	s_waitcnt vmcnt(0)
	v_lshlrev_b32_e32 v2, 4, v0
	v_and_b32_e32 v168, 0x70, v2
	v_mov_b32_e32 v169, 0
	v_lshl_add_u64 v[2:3], s[76:77], 0, v[168:169]
	s_mov_b64 s[0:1], 0x880000
	v_lshl_add_u64 v[174:175], v[2:3], 0, s[0:1]
	v_lshrrev_b32_e32 v2, 4, v0
	v_and_b32_e32 v4, 15, v0
	v_xor_b32_e32 v2, v2, v0
	v_ashrrev_i32_e32 v203, 3, v0
	v_bfe_u32 v5, v0, 6, 1
	v_ashrrev_i32_e32 v6, 7, v0
	v_lshlrev_b32_e32 v2, 4, v2
	v_lshlrev_b32_e32 v4, 7, v4
	v_lshlrev_b32_e32 v3, 7, v203
	v_and_b32_e32 v2, 0x70, v2
	s_add_i32 s0, 16, 0x10000
	v_lshl_or_b32 v7, v6, 13, v4
	v_lshl_or_b32 v4, v5, 13, v4
	v_bfe_u32 v1, v0, 4, 2
	v_add3_u32 v205, s0, v3, v2
	v_add_u32_e32 v8, s0, v4
	v_bfe_u32 v9, v0, 1, 3
	s_add_i32 s0, 16, 0x14000
	v_add3_u32 v204, 16, v3, v2
	v_xor_b32_e32 v10, v1, v9
	v_bitop3_b32 v1, v1, v9, 4 bitop3:0x36
	v_add3_u32 v210, s0, v3, v2
	v_add_u32_e32 v2, s0, v4
	s_mul_i32 s0, s56, 0x2100
	s_lshl_b32 s1, s62, 7
	v_and_b32_e32 v202, 63, v0
	v_add_u32_e32 v7, 16, v7
	v_lshlrev_b32_e32 v9, 4, v10
	v_lshlrev_b32_e32 v1, 4, v1
	v_and_b32_e32 v0, 7, v0
	s_add_i32 s19, s0, s1
	s_lshl_b32 s0, s62, 5
	v_lshl_add_u64 v[172:173], s[40:41], 0, v[168:169]
	s_mov_b32 s18, 0x10000
	v_add_u32_e32 v206, v7, v9
	v_add_u32_e32 v207, v8, v9
	v_add_u32_e32 v208, v7, v1
	v_add_u32_e32 v209, v8, v1
	v_add_u32_e32 v211, v2, v9
	v_add_u32_e32 v212, v2, v1
	v_lshlrev_b32_e32 v213, 6, v6
	v_lshlrev_b32_e32 v214, 6, v5
	v_lshlrev_b32_e32 v176, 4, v0
	v_mov_b32_e32 v177, v169
	s_lshl_b32 s20, s51, 7
	s_add_i32 s21, s28, s0
	s_lshl_b32 s22, s51, 5
	s_mov_b64 s[12:13], 0
	s_mov_b32 s23, 0x20000
	s_mov_b64 s[2:3], 0x20080
	s_mov_b64 s[4:5], 0x20000
	s_mov_b64 s[6:7], 0x60000
	s_mov_b64 s[8:9], 0x100
	s_mov_b32 s24, 0x3e0f83e1
	s_movk_i32 s25, 0x1fff
	s_movk_i32 s26, 0x2000
	s_movk_i32 s27, 0x3000
	s_mov_b64 s[10:11], 0x2000
	s_movk_i32 s30, 0xe000
	s_movk_i32 s31, 0x1000
	s_mov_b32 s34, 0x11000
	s_mov_b32 s35, 0x12000
	s_mov_b32 s36, 0x13000
	s_mov_b32 s37, 0x21000
	s_mov_b32 s38, 0x22000
	s_mov_b32 s39, 0x23000
	s_mov_b32 s40, 0x30000
	s_mov_b32 s41, 0x31000
	s_mov_b32 s42, 0x32000
	s_mov_b32 s43, 0x33000
	v_mov_b32_e32 v215, 0x3000
	s_mov_b32 s44, s62
	s_mov_b32 s8, 0
	s_mov_b32 s9, 0x18000
	s_branch .LBB0_629

.LBB0_629:
	s_add_i32 s0, s44, s29
	s_lshl_b32 s1, s0, 5
	s_lshl_b32 s0, s0, 7
	s_and_b32 s45, s1, 0x7fffff00
	s_and_b32 s46, s0, 0x380
	v_add_u32_e32 v48, s45, v203
	v_add_u32_e32 v50, s46, v203
	v_ashrrev_i32_e32 v49, 31, v48
	v_ashrrev_i32_e32 v51, 31, v50
	v_lshlrev_b64 v[48:49], 11, v[48:49]
	v_lshlrev_b64 v[50:51], 11, v[50:51]
	v_lshl_add_u64 v[48:49], v[172:173], 0, v[48:49]
	v_lshl_add_u64 v[50:51], v[174:175], 0, v[50:51]
	v_writelane_b32 v250, s12, 4
	s_and_b64 vcc, exec, s[12:13]
	s_cbranch_vccnz .LBB0_631
	v_add_co_u32_e32 v4, vcc, 0x20000, v48
	s_nop 1
	v_addc_co_u32_e32 v5, vcc, 0, v49, vcc
	v_add_co_u32_e32 v8, vcc, 0x40000, v48
	s_nop 1
	v_addc_co_u32_e32 v9, vcc, 0, v49, vcc
	v_add_co_u32_e32 v12, vcc, 0x60000, v48
	s_nop 1
	v_addc_co_u32_e32 v13, vcc, 0, v49, vcc
	v_add_co_u32_e32 v24, vcc, 0x20000, v50
	s_nop 1
	v_addc_co_u32_e32 v25, vcc, 0, v51, vcc
	s_nop 0
	s_nop 0
	s_nop 0
	s_nop 0
	s_nop 0
	s_nop 0
	s_nop 0
.LBB0_631:
	v_add_co_u32_e32 v20, vcc, s23, v50
	s_and_b32 s0, s19, 0x380
	s_nop 0
	v_addc_co_u32_e32 v21, vcc, 0, v51, vcc
	v_add_co_u32_e32 v32, vcc, 0x60000, v48
	s_nop 0
	v_addc_co_u32_e32 v33, vcc, 0, v49, vcc
	v_add_co_u32_e32 v32, vcc, 0x40000, v48
	v_add_u32_e32 v52, s0, v203
	s_nop 0
	v_addc_co_u32_e32 v33, vcc, 0, v49, vcc
	v_add_co_u32_e32 v36, vcc, 0x20000, v48
	s_nop 0
	v_addc_co_u32_e32 v37, vcc, 0, v49, vcc
	s_nop 0
	v_ashrrev_i32_e32 v53, 31, v52
	s_and_b32 s0, s21, 0x7fffff00
	s_add_i32 s44, s44, s51
	v_lshlrev_b64 v[52:53], 11, v[52:53]
	s_cmp_ge_i32 s44, s33
	v_lshl_add_u64 v[178:179], s[76:77], 0, v[52:53]
	v_add_u32_e32 v52, s0, v203
	s_cselect_b64 s[0:1], -1, 0
	s_add_i32 s16, s44, s29
	s_cmp_lt_i32 s44, s33
	s_cselect_b64 s[12:13], -1, 0
	s_and_b64 s[14:15], s[12:13], exec
	s_cselect_b32 s14, s16, 0
	s_lshl_b32 s98, s14, 5
	s_and_b32 s98, s98, 0x7fffff00
	s_lshl_b32 s100, s14, 7
	s_and_b32 s100, s100, 0x380
	s_lshl_b32 s98, s98, 11
	s_add_u32 s98, s76, s98
	s_addc_u32 s99, s77, 0
	s_add_u32 s98, s98, 0xac00000
	s_addc_u32 s99, s99, 0
	s_lshl_b32 s100, s100, 11
	s_add_u32 s100, s76, s100
	s_addc_u32 s101, s77, 0
	s_add_u32 s100, s100, 0x880000
	s_addc_u32 s101, s101, 0
	v_writelane_b32 v250, s98, 0
	v_writelane_b32 v250, s99, 1
	v_writelane_b32 v250, s100, 2
	v_writelane_b32 v250, s101, 3
	v_ashrrev_i32_e32 v53, 31, v52
	s_lshl_b32 s15, s14, 5
	v_lshlrev_b64 v[52:53], 11, v[52:53]
	s_and_b32 s15, s15, 0x7fffff00
	v_lshl_add_u64 v[180:181], s[76:77], 0, v[52:53]
	v_add_u32_e32 v52, s15, v203
	s_lshl_b32 s14, s14, 7
	v_ashrrev_i32_e32 v53, 31, v52
	s_and_b32 s14, s14, 0x380
	v_lshlrev_b64 v[52:53], 11, v[52:53]
	v_add_u32_e32 v54, s14, v203
	v_ashrrev_i32_e32 v55, 31, v54
	v_lshl_add_u64 v[182:183], v[172:173], 0, v[52:53]
	s_mov_b64 s[14:15], 0x40080
	v_lshlrev_b64 v[54:55], 11, v[54:55]
	v_lshl_add_u64 v[188:189], v[182:183], 0, s[14:15]
	s_mov_b64 s[14:15], 0x60080
	v_lshl_add_u64 v[184:185], v[174:175], 0, v[54:55]
	v_lshl_add_u64 v[190:191], v[182:183], 0, s[14:15]
	s_mov_b64 s[14:15], 0x40000
	v_mov_b32_e32 v48, 0
	s_mov_b32 s47, 0
	v_lshl_add_u64 v[186:187], v[182:183], 0, s[2:3]
	v_lshl_add_u64 v[192:193], v[184:185], 0, s[2:3]
	v_lshl_add_u64 v[194:195], v[182:183], 0, s[4:5]
	v_lshl_add_u64 v[196:197], v[182:183], 0, s[14:15]
	v_lshl_add_u64 v[198:199], v[182:183], 0, s[6:7]
	v_lshl_add_u64 v[200:201], v[184:185], 0, s[4:5]
	v_mov_b32_e32 v49, v48
	v_mov_b32_e32 v50, v48
	v_mov_b32_e32 v51, v48
	v_mov_b32_e32 v52, v48
	v_mov_b32_e32 v53, v48
	v_mov_b32_e32 v54, v48
	v_mov_b32_e32 v55, v48
	v_mov_b32_e32 v56, v48
	v_mov_b32_e32 v57, v48
	v_mov_b32_e32 v58, v48
	v_mov_b32_e32 v59, v48
	v_mov_b32_e32 v60, v48
	v_mov_b32_e32 v61, v48
	v_mov_b32_e32 v62, v48
	v_mov_b32_e32 v63, v48
	v_mov_b32_e32 v64, v48
	v_mov_b32_e32 v65, v48
	v_mov_b32_e32 v66, v48
	v_mov_b32_e32 v67, v48
	v_mov_b32_e32 v68, v48
	v_mov_b32_e32 v69, v48
	v_mov_b32_e32 v70, v48
	v_mov_b32_e32 v71, v48
	v_mov_b32_e32 v72, v48
	v_mov_b32_e32 v73, v48
	v_mov_b32_e32 v74, v48
	v_mov_b32_e32 v75, v48
	v_mov_b32_e32 v76, v48
	v_mov_b32_e32 v77, v48
	v_mov_b32_e32 v78, v48
	v_mov_b32_e32 v79, v48
	v_mov_b32_e32 v80, v48
	v_mov_b32_e32 v81, v48
	v_mov_b32_e32 v82, v48
	v_mov_b32_e32 v83, v48
	v_mov_b32_e32 v84, v48
	v_mov_b32_e32 v85, v48
	v_mov_b32_e32 v86, v48
	v_mov_b32_e32 v87, v48
	v_mov_b32_e32 v88, v48
	v_mov_b32_e32 v89, v48
	v_mov_b32_e32 v90, v48
	v_mov_b32_e32 v91, v48
	v_mov_b32_e32 v92, v48
	v_mov_b32_e32 v93, v48
	v_mov_b32_e32 v94, v48
	v_mov_b32_e32 v95, v48
	v_mov_b32_e32 v96, v48
	v_mov_b32_e32 v97, v48
	v_mov_b32_e32 v98, v48
	v_mov_b32_e32 v99, v48
	v_mov_b32_e32 v100, v48
	v_mov_b32_e32 v101, v48
	v_mov_b32_e32 v102, v48
	v_mov_b32_e32 v103, v48
	v_mov_b32_e32 v104, v48
	v_mov_b32_e32 v105, v48
	v_mov_b32_e32 v106, v48
	v_mov_b32_e32 v107, v48
	v_mov_b32_e32 v108, v48
	v_mov_b32_e32 v109, v48
	v_mov_b32_e32 v110, v48
	v_mov_b32_e32 v111, v48
	v_lshrrev_b32_e32 v7, 1, v203
	v_lshrrev_b32_e32 v6, 4, v176
	v_xor_b32_e32 v7, v7, v6
	v_and_b32_e32 v7, 7, v7
	v_lshlrev_b32_e32 v7, 4, v7
	v_lshl_add_u32 v0, v203, 11, v7
	v_add_u32_e32 v1, 0x20000, v0
	v_add_u32_e32 v2, 0x40000, v0
	v_add_u32_e32 v3, 0x60000, v0
	v_mov_b32_e32 v4, v0
	v_add_u32_e32 v5, 0x20000, v4
	v_lshrrev_b32_e32 v6, 3, v203
	v_lshl_add_u32 v6, v6, 10, 16
	v_add_u32_e32 v10, 0xffff8000, v207
	v_add_u32_e32 v11, 0xffff8000, v209
	v_readlane_b32 vcc_hi, v250, 4
	s_lshl_b32 s98, s45, 11
	s_add_u32 s98, s76, s98
	s_addc_u32 s99, s77, 0
	s_add_u32 s98, s98, 0xac00000
	s_addc_u32 s99, s99, 0
	s_lshl_b32 s100, s46, 11
	s_add_u32 s100, s76, s100
	s_addc_u32 s101, s77, 0
	s_add_u32 s100, s100, 0x880000
	s_addc_u32 s101, s101, 0
	s_cmp_lg_u32 vcc_hi, 0
	s_cbranch_scc1 .Lmyb_primed
	v_readfirstlane_b32 vcc_lo, v6
	s_nop 0
	s_add_u32 vcc_lo, vcc_lo, s8
	s_mov_b32 m0, vcc_lo
	s_nop 0
	global_load_lds_dwordx4 v0, s[98:99]
	s_add_u32 m0, m0, 0x2000
	s_nop 0
	global_load_lds_dwordx4 v1, s[98:99]
	s_add_u32 m0, m0, 0x2000
	s_nop 0
	global_load_lds_dwordx4 v2, s[98:99]
	s_add_u32 m0, m0, 0x2000
	s_nop 0
	global_load_lds_dwordx4 v3, s[98:99]
	s_add_u32 m0, vcc_lo, 0x8000
	s_nop 0
	global_load_lds_dwordx4 v4, s[100:101]
	s_add_u32 m0, m0, 0x2000
	s_nop 0
	global_load_lds_dwordx4 v5, s[100:101]
	s_add_u32 s98, s98, 0x80
	s_addc_u32 s99, s99, 0
	s_add_u32 s100, s100, 0x80
	s_addc_u32 s101, s101, 0
	s_add_u32 vcc_hi, s8, 0xc000
	s_sub_u32 vcc_lo, vcc_hi, 0x24000
	s_cselect_b32 vcc_hi, vcc_hi, vcc_lo
	v_readfirstlane_b32 vcc_lo, v6
	s_nop 0
	s_add_u32 vcc_lo, vcc_lo, vcc_hi
	s_mov_b32 m0, vcc_lo
	s_nop 0
	global_load_lds_dwordx4 v0, s[98:99]
	s_add_u32 m0, m0, 0x2000
	s_nop 0
	global_load_lds_dwordx4 v1, s[98:99]
	s_add_u32 m0, m0, 0x2000
	s_nop 0
	global_load_lds_dwordx4 v2, s[98:99]
	s_add_u32 m0, m0, 0x2000
	s_nop 0
	global_load_lds_dwordx4 v3, s[98:99]
	s_add_u32 m0, vcc_lo, 0x8000
	s_nop 0
	global_load_lds_dwordx4 v4, s[100:101]
	s_add_u32 m0, m0, 0x2000
	s_nop 0
	global_load_lds_dwordx4 v5, s[100:101]
	s_add_u32 s98, s98, 0x80
	s_addc_u32 s99, s99, 0
	s_add_u32 s100, s100, 0x80
	s_addc_u32 s101, s101, 0
	s_branch .LBB0_633
.Lmyb_primed:
	s_add_u32 s98, s98, 0x100
	s_addc_u32 s99, s99, 0
	s_add_u32 s100, s100, 0x100
	s_addc_u32 s101, s101, 0
	s_branch .LBB0_633
.LBB0_633:
	s_waitcnt vmcnt(6) lgkmcnt(0)
	s_barrier
	v_add_u32_e32 v12, s8, v206
	v_add_u32_e32 v13, s8, v10
	v_add_u32_e32 v14, s8, v208
	v_add_u32_e32 v15, s8, v11
	v_readfirstlane_b32 vcc_lo, v6
	s_nop 0
	s_add_u32 vcc_lo, vcc_lo, s9
	ds_read_b128 v[112:115], v12
	ds_read_b128 v[116:119], v12 offset:2048
	ds_read_b128 v[120:123], v12 offset:4096
	ds_read_b128 v[124:127], v12 offset:6144
	ds_read_b128 v[128:131], v13
	ds_read_b128 v[132:135], v13 offset:2048
	ds_read_b128 v[136:139], v13 offset:4096
	ds_read_b128 v[140:143], v13 offset:6144
	s_mov_b32 m0, vcc_lo
	s_nop 0
	global_load_lds_dwordx4 v0, s[98:99]
	s_add_u32 m0, m0, 0x2000
	s_nop 0
	global_load_lds_dwordx4 v1, s[98:99]
	s_add_u32 m0, m0, 0x2000
	s_nop 0
	global_load_lds_dwordx4 v2, s[98:99]
	s_add_u32 m0, m0, 0x2000
	s_nop 0
	global_load_lds_dwordx4 v3, s[98:99]
	s_add_u32 m0, vcc_lo, 0x8000
	s_nop 0
	global_load_lds_dwordx4 v4, s[100:101]
	s_add_u32 m0, m0, 0x2000
	s_nop 0
	global_load_lds_dwordx4 v5, s[100:101]
	s_add_u32 s98, s98, 0x80
	s_addc_u32 s99, s99, 0
	s_add_u32 s100, s100, 0x80
	s_addc_u32 s101, s101, 0
	s_waitcnt lgkmcnt(0)
	v_mfma_f32_16x16x32_bf16 v[108:111], v[112:115], v[128:131], v[108:111]
	ds_read_b128 v[144:147], v14
	v_mfma_f32_16x16x32_bf16 v[104:107], v[112:115], v[132:135], v[104:107]
	ds_read_b128 v[148:151], v14 offset:2048
	v_mfma_f32_16x16x32_bf16 v[100:103], v[112:115], v[136:139], v[100:103]
	ds_read_b128 v[152:155], v14 offset:4096
	v_mfma_f32_16x16x32_bf16 v[96:99], v[112:115], v[140:143], v[96:99]
	ds_read_b128 v[156:159], v14 offset:6144
	v_mfma_f32_16x16x32_bf16 v[92:95], v[116:119], v[128:131], v[92:95]
	ds_read_b128 v[160:163], v15
	v_mfma_f32_16x16x32_bf16 v[88:91], v[116:119], v[132:135], v[88:91]
	ds_read_b128 v[164:167], v15 offset:2048
	v_mfma_f32_16x16x32_bf16 v[84:87], v[116:119], v[136:139], v[84:87]
	ds_read_b128 v[216:219], v15 offset:4096
	v_mfma_f32_16x16x32_bf16 v[80:83], v[116:119], v[140:143], v[80:83]
	ds_read_b128 v[228:231], v15 offset:6144
	v_mfma_f32_16x16x32_bf16 v[76:79], v[120:123], v[128:131], v[76:79]
	v_mfma_f32_16x16x32_bf16 v[72:75], v[120:123], v[132:135], v[72:75]
	v_mfma_f32_16x16x32_bf16 v[68:71], v[120:123], v[136:139], v[68:71]
	v_mfma_f32_16x16x32_bf16 v[64:67], v[120:123], v[140:143], v[64:67]
	v_mfma_f32_16x16x32_bf16 v[60:63], v[124:127], v[128:131], v[60:63]
	v_mfma_f32_16x16x32_bf16 v[56:59], v[124:127], v[132:135], v[56:59]
	v_mfma_f32_16x16x32_bf16 v[52:55], v[124:127], v[136:139], v[52:55]
	v_mfma_f32_16x16x32_bf16 v[48:51], v[124:127], v[140:143], v[48:51]
	s_mov_b32 s9, s8
	s_add_u32 s8, s8, 0xc000
	s_sub_u32 vcc_lo, s8, 0x24000
	s_cselect_b32 s8, s8, vcc_lo
	s_mov_b32 s47, 1
.Lmyb_steady:
	s_waitcnt vmcnt(6) lgkmcnt(0)
	s_barrier
	v_add_u32_e32 v12, s8, v206
	v_add_u32_e32 v13, s8, v10
	v_add_u32_e32 v14, s8, v208
	v_add_u32_e32 v15, s8, v11
	v_readfirstlane_b32 vcc_lo, v6
	s_nop 0
	s_add_u32 vcc_lo, vcc_lo, s9
	s_mov_b32 m0, vcc_lo
	v_mfma_f32_16x16x32_bf16 v[108:111], v[144:147], v[160:163], v[108:111]
	ds_read_b128 v[112:115], v12
	global_load_lds_dwordx4 v0, s[98:99]
	s_add_u32 m0, m0, 0x2000
	v_mfma_f32_16x16x32_bf16 v[104:107], v[144:147], v[164:167], v[104:107]
	ds_read_b128 v[116:119], v12 offset:2048
	global_load_lds_dwordx4 v1, s[98:99]
	s_add_u32 m0, m0, 0x2000
	v_mfma_f32_16x16x32_bf16 v[100:103], v[144:147], v[216:219], v[100:103]
	ds_read_b128 v[120:123], v12 offset:4096
	global_load_lds_dwordx4 v2, s[98:99]
	s_add_u32 m0, m0, 0x2000
	v_mfma_f32_16x16x32_bf16 v[96:99], v[144:147], v[228:231], v[96:99]
	ds_read_b128 v[124:127], v12 offset:6144
	global_load_lds_dwordx4 v3, s[98:99]
	s_add_u32 m0, vcc_lo, 0x8000
	v_mfma_f32_16x16x32_bf16 v[92:95], v[148:151], v[160:163], v[92:95]
	ds_read_b128 v[128:131], v13
	global_load_lds_dwordx4 v4, s[100:101]
	s_add_u32 m0, m0, 0x2000
	v_mfma_f32_16x16x32_bf16 v[88:91], v[148:151], v[164:167], v[88:91]
	ds_read_b128 v[132:135], v13 offset:2048
	global_load_lds_dwordx4 v5, s[100:101]
	v_mfma_f32_16x16x32_bf16 v[84:87], v[148:151], v[216:219], v[84:87]
	ds_read_b128 v[136:139], v13 offset:4096
	s_add_u32 s98, s98, 0x80
	s_addc_u32 s99, s99, 0
	s_add_u32 s100, s100, 0x80
	s_addc_u32 s101, s101, 0
	v_mfma_f32_16x16x32_bf16 v[80:83], v[148:151], v[228:231], v[80:83]
	ds_read_b128 v[140:143], v13 offset:6144
	v_mfma_f32_16x16x32_bf16 v[76:79], v[152:155], v[160:163], v[76:79]
	v_mfma_f32_16x16x32_bf16 v[72:75], v[152:155], v[164:167], v[72:75]
	v_mfma_f32_16x16x32_bf16 v[68:71], v[152:155], v[216:219], v[68:71]
	v_mfma_f32_16x16x32_bf16 v[64:67], v[152:155], v[228:231], v[64:67]
	v_mfma_f32_16x16x32_bf16 v[60:63], v[156:159], v[160:163], v[60:63]
	v_mfma_f32_16x16x32_bf16 v[56:59], v[156:159], v[164:167], v[56:59]
	v_mfma_f32_16x16x32_bf16 v[52:55], v[156:159], v[216:219], v[52:55]
	v_mfma_f32_16x16x32_bf16 v[48:51], v[156:159], v[228:231], v[48:51]
	s_waitcnt lgkmcnt(0)
	v_mfma_f32_16x16x32_bf16 v[108:111], v[112:115], v[128:131], v[108:111]
	ds_read_b128 v[144:147], v14
	v_mfma_f32_16x16x32_bf16 v[104:107], v[112:115], v[132:135], v[104:107]
	ds_read_b128 v[148:151], v14 offset:2048
	v_mfma_f32_16x16x32_bf16 v[100:103], v[112:115], v[136:139], v[100:103]
	ds_read_b128 v[152:155], v14 offset:4096
	v_mfma_f32_16x16x32_bf16 v[96:99], v[112:115], v[140:143], v[96:99]
	ds_read_b128 v[156:159], v14 offset:6144
	v_mfma_f32_16x16x32_bf16 v[92:95], v[116:119], v[128:131], v[92:95]
	ds_read_b128 v[160:163], v15
	v_mfma_f32_16x16x32_bf16 v[88:91], v[116:119], v[132:135], v[88:91]
	ds_read_b128 v[164:167], v15 offset:2048
	v_mfma_f32_16x16x32_bf16 v[84:87], v[116:119], v[136:139], v[84:87]
	ds_read_b128 v[216:219], v15 offset:4096
	v_mfma_f32_16x16x32_bf16 v[80:83], v[116:119], v[140:143], v[80:83]
	ds_read_b128 v[228:231], v15 offset:6144
	v_mfma_f32_16x16x32_bf16 v[76:79], v[120:123], v[128:131], v[76:79]
	v_mfma_f32_16x16x32_bf16 v[72:75], v[120:123], v[132:135], v[72:75]
	v_mfma_f32_16x16x32_bf16 v[68:71], v[120:123], v[136:139], v[68:71]
	v_mfma_f32_16x16x32_bf16 v[64:67], v[120:123], v[140:143], v[64:67]
	v_mfma_f32_16x16x32_bf16 v[60:63], v[124:127], v[128:131], v[60:63]
	v_mfma_f32_16x16x32_bf16 v[56:59], v[124:127], v[132:135], v[56:59]
	v_mfma_f32_16x16x32_bf16 v[52:55], v[124:127], v[136:139], v[52:55]
	v_mfma_f32_16x16x32_bf16 v[48:51], v[124:127], v[140:143], v[48:51]
	s_mov_b32 s9, s8
	s_add_u32 s8, s8, 0xc000
	s_sub_u32 vcc_lo, s8, 0x24000
	s_cselect_b32 s8, s8, vcc_lo
	s_add_i32 s47, s47, 1
	s_cmp_lt_u32 s47, 14
	s_cbranch_scc1 .Lmyb_steady
	s_andn2_b64 vcc, exec, s[12:13]
	s_cbranch_vccnz .Lmyb_prelast_n
	v_readlane_b32 s98, v250, 0
	v_readlane_b32 s99, v250, 1
	v_readlane_b32 s100, v250, 2
	v_readlane_b32 s101, v250, 3
	s_waitcnt vmcnt(6) lgkmcnt(0)
	s_barrier
	v_add_u32_e32 v12, s8, v206
	v_add_u32_e32 v13, s8, v10
	v_add_u32_e32 v14, s8, v208
	v_add_u32_e32 v15, s8, v11
	v_readfirstlane_b32 vcc_lo, v6
	s_nop 0
	s_add_u32 vcc_lo, vcc_lo, s9
	s_mov_b32 m0, vcc_lo
	v_mfma_f32_16x16x32_bf16 v[108:111], v[144:147], v[160:163], v[108:111]
	ds_read_b128 v[112:115], v12
	global_load_lds_dwordx4 v0, s[98:99]
	s_add_u32 m0, m0, 0x2000
	v_mfma_f32_16x16x32_bf16 v[104:107], v[144:147], v[164:167], v[104:107]
	ds_read_b128 v[116:119], v12 offset:2048
	global_load_lds_dwordx4 v1, s[98:99]
	s_add_u32 m0, m0, 0x2000
	v_mfma_f32_16x16x32_bf16 v[100:103], v[144:147], v[216:219], v[100:103]
	ds_read_b128 v[120:123], v12 offset:4096
	global_load_lds_dwordx4 v2, s[98:99]
	s_add_u32 m0, m0, 0x2000
	v_mfma_f32_16x16x32_bf16 v[96:99], v[144:147], v[228:231], v[96:99]
	ds_read_b128 v[124:127], v12 offset:6144
	global_load_lds_dwordx4 v3, s[98:99]
	s_add_u32 m0, vcc_lo, 0x8000
	v_mfma_f32_16x16x32_bf16 v[92:95], v[148:151], v[160:163], v[92:95]
	ds_read_b128 v[128:131], v13
	global_load_lds_dwordx4 v4, s[100:101]
	s_add_u32 m0, m0, 0x2000
	v_mfma_f32_16x16x32_bf16 v[88:91], v[148:151], v[164:167], v[88:91]
	ds_read_b128 v[132:135], v13 offset:2048
	global_load_lds_dwordx4 v5, s[100:101]
	v_mfma_f32_16x16x32_bf16 v[84:87], v[148:151], v[216:219], v[84:87]
	ds_read_b128 v[136:139], v13 offset:4096
	s_add_u32 s98, s98, 0x80
	s_addc_u32 s99, s99, 0
	s_add_u32 s100, s100, 0x80
	s_addc_u32 s101, s101, 0
	v_mfma_f32_16x16x32_bf16 v[80:83], v[148:151], v[228:231], v[80:83]
	ds_read_b128 v[140:143], v13 offset:6144
	v_mfma_f32_16x16x32_bf16 v[76:79], v[152:155], v[160:163], v[76:79]
	v_mfma_f32_16x16x32_bf16 v[72:75], v[152:155], v[164:167], v[72:75]
	v_mfma_f32_16x16x32_bf16 v[68:71], v[152:155], v[216:219], v[68:71]
	v_mfma_f32_16x16x32_bf16 v[64:67], v[152:155], v[228:231], v[64:67]
	v_mfma_f32_16x16x32_bf16 v[60:63], v[156:159], v[160:163], v[60:63]
	v_mfma_f32_16x16x32_bf16 v[56:59], v[156:159], v[164:167], v[56:59]
	v_mfma_f32_16x16x32_bf16 v[52:55], v[156:159], v[216:219], v[52:55]
	v_mfma_f32_16x16x32_bf16 v[48:51], v[156:159], v[228:231], v[48:51]
	s_waitcnt lgkmcnt(0)
	v_mfma_f32_16x16x32_bf16 v[108:111], v[112:115], v[128:131], v[108:111]
	ds_read_b128 v[144:147], v14
	v_mfma_f32_16x16x32_bf16 v[104:107], v[112:115], v[132:135], v[104:107]
	ds_read_b128 v[148:151], v14 offset:2048
	v_mfma_f32_16x16x32_bf16 v[100:103], v[112:115], v[136:139], v[100:103]
	ds_read_b128 v[152:155], v14 offset:4096
	v_mfma_f32_16x16x32_bf16 v[96:99], v[112:115], v[140:143], v[96:99]
	ds_read_b128 v[156:159], v14 offset:6144
	v_mfma_f32_16x16x32_bf16 v[92:95], v[116:119], v[128:131], v[92:95]
	ds_read_b128 v[160:163], v15
	v_mfma_f32_16x16x32_bf16 v[88:91], v[116:119], v[132:135], v[88:91]
	ds_read_b128 v[164:167], v15 offset:2048
	v_mfma_f32_16x16x32_bf16 v[84:87], v[116:119], v[136:139], v[84:87]
	ds_read_b128 v[216:219], v15 offset:4096
	v_mfma_f32_16x16x32_bf16 v[80:83], v[116:119], v[140:143], v[80:83]
	ds_read_b128 v[228:231], v15 offset:6144
	v_mfma_f32_16x16x32_bf16 v[76:79], v[120:123], v[128:131], v[76:79]
	v_mfma_f32_16x16x32_bf16 v[72:75], v[120:123], v[132:135], v[72:75]
	v_mfma_f32_16x16x32_bf16 v[68:71], v[120:123], v[136:139], v[68:71]
	v_mfma_f32_16x16x32_bf16 v[64:67], v[120:123], v[140:143], v[64:67]
	v_mfma_f32_16x16x32_bf16 v[60:63], v[124:127], v[128:131], v[60:63]
	v_mfma_f32_16x16x32_bf16 v[56:59], v[124:127], v[132:135], v[56:59]
	v_mfma_f32_16x16x32_bf16 v[52:55], v[124:127], v[136:139], v[52:55]
	v_mfma_f32_16x16x32_bf16 v[48:51], v[124:127], v[140:143], v[48:51]
	s_mov_b32 s9, s8
	s_add_u32 s8, s8, 0xc000
	s_sub_u32 vcc_lo, s8, 0x24000
	s_cselect_b32 s8, s8, vcc_lo
	s_waitcnt vmcnt(6) lgkmcnt(0)
	s_barrier
	v_add_u32_e32 v12, s8, v206
	v_add_u32_e32 v13, s8, v10
	v_add_u32_e32 v14, s8, v208
	v_add_u32_e32 v15, s8, v11
	v_readfirstlane_b32 vcc_lo, v6
	s_nop 0
	s_add_u32 vcc_lo, vcc_lo, s9
	s_mov_b32 m0, vcc_lo
	v_mfma_f32_16x16x32_bf16 v[108:111], v[144:147], v[160:163], v[108:111]
	ds_read_b128 v[112:115], v12
	global_load_lds_dwordx4 v0, s[98:99]
	s_add_u32 m0, m0, 0x2000
	v_mfma_f32_16x16x32_bf16 v[104:107], v[144:147], v[164:167], v[104:107]
	ds_read_b128 v[116:119], v12 offset:2048
	global_load_lds_dwordx4 v1, s[98:99]
	s_add_u32 m0, m0, 0x2000
	v_mfma_f32_16x16x32_bf16 v[100:103], v[144:147], v[216:219], v[100:103]
	ds_read_b128 v[120:123], v12 offset:4096
	global_load_lds_dwordx4 v2, s[98:99]
	s_add_u32 m0, m0, 0x2000
	v_mfma_f32_16x16x32_bf16 v[96:99], v[144:147], v[228:231], v[96:99]
	ds_read_b128 v[124:127], v12 offset:6144
	global_load_lds_dwordx4 v3, s[98:99]
	s_add_u32 m0, vcc_lo, 0x8000
	v_mfma_f32_16x16x32_bf16 v[92:95], v[148:151], v[160:163], v[92:95]
	ds_read_b128 v[128:131], v13
	global_load_lds_dwordx4 v4, s[100:101]
	s_add_u32 m0, m0, 0x2000
	v_mfma_f32_16x16x32_bf16 v[88:91], v[148:151], v[164:167], v[88:91]
	ds_read_b128 v[132:135], v13 offset:2048
	global_load_lds_dwordx4 v5, s[100:101]
	v_mfma_f32_16x16x32_bf16 v[84:87], v[148:151], v[216:219], v[84:87]
	ds_read_b128 v[136:139], v13 offset:4096
	s_add_u32 s98, s98, 0x80
	s_addc_u32 s99, s99, 0
	s_add_u32 s100, s100, 0x80
	s_addc_u32 s101, s101, 0
	v_mfma_f32_16x16x32_bf16 v[80:83], v[148:151], v[228:231], v[80:83]
	ds_read_b128 v[140:143], v13 offset:6144
	v_mfma_f32_16x16x32_bf16 v[76:79], v[152:155], v[160:163], v[76:79]
	v_mfma_f32_16x16x32_bf16 v[72:75], v[152:155], v[164:167], v[72:75]
	v_mfma_f32_16x16x32_bf16 v[68:71], v[152:155], v[216:219], v[68:71]
	v_mfma_f32_16x16x32_bf16 v[64:67], v[152:155], v[228:231], v[64:67]
	v_mfma_f32_16x16x32_bf16 v[60:63], v[156:159], v[160:163], v[60:63]
	v_mfma_f32_16x16x32_bf16 v[56:59], v[156:159], v[164:167], v[56:59]
	v_mfma_f32_16x16x32_bf16 v[52:55], v[156:159], v[216:219], v[52:55]
	v_mfma_f32_16x16x32_bf16 v[48:51], v[156:159], v[228:231], v[48:51]
	s_waitcnt lgkmcnt(0)
	v_mfma_f32_16x16x32_bf16 v[108:111], v[112:115], v[128:131], v[108:111]
	ds_read_b128 v[144:147], v14
	v_mfma_f32_16x16x32_bf16 v[104:107], v[112:115], v[132:135], v[104:107]
	ds_read_b128 v[148:151], v14 offset:2048
	v_mfma_f32_16x16x32_bf16 v[100:103], v[112:115], v[136:139], v[100:103]
	ds_read_b128 v[152:155], v14 offset:4096
	v_mfma_f32_16x16x32_bf16 v[96:99], v[112:115], v[140:143], v[96:99]
	ds_read_b128 v[156:159], v14 offset:6144
	v_mfma_f32_16x16x32_bf16 v[92:95], v[116:119], v[128:131], v[92:95]
	ds_read_b128 v[160:163], v15
	v_mfma_f32_16x16x32_bf16 v[88:91], v[116:119], v[132:135], v[88:91]
	ds_read_b128 v[164:167], v15 offset:2048
	v_mfma_f32_16x16x32_bf16 v[84:87], v[116:119], v[136:139], v[84:87]
	ds_read_b128 v[216:219], v15 offset:4096
	v_mfma_f32_16x16x32_bf16 v[80:83], v[116:119], v[140:143], v[80:83]
	ds_read_b128 v[228:231], v15 offset:6144
	v_mfma_f32_16x16x32_bf16 v[76:79], v[120:123], v[128:131], v[76:79]
	v_mfma_f32_16x16x32_bf16 v[72:75], v[120:123], v[132:135], v[72:75]
	v_mfma_f32_16x16x32_bf16 v[68:71], v[120:123], v[136:139], v[68:71]
	v_mfma_f32_16x16x32_bf16 v[64:67], v[120:123], v[140:143], v[64:67]
	v_mfma_f32_16x16x32_bf16 v[60:63], v[124:127], v[128:131], v[60:63]
	v_mfma_f32_16x16x32_bf16 v[56:59], v[124:127], v[132:135], v[56:59]
	v_mfma_f32_16x16x32_bf16 v[52:55], v[124:127], v[136:139], v[52:55]
	v_mfma_f32_16x16x32_bf16 v[48:51], v[124:127], v[140:143], v[48:51]
	s_mov_b32 s9, s8
	s_add_u32 s8, s8, 0xc000
	s_sub_u32 vcc_lo, s8, 0x24000
	s_cselect_b32 s8, s8, vcc_lo
	s_waitcnt lgkmcnt(0)
	v_mfma_f32_16x16x32_bf16 v[108:111], v[144:147], v[160:163], v[108:111]
	v_mfma_f32_16x16x32_bf16 v[104:107], v[144:147], v[164:167], v[104:107]
	v_mfma_f32_16x16x32_bf16 v[100:103], v[144:147], v[216:219], v[100:103]
	v_mfma_f32_16x16x32_bf16 v[96:99], v[144:147], v[228:231], v[96:99]
	v_mfma_f32_16x16x32_bf16 v[92:95], v[148:151], v[160:163], v[92:95]
	v_mfma_f32_16x16x32_bf16 v[88:91], v[148:151], v[164:167], v[88:91]
	v_mfma_f32_16x16x32_bf16 v[84:87], v[148:151], v[216:219], v[84:87]
	v_mfma_f32_16x16x32_bf16 v[80:83], v[148:151], v[228:231], v[80:83]
	v_mfma_f32_16x16x32_bf16 v[76:79], v[152:155], v[160:163], v[76:79]
	v_mfma_f32_16x16x32_bf16 v[72:75], v[152:155], v[164:167], v[72:75]
	v_mfma_f32_16x16x32_bf16 v[68:71], v[152:155], v[216:219], v[68:71]
	v_mfma_f32_16x16x32_bf16 v[64:67], v[152:155], v[228:231], v[64:67]
	v_mfma_f32_16x16x32_bf16 v[60:63], v[156:159], v[160:163], v[60:63]
	v_mfma_f32_16x16x32_bf16 v[56:59], v[156:159], v[164:167], v[56:59]
	v_mfma_f32_16x16x32_bf16 v[52:55], v[156:159], v[216:219], v[52:55]
	v_mfma_f32_16x16x32_bf16 v[48:51], v[156:159], v[228:231], v[48:51]
	s_and_b64 vcc, exec, s[14:15]
	s_nop 7
	s_branch .LBB0_646
.Lmyb_prelast_n:
	s_waitcnt vmcnt(6) lgkmcnt(0)
	s_barrier
	v_add_u32_e32 v12, s8, v206
	v_add_u32_e32 v13, s8, v10
	v_add_u32_e32 v14, s8, v208
	v_add_u32_e32 v15, s8, v11
	v_mfma_f32_16x16x32_bf16 v[108:111], v[144:147], v[160:163], v[108:111]
	ds_read_b128 v[112:115], v12
	v_mfma_f32_16x16x32_bf16 v[104:107], v[144:147], v[164:167], v[104:107]
	ds_read_b128 v[116:119], v12 offset:2048
	v_mfma_f32_16x16x32_bf16 v[100:103], v[144:147], v[216:219], v[100:103]
	ds_read_b128 v[120:123], v12 offset:4096
	v_mfma_f32_16x16x32_bf16 v[96:99], v[144:147], v[228:231], v[96:99]
	ds_read_b128 v[124:127], v12 offset:6144
	v_mfma_f32_16x16x32_bf16 v[92:95], v[148:151], v[160:163], v[92:95]
	ds_read_b128 v[128:131], v13
	v_mfma_f32_16x16x32_bf16 v[88:91], v[148:151], v[164:167], v[88:91]
	ds_read_b128 v[132:135], v13 offset:2048
	v_mfma_f32_16x16x32_bf16 v[84:87], v[148:151], v[216:219], v[84:87]
	ds_read_b128 v[136:139], v13 offset:4096
	v_mfma_f32_16x16x32_bf16 v[80:83], v[148:151], v[228:231], v[80:83]
	ds_read_b128 v[140:143], v13 offset:6144
	v_mfma_f32_16x16x32_bf16 v[76:79], v[152:155], v[160:163], v[76:79]
	v_mfma_f32_16x16x32_bf16 v[72:75], v[152:155], v[164:167], v[72:75]
	v_mfma_f32_16x16x32_bf16 v[68:71], v[152:155], v[216:219], v[68:71]
	v_mfma_f32_16x16x32_bf16 v[64:67], v[152:155], v[228:231], v[64:67]
	v_mfma_f32_16x16x32_bf16 v[60:63], v[156:159], v[160:163], v[60:63]
	v_mfma_f32_16x16x32_bf16 v[56:59], v[156:159], v[164:167], v[56:59]
	v_mfma_f32_16x16x32_bf16 v[52:55], v[156:159], v[216:219], v[52:55]
	v_mfma_f32_16x16x32_bf16 v[48:51], v[156:159], v[228:231], v[48:51]
	s_waitcnt lgkmcnt(0)
	v_mfma_f32_16x16x32_bf16 v[108:111], v[112:115], v[128:131], v[108:111]
	ds_read_b128 v[144:147], v14
	v_mfma_f32_16x16x32_bf16 v[104:107], v[112:115], v[132:135], v[104:107]
	ds_read_b128 v[148:151], v14 offset:2048
	v_mfma_f32_16x16x32_bf16 v[100:103], v[112:115], v[136:139], v[100:103]
	ds_read_b128 v[152:155], v14 offset:4096
	v_mfma_f32_16x16x32_bf16 v[96:99], v[112:115], v[140:143], v[96:99]
	ds_read_b128 v[156:159], v14 offset:6144
	v_mfma_f32_16x16x32_bf16 v[92:95], v[116:119], v[128:131], v[92:95]
	ds_read_b128 v[160:163], v15
	v_mfma_f32_16x16x32_bf16 v[88:91], v[116:119], v[132:135], v[88:91]
	ds_read_b128 v[164:167], v15 offset:2048
	v_mfma_f32_16x16x32_bf16 v[84:87], v[116:119], v[136:139], v[84:87]
	ds_read_b128 v[216:219], v15 offset:4096
	v_mfma_f32_16x16x32_bf16 v[80:83], v[116:119], v[140:143], v[80:83]
	ds_read_b128 v[228:231], v15 offset:6144
	v_mfma_f32_16x16x32_bf16 v[76:79], v[120:123], v[128:131], v[76:79]
	v_mfma_f32_16x16x32_bf16 v[72:75], v[120:123], v[132:135], v[72:75]
	v_mfma_f32_16x16x32_bf16 v[68:71], v[120:123], v[136:139], v[68:71]
	v_mfma_f32_16x16x32_bf16 v[64:67], v[120:123], v[140:143], v[64:67]
	v_mfma_f32_16x16x32_bf16 v[60:63], v[124:127], v[128:131], v[60:63]
	v_mfma_f32_16x16x32_bf16 v[56:59], v[124:127], v[132:135], v[56:59]
	v_mfma_f32_16x16x32_bf16 v[52:55], v[124:127], v[136:139], v[52:55]
	v_mfma_f32_16x16x32_bf16 v[48:51], v[124:127], v[140:143], v[48:51]
	s_mov_b32 s9, s8
	s_add_u32 s8, s8, 0xc000
	s_sub_u32 vcc_lo, s8, 0x24000
	s_cselect_b32 s8, s8, vcc_lo
	s_waitcnt vmcnt(0) lgkmcnt(0)
	s_barrier
	v_add_u32_e32 v12, s8, v206
	v_add_u32_e32 v13, s8, v10
	v_add_u32_e32 v14, s8, v208
	v_add_u32_e32 v15, s8, v11
	v_mfma_f32_16x16x32_bf16 v[108:111], v[144:147], v[160:163], v[108:111]
	ds_read_b128 v[112:115], v12
	v_mfma_f32_16x16x32_bf16 v[104:107], v[144:147], v[164:167], v[104:107]
	ds_read_b128 v[116:119], v12 offset:2048
	v_mfma_f32_16x16x32_bf16 v[100:103], v[144:147], v[216:219], v[100:103]
	ds_read_b128 v[120:123], v12 offset:4096
	v_mfma_f32_16x16x32_bf16 v[96:99], v[144:147], v[228:231], v[96:99]
	ds_read_b128 v[124:127], v12 offset:6144
	v_mfma_f32_16x16x32_bf16 v[92:95], v[148:151], v[160:163], v[92:95]
	ds_read_b128 v[128:131], v13
	v_mfma_f32_16x16x32_bf16 v[88:91], v[148:151], v[164:167], v[88:91]
	ds_read_b128 v[132:135], v13 offset:2048
	v_mfma_f32_16x16x32_bf16 v[84:87], v[148:151], v[216:219], v[84:87]
	ds_read_b128 v[136:139], v13 offset:4096
	v_mfma_f32_16x16x32_bf16 v[80:83], v[148:151], v[228:231], v[80:83]
	ds_read_b128 v[140:143], v13 offset:6144
	v_mfma_f32_16x16x32_bf16 v[76:79], v[152:155], v[160:163], v[76:79]
	v_mfma_f32_16x16x32_bf16 v[72:75], v[152:155], v[164:167], v[72:75]
	v_mfma_f32_16x16x32_bf16 v[68:71], v[152:155], v[216:219], v[68:71]
	v_mfma_f32_16x16x32_bf16 v[64:67], v[152:155], v[228:231], v[64:67]
	v_mfma_f32_16x16x32_bf16 v[60:63], v[156:159], v[160:163], v[60:63]
	v_mfma_f32_16x16x32_bf16 v[56:59], v[156:159], v[164:167], v[56:59]
	v_mfma_f32_16x16x32_bf16 v[52:55], v[156:159], v[216:219], v[52:55]
	v_mfma_f32_16x16x32_bf16 v[48:51], v[156:159], v[228:231], v[48:51]
	s_waitcnt lgkmcnt(0)
	v_mfma_f32_16x16x32_bf16 v[108:111], v[112:115], v[128:131], v[108:111]
	ds_read_b128 v[144:147], v14
	v_mfma_f32_16x16x32_bf16 v[104:107], v[112:115], v[132:135], v[104:107]
	ds_read_b128 v[148:151], v14 offset:2048
	v_mfma_f32_16x16x32_bf16 v[100:103], v[112:115], v[136:139], v[100:103]
	ds_read_b128 v[152:155], v14 offset:4096
	v_mfma_f32_16x16x32_bf16 v[96:99], v[112:115], v[140:143], v[96:99]
	ds_read_b128 v[156:159], v14 offset:6144
	v_mfma_f32_16x16x32_bf16 v[92:95], v[116:119], v[128:131], v[92:95]
	ds_read_b128 v[160:163], v15
	v_mfma_f32_16x16x32_bf16 v[88:91], v[116:119], v[132:135], v[88:91]
	ds_read_b128 v[164:167], v15 offset:2048
	v_mfma_f32_16x16x32_bf16 v[84:87], v[116:119], v[136:139], v[84:87]
	ds_read_b128 v[216:219], v15 offset:4096
	v_mfma_f32_16x16x32_bf16 v[80:83], v[116:119], v[140:143], v[80:83]
	ds_read_b128 v[228:231], v15 offset:6144
	v_mfma_f32_16x16x32_bf16 v[76:79], v[120:123], v[128:131], v[76:79]
	v_mfma_f32_16x16x32_bf16 v[72:75], v[120:123], v[132:135], v[72:75]
	v_mfma_f32_16x16x32_bf16 v[68:71], v[120:123], v[136:139], v[68:71]
	v_mfma_f32_16x16x32_bf16 v[64:67], v[120:123], v[140:143], v[64:67]
	v_mfma_f32_16x16x32_bf16 v[60:63], v[124:127], v[128:131], v[60:63]
	v_mfma_f32_16x16x32_bf16 v[56:59], v[124:127], v[132:135], v[56:59]
	v_mfma_f32_16x16x32_bf16 v[52:55], v[124:127], v[136:139], v[52:55]
	v_mfma_f32_16x16x32_bf16 v[48:51], v[124:127], v[140:143], v[48:51]
	s_mov_b32 s9, s8
	s_add_u32 s8, s8, 0xc000
	s_sub_u32 vcc_lo, s8, 0x24000
	s_cselect_b32 s8, s8, vcc_lo
	s_waitcnt lgkmcnt(0)
	v_mfma_f32_16x16x32_bf16 v[108:111], v[144:147], v[160:163], v[108:111]
	v_mfma_f32_16x16x32_bf16 v[104:107], v[144:147], v[164:167], v[104:107]
	v_mfma_f32_16x16x32_bf16 v[100:103], v[144:147], v[216:219], v[100:103]
	v_mfma_f32_16x16x32_bf16 v[96:99], v[144:147], v[228:231], v[96:99]
	v_mfma_f32_16x16x32_bf16 v[92:95], v[148:151], v[160:163], v[92:95]
	v_mfma_f32_16x16x32_bf16 v[88:91], v[148:151], v[164:167], v[88:91]
	v_mfma_f32_16x16x32_bf16 v[84:87], v[148:151], v[216:219], v[84:87]
	v_mfma_f32_16x16x32_bf16 v[80:83], v[148:151], v[228:231], v[80:83]
	v_mfma_f32_16x16x32_bf16 v[76:79], v[152:155], v[160:163], v[76:79]
	v_mfma_f32_16x16x32_bf16 v[72:75], v[152:155], v[164:167], v[72:75]
	v_mfma_f32_16x16x32_bf16 v[68:71], v[152:155], v[216:219], v[68:71]
	v_mfma_f32_16x16x32_bf16 v[64:67], v[152:155], v[228:231], v[64:67]
	v_mfma_f32_16x16x32_bf16 v[60:63], v[156:159], v[160:163], v[60:63]
	v_mfma_f32_16x16x32_bf16 v[56:59], v[156:159], v[164:167], v[56:59]
	v_mfma_f32_16x16x32_bf16 v[52:55], v[156:159], v[216:219], v[52:55]
	v_mfma_f32_16x16x32_bf16 v[48:51], v[156:159], v[228:231], v[48:51]
	s_and_b64 vcc, exec, s[14:15]
	s_nop 7
	s_branch .LBB0_646

.LBB0_767:
	s_or_b64 exec, exec, s[0:1]
	s_lshr_b32 s22, s28, 3
	s_mul_i32 s0, s56, 0x108
	s_sub_i32 s23, s0, s22
	s_addk_i32 s23, 0x108
	v_mov_b32_e32 v0, v170
	v_writelane_b32 v252, s0, 28
	s_cmp_ge_i32 s62, s23
	s_mul_i32 s36, s56, 0x8400
	s_waitcnt lgkmcnt(0)
	s_barrier
	s_cbranch_scc1 .LBB0_787
	v_lshlrev_b32_e32 v2, 4, v0
	v_readlane_b32 s0, v252, 13
	v_and_b32_e32 v168, 0x70, v2
	v_mov_b32_e32 v169, 0
	v_readlane_b32 s1, v252, 14
	v_lshl_add_u64 v[2:3], s[76:77], 0, v[168:169]
	v_and_b32_e32 v4, 15, v0
	v_lshl_add_u64 v[172:173], s[0:1], 0, v[168:169]
	s_mov_b64 s[0:1], 0xa80000
	v_lshl_add_u64 v[174:175], v[2:3], 0, s[0:1]
	v_lshrrev_b32_e32 v2, 4, v0
	v_xor_b32_e32 v2, v2, v0
	v_ashrrev_i32_e32 v203, 3, v0
	v_bfe_u32 v5, v0, 6, 1
	v_ashrrev_i32_e32 v6, 7, v0
	v_lshlrev_b32_e32 v2, 4, v2
	v_lshlrev_b32_e32 v4, 7, v4
	v_lshlrev_b32_e32 v3, 7, v203
	v_and_b32_e32 v2, 0x70, v2
	s_add_i32 s0, 16, 0x10000
	v_lshl_or_b32 v7, v6, 13, v4
	v_lshl_or_b32 v4, v5, 13, v4
	v_bfe_u32 v1, v0, 4, 2
	v_add3_u32 v205, s0, v3, v2
	v_add_u32_e32 v8, s0, v4
	v_bfe_u32 v9, v0, 1, 3
	s_add_i32 s0, 16, 0x14000
	v_add3_u32 v204, 16, v3, v2
	v_xor_b32_e32 v10, v1, v9
	v_bitop3_b32 v1, v1, v9, 4 bitop3:0x36
	v_add3_u32 v210, s0, v3, v2
	v_add_u32_e32 v2, s0, v4
	s_lshl_b32 s0, s62, 7
	v_and_b32_e32 v202, 63, v0
	v_add_u32_e32 v7, 16, v7
	v_lshlrev_b32_e32 v9, 4, v10
	v_lshlrev_b32_e32 v1, 4, v1
	v_and_b32_e32 v0, 7, v0
	s_add_i32 s24, s36, s0
	s_lshl_b32 s0, s62, 3
	v_add_u32_e32 v206, v7, v9
	v_add_u32_e32 v207, v8, v9
	v_add_u32_e32 v208, v7, v1
	v_add_u32_e32 v209, v8, v1
	v_add_u32_e32 v211, v2, v9
	v_add_u32_e32 v212, v2, v1
	v_lshlrev_b32_e32 v213, 6, v6
	v_lshlrev_b32_e32 v214, 6, v5
	v_lshlrev_b32_e32 v176, 4, v0
	v_mov_b32_e32 v177, v169
	s_lshl_b32 s25, s51, 7
	s_add_i32 s26, s28, s0
	s_lshl_b32 s27, s51, 3
	s_mov_b64 s[16:17], 0
	s_mov_b32 s30, 0x20000
	s_mov_b64 s[0:1], 0x20080
	s_mov_b64 s[2:3], 0x40080
	s_mov_b64 s[4:5], 0x60080
	s_mov_b64 s[6:7], 0x20000
	s_mov_b64 s[8:9], 0x40000
	s_mov_b64 s[10:11], 0x60000
	s_mov_b64 s[12:13], 0x100
	s_movk_i32 s31, 0x7fff
	s_mov_b32 s34, s62
	s_mov_b32 s12, 0
	s_mov_b32 s13, 0x18000
	s_branch .LBB0_770

.Lswz_c1:
	v_add_u32_e32 v48, s35, v203
	v_add_u32_e32 v50, s37, v203
	v_ashrrev_i32_e32 v49, 31, v48
	v_ashrrev_i32_e32 v51, 31, v50
	v_lshlrev_b64 v[48:49], 11, v[48:49]
	v_lshlrev_b64 v[50:51], 11, v[50:51]
	v_lshl_add_u64 v[48:49], v[172:173], 0, v[48:49]
	v_lshl_add_u64 v[50:51], v[174:175], 0, v[50:51]
	v_writelane_b32 v250, s16, 4
	s_and_b64 vcc, exec, s[16:17]
	s_cbranch_vccnz .LBB0_772
	v_add_co_u32_e32 v4, vcc, 0x20000, v48
	s_nop 1
	v_addc_co_u32_e32 v5, vcc, 0, v49, vcc
	v_add_co_u32_e32 v8, vcc, 0x40000, v48
	s_nop 1
	v_addc_co_u32_e32 v9, vcc, 0, v49, vcc
	v_add_co_u32_e32 v16, vcc, 0x60000, v48
	s_nop 1
	v_addc_co_u32_e32 v17, vcc, 0, v49, vcc
	v_add_co_u32_e32 v36, vcc, 0x20000, v50
	s_nop 1
	v_addc_co_u32_e32 v37, vcc, 0, v51, vcc
	s_nop 0
	s_nop 0
	s_nop 0
	s_nop 0
	s_nop 0
	s_nop 0
	s_nop 0
.LBB0_772:
	v_add_co_u32_e32 v12, vcc, s30, v50
	s_mov_b32 s14, s37
	s_nop 0
	v_addc_co_u32_e32 v13, vcc, 0, v51, vcc
	v_add_co_u32_e32 v14, vcc, 0x60000, v48
	v_add_u32_e32 v52, s14, v203
	s_nop 0
	v_addc_co_u32_e32 v15, vcc, 0, v49, vcc
	v_add_co_u32_e32 v12, vcc, 0x40000, v48
	v_ashrrev_i32_e32 v53, 31, v52
	s_nop 0
	v_addc_co_u32_e32 v13, vcc, 0, v49, vcc
	v_add_co_u32_e32 v14, vcc, 0x20000, v48
	s_mov_b32 s14, s35
	s_nop 0
	v_addc_co_u32_e32 v15, vcc, 0, v49, vcc
	s_nop 0
	s_add_i32 s34, s34, s51
	v_lshlrev_b64 v[52:53], 11, v[52:53]
	s_cmp_ge_i32 s34, s23
	v_lshl_add_u64 v[178:179], s[76:77], 0, v[52:53]
	v_add_u32_e32 v52, s14, v203
	s_cselect_b64 s[14:15], -1, 0
	s_add_i32 s20, s34, s22
	s_cmp_lt_i32 s34, s23
	s_cselect_b64 s[16:17], -1, 0
	s_and_b64 s[18:19], s[16:17], exec
	s_cselect_b32 s18, s20, 0
	v_ashrrev_i32_e32 v53, 31, v52
	v_lshlrev_b64 v[52:53], 11, v[52:53]
	s_mov_b32 s100, s18
	s_lshr_b32 s98, s100, 7
	s_lshl_b32 s98, s98, 10
	s_and_b32 s99, s100, 3
	s_lshl_b32 s99, s99, 8
	s_or_b32 s19, s98, s99
	s_lshl_b32 s98, s100, 5
	s_and_b32 s18, s98, 0xf80
	s_cmp_lt_u32 s100, 0x800
	s_cbranch_scc1 .Lswz_c3
	s_and_b32 s98, s100, 1
	s_lshl_b32 s98, s98, 8
	s_or_b32 s19, s98, 0x4000
	s_lshl_b32 s98, s100, 6
	s_and_b32 s18, s98, 0xf80
.Lswz_c3:
	s_lshl_b32 s98, s19, 11
	s_add_u32 s98, s76, s98
	s_addc_u32 s99, s77, 0
	s_add_u32 s98, s98, 0x2800000
	s_addc_u32 s99, s99, 0
	s_lshl_b32 s100, s18, 11
	s_add_u32 s100, s76, s100
	s_addc_u32 s101, s77, 0
	s_add_u32 s100, s100, 0xa80000
	s_addc_u32 s101, s101, 0
	v_writelane_b32 v250, s98, 0
	v_writelane_b32 v250, s99, 1
	v_writelane_b32 v250, s100, 2
	v_writelane_b32 v250, s101, 3
	v_lshl_add_u64 v[180:181], s[76:77], 0, v[52:53]
	v_add_u32_e32 v52, s19, v203
	v_add_u32_e32 v48, s18, v203
	v_ashrrev_i32_e32 v53, 31, v52
	v_ashrrev_i32_e32 v49, 31, v48
	v_lshlrev_b64 v[52:53], 11, v[52:53]
	v_lshlrev_b64 v[48:49], 11, v[48:49]
	v_lshl_add_u64 v[182:183], v[172:173], 0, v[52:53]
	v_lshl_add_u64 v[184:185], v[174:175], 0, v[48:49]
	v_mov_b32_e32 v48, 0
	s_mov_b32 s38, 0
	v_lshl_add_u64 v[186:187], v[182:183], 0, s[0:1]
	v_lshl_add_u64 v[188:189], v[182:183], 0, s[2:3]
	v_lshl_add_u64 v[190:191], v[182:183], 0, s[4:5]
	v_lshl_add_u64 v[192:193], v[184:185], 0, s[0:1]
	v_lshl_add_u64 v[194:195], v[182:183], 0, s[6:7]
	v_lshl_add_u64 v[196:197], v[182:183], 0, s[8:9]
	v_lshl_add_u64 v[198:199], v[182:183], 0, s[10:11]
	v_lshl_add_u64 v[200:201], v[184:185], 0, s[6:7]
	v_mov_b32_e32 v49, v48
	v_mov_b32_e32 v50, v48
	v_mov_b32_e32 v51, v48
	v_mov_b32_e32 v52, v48
	v_mov_b32_e32 v53, v48
	v_mov_b32_e32 v54, v48
	v_mov_b32_e32 v55, v48
	v_mov_b32_e32 v56, v48
	v_mov_b32_e32 v57, v48
	v_mov_b32_e32 v58, v48
	v_mov_b32_e32 v59, v48
	v_mov_b32_e32 v60, v48
	v_mov_b32_e32 v61, v48
	v_mov_b32_e32 v62, v48
	v_mov_b32_e32 v63, v48
	v_mov_b32_e32 v64, v48
	v_mov_b32_e32 v65, v48
	v_mov_b32_e32 v66, v48
	v_mov_b32_e32 v67, v48
	v_mov_b32_e32 v68, v48
	v_mov_b32_e32 v69, v48
	v_mov_b32_e32 v70, v48
	v_mov_b32_e32 v71, v48
	v_mov_b32_e32 v72, v48
	v_mov_b32_e32 v73, v48
	v_mov_b32_e32 v74, v48
	v_mov_b32_e32 v75, v48
	v_mov_b32_e32 v76, v48
	v_mov_b32_e32 v77, v48
	v_mov_b32_e32 v78, v48
	v_mov_b32_e32 v79, v48
	v_mov_b32_e32 v80, v48
	v_mov_b32_e32 v81, v48
	v_mov_b32_e32 v82, v48
	v_mov_b32_e32 v83, v48
	v_mov_b32_e32 v84, v48
	v_mov_b32_e32 v85, v48
	v_mov_b32_e32 v86, v48
	v_mov_b32_e32 v87, v48
	v_mov_b32_e32 v88, v48
	v_mov_b32_e32 v89, v48
	v_mov_b32_e32 v90, v48
	v_mov_b32_e32 v91, v48
	v_mov_b32_e32 v92, v48
	v_mov_b32_e32 v93, v48
	v_mov_b32_e32 v94, v48
	v_mov_b32_e32 v95, v48
	v_mov_b32_e32 v96, v48
	v_mov_b32_e32 v97, v48
	v_mov_b32_e32 v98, v48
	v_mov_b32_e32 v99, v48
	v_mov_b32_e32 v100, v48
	v_mov_b32_e32 v101, v48
	v_mov_b32_e32 v102, v48
	v_mov_b32_e32 v103, v48
	v_mov_b32_e32 v104, v48
	v_mov_b32_e32 v105, v48
	v_mov_b32_e32 v106, v48
	v_mov_b32_e32 v107, v48
	v_mov_b32_e32 v108, v48
	v_mov_b32_e32 v109, v48
	v_mov_b32_e32 v110, v48
	v_mov_b32_e32 v111, v48
	v_lshrrev_b32_e32 v7, 1, v203
	v_lshrrev_b32_e32 v6, 4, v176
	v_xor_b32_e32 v7, v7, v6
	v_and_b32_e32 v7, 7, v7
	v_lshlrev_b32_e32 v7, 4, v7
	v_lshl_add_u32 v0, v203, 11, v7
	v_add_u32_e32 v1, 0x20000, v0
	v_add_u32_e32 v2, 0x40000, v0
	v_add_u32_e32 v3, 0x60000, v0
	v_and_b32_e32 v4, 15, v203
	v_lshlrev_b32_e32 v4, 2, v4
	v_lshrrev_b32_e32 v5, 4, v203
	v_add_u32_e32 v4, v4, v5
	v_lshl_add_u32 v4, v4, 11, v7
	v_add_u32_e32 v5, 0x20000, v4
	v_lshrrev_b32_e32 v6, 3, v203
	v_lshl_add_u32 v6, v6, 10, 16
	v_add_u32_e32 v10, 0xffff8000, v207
	v_add_u32_e32 v11, 0xffff8000, v209
	v_readlane_b32 vcc_hi, v250, 4
	s_lshl_b32 s98, s35, 11
	s_add_u32 s98, s76, s98
	s_addc_u32 s99, s77, 0
	s_add_u32 s98, s98, 0x2800000
	s_addc_u32 s99, s99, 0
	s_lshl_b32 s100, s37, 11
	s_add_u32 s100, s76, s100
	s_addc_u32 s101, s77, 0
	s_add_u32 s100, s100, 0xa80000
	s_addc_u32 s101, s101, 0
	s_cmp_lg_u32 vcc_hi, 0
	s_cbranch_scc1 .Lmyc_primed
	v_readfirstlane_b32 vcc_lo, v6
	s_nop 0
	s_add_u32 vcc_lo, vcc_lo, s12
	s_mov_b32 m0, vcc_lo
	s_nop 0
	global_load_lds_dwordx4 v0, s[98:99]
	s_add_u32 m0, m0, 0x2000
	s_nop 0
	global_load_lds_dwordx4 v1, s[98:99]
	s_add_u32 m0, m0, 0x2000
	s_nop 0
	global_load_lds_dwordx4 v2, s[98:99]
	s_add_u32 m0, m0, 0x2000
	s_nop 0
	global_load_lds_dwordx4 v3, s[98:99]
	s_add_u32 m0, vcc_lo, 0x8000
	s_nop 0
	global_load_lds_dwordx4 v4, s[100:101]
	s_add_u32 m0, m0, 0x2000
	s_nop 0
	global_load_lds_dwordx4 v5, s[100:101]
	s_add_u32 s98, s98, 0x80
	s_addc_u32 s99, s99, 0
	s_add_u32 s100, s100, 0x80
	s_addc_u32 s101, s101, 0
	s_add_u32 vcc_hi, s12, 0xc000
	s_sub_u32 vcc_lo, vcc_hi, 0x24000
	s_cselect_b32 vcc_hi, vcc_hi, vcc_lo
	v_readfirstlane_b32 vcc_lo, v6
	s_nop 0
	s_add_u32 vcc_lo, vcc_lo, vcc_hi
	s_mov_b32 m0, vcc_lo
	s_nop 0
	global_load_lds_dwordx4 v0, s[98:99]
	s_add_u32 m0, m0, 0x2000
	s_nop 0
	global_load_lds_dwordx4 v1, s[98:99]
	s_add_u32 m0, m0, 0x2000
	s_nop 0
	global_load_lds_dwordx4 v2, s[98:99]
	s_add_u32 m0, m0, 0x2000
	s_nop 0
	global_load_lds_dwordx4 v3, s[98:99]
	s_add_u32 m0, vcc_lo, 0x8000
	s_nop 0
	global_load_lds_dwordx4 v4, s[100:101]
	s_add_u32 m0, m0, 0x2000
	s_nop 0
	global_load_lds_dwordx4 v5, s[100:101]
	s_add_u32 s98, s98, 0x80
	s_addc_u32 s99, s99, 0
	s_add_u32 s100, s100, 0x80
	s_addc_u32 s101, s101, 0
	s_branch .LBB0_774

.LBB0_774:
	s_waitcnt vmcnt(6) lgkmcnt(0)
	s_barrier
	v_add_u32_e32 v12, s12, v206
	v_add_u32_e32 v13, s12, v10
	v_add_u32_e32 v14, s12, v208
	v_add_u32_e32 v15, s12, v11
	v_readfirstlane_b32 vcc_lo, v6
	s_nop 0
	s_add_u32 vcc_lo, vcc_lo, s13
	ds_read_b128 v[112:115], v12
	ds_read_b128 v[116:119], v12 offset:2048
	ds_read_b128 v[120:123], v12 offset:4096
	ds_read_b128 v[124:127], v12 offset:6144
	ds_read_b128 v[128:131], v13
	ds_read_b128 v[132:135], v13 offset:2048
	ds_read_b128 v[136:139], v13 offset:4096
	ds_read_b128 v[140:143], v13 offset:6144
	s_mov_b32 m0, vcc_lo
	s_nop 0
	global_load_lds_dwordx4 v0, s[98:99]
	s_add_u32 m0, m0, 0x2000
	s_nop 0
	global_load_lds_dwordx4 v1, s[98:99]
	s_add_u32 m0, m0, 0x2000
	s_nop 0
	global_load_lds_dwordx4 v2, s[98:99]
	s_add_u32 m0, m0, 0x2000
	s_nop 0
	global_load_lds_dwordx4 v3, s[98:99]
	s_add_u32 m0, vcc_lo, 0x8000
	s_nop 0
	global_load_lds_dwordx4 v4, s[100:101]
	s_add_u32 m0, m0, 0x2000
	s_nop 0
	global_load_lds_dwordx4 v5, s[100:101]
	s_add_u32 s98, s98, 0x80
	s_addc_u32 s99, s99, 0
	s_add_u32 s100, s100, 0x80
	s_addc_u32 s101, s101, 0
	s_waitcnt lgkmcnt(0)
	v_mfma_f32_16x16x32_bf16 v[108:111], v[128:131], v[112:115], v[108:111]
	ds_read_b128 v[144:147], v14
	v_mfma_f32_16x16x32_bf16 v[104:107], v[132:135], v[112:115], v[104:107]
	ds_read_b128 v[148:151], v14 offset:2048
	v_mfma_f32_16x16x32_bf16 v[100:103], v[136:139], v[112:115], v[100:103]
	ds_read_b128 v[152:155], v14 offset:4096
	v_mfma_f32_16x16x32_bf16 v[96:99], v[140:143], v[112:115], v[96:99]
	ds_read_b128 v[156:159], v14 offset:6144
	v_mfma_f32_16x16x32_bf16 v[92:95], v[128:131], v[116:119], v[92:95]
	ds_read_b128 v[160:163], v15
	v_mfma_f32_16x16x32_bf16 v[88:91], v[132:135], v[116:119], v[88:91]
	ds_read_b128 v[164:167], v15 offset:2048
	v_mfma_f32_16x16x32_bf16 v[84:87], v[136:139], v[116:119], v[84:87]
	ds_read_b128 v[216:219], v15 offset:4096
	v_mfma_f32_16x16x32_bf16 v[80:83], v[140:143], v[116:119], v[80:83]
	ds_read_b128 v[228:231], v15 offset:6144
	v_mfma_f32_16x16x32_bf16 v[76:79], v[128:131], v[120:123], v[76:79]
	v_mfma_f32_16x16x32_bf16 v[72:75], v[132:135], v[120:123], v[72:75]
	v_mfma_f32_16x16x32_bf16 v[68:71], v[136:139], v[120:123], v[68:71]
	v_mfma_f32_16x16x32_bf16 v[64:67], v[140:143], v[120:123], v[64:67]
	v_mfma_f32_16x16x32_bf16 v[60:63], v[128:131], v[124:127], v[60:63]
	v_mfma_f32_16x16x32_bf16 v[56:59], v[132:135], v[124:127], v[56:59]
	v_mfma_f32_16x16x32_bf16 v[52:55], v[136:139], v[124:127], v[52:55]
	v_mfma_f32_16x16x32_bf16 v[48:51], v[140:143], v[124:127], v[48:51]
	s_mov_b32 s13, s12
	s_add_u32 s12, s12, 0xc000
	s_sub_u32 vcc_lo, s12, 0x24000
	s_cselect_b32 s12, s12, vcc_lo
	s_mov_b32 s38, 1
.Lmyc_steady:
	s_waitcnt vmcnt(6) lgkmcnt(0)
	s_barrier
	v_add_u32_e32 v12, s12, v206
	v_add_u32_e32 v13, s12, v10
	v_add_u32_e32 v14, s12, v208
	v_add_u32_e32 v15, s12, v11
	v_readfirstlane_b32 vcc_lo, v6
	s_nop 0
	s_add_u32 vcc_lo, vcc_lo, s13
	s_mov_b32 m0, vcc_lo
	v_mfma_f32_16x16x32_bf16 v[108:111], v[160:163], v[144:147], v[108:111]
	ds_read_b128 v[112:115], v12
	global_load_lds_dwordx4 v0, s[98:99]
	s_add_u32 m0, m0, 0x2000
	v_mfma_f32_16x16x32_bf16 v[104:107], v[164:167], v[144:147], v[104:107]
	ds_read_b128 v[116:119], v12 offset:2048
	global_load_lds_dwordx4 v1, s[98:99]
	s_add_u32 m0, m0, 0x2000
	v_mfma_f32_16x16x32_bf16 v[100:103], v[216:219], v[144:147], v[100:103]
	ds_read_b128 v[120:123], v12 offset:4096
	global_load_lds_dwordx4 v2, s[98:99]
	s_add_u32 m0, m0, 0x2000
	v_mfma_f32_16x16x32_bf16 v[96:99], v[228:231], v[144:147], v[96:99]
	ds_read_b128 v[124:127], v12 offset:6144
	global_load_lds_dwordx4 v3, s[98:99]
	s_add_u32 m0, vcc_lo, 0x8000
	v_mfma_f32_16x16x32_bf16 v[92:95], v[160:163], v[148:151], v[92:95]
	ds_read_b128 v[128:131], v13
	global_load_lds_dwordx4 v4, s[100:101]
	s_add_u32 m0, m0, 0x2000
	v_mfma_f32_16x16x32_bf16 v[88:91], v[164:167], v[148:151], v[88:91]
	ds_read_b128 v[132:135], v13 offset:2048
	global_load_lds_dwordx4 v5, s[100:101]
	v_mfma_f32_16x16x32_bf16 v[84:87], v[216:219], v[148:151], v[84:87]
	ds_read_b128 v[136:139], v13 offset:4096
	s_add_u32 s98, s98, 0x80
	s_addc_u32 s99, s99, 0
	s_add_u32 s100, s100, 0x80
	s_addc_u32 s101, s101, 0
	v_mfma_f32_16x16x32_bf16 v[80:83], v[228:231], v[148:151], v[80:83]
	ds_read_b128 v[140:143], v13 offset:6144
	v_mfma_f32_16x16x32_bf16 v[76:79], v[160:163], v[152:155], v[76:79]
	v_mfma_f32_16x16x32_bf16 v[72:75], v[164:167], v[152:155], v[72:75]
	v_mfma_f32_16x16x32_bf16 v[68:71], v[216:219], v[152:155], v[68:71]
	v_mfma_f32_16x16x32_bf16 v[64:67], v[228:231], v[152:155], v[64:67]
	v_mfma_f32_16x16x32_bf16 v[60:63], v[160:163], v[156:159], v[60:63]
	v_mfma_f32_16x16x32_bf16 v[56:59], v[164:167], v[156:159], v[56:59]
	v_mfma_f32_16x16x32_bf16 v[52:55], v[216:219], v[156:159], v[52:55]
	v_mfma_f32_16x16x32_bf16 v[48:51], v[228:231], v[156:159], v[48:51]
	s_waitcnt lgkmcnt(0)
	v_mfma_f32_16x16x32_bf16 v[108:111], v[128:131], v[112:115], v[108:111]
	ds_read_b128 v[144:147], v14
	v_mfma_f32_16x16x32_bf16 v[104:107], v[132:135], v[112:115], v[104:107]
	ds_read_b128 v[148:151], v14 offset:2048
	v_mfma_f32_16x16x32_bf16 v[100:103], v[136:139], v[112:115], v[100:103]
	ds_read_b128 v[152:155], v14 offset:4096
	v_mfma_f32_16x16x32_bf16 v[96:99], v[140:143], v[112:115], v[96:99]
	ds_read_b128 v[156:159], v14 offset:6144
	v_mfma_f32_16x16x32_bf16 v[92:95], v[128:131], v[116:119], v[92:95]
	ds_read_b128 v[160:163], v15
	v_mfma_f32_16x16x32_bf16 v[88:91], v[132:135], v[116:119], v[88:91]
	ds_read_b128 v[164:167], v15 offset:2048
	v_mfma_f32_16x16x32_bf16 v[84:87], v[136:139], v[116:119], v[84:87]
	ds_read_b128 v[216:219], v15 offset:4096
	v_mfma_f32_16x16x32_bf16 v[80:83], v[140:143], v[116:119], v[80:83]
	ds_read_b128 v[228:231], v15 offset:6144
	v_mfma_f32_16x16x32_bf16 v[76:79], v[128:131], v[120:123], v[76:79]
	v_mfma_f32_16x16x32_bf16 v[72:75], v[132:135], v[120:123], v[72:75]
	v_mfma_f32_16x16x32_bf16 v[68:71], v[136:139], v[120:123], v[68:71]
	v_mfma_f32_16x16x32_bf16 v[64:67], v[140:143], v[120:123], v[64:67]
	v_mfma_f32_16x16x32_bf16 v[60:63], v[128:131], v[124:127], v[60:63]
	v_mfma_f32_16x16x32_bf16 v[56:59], v[132:135], v[124:127], v[56:59]
	v_mfma_f32_16x16x32_bf16 v[52:55], v[136:139], v[124:127], v[52:55]
	v_mfma_f32_16x16x32_bf16 v[48:51], v[140:143], v[124:127], v[48:51]
	s_mov_b32 s13, s12
	s_add_u32 s12, s12, 0xc000
	s_sub_u32 vcc_lo, s12, 0x24000
	s_cselect_b32 s12, s12, vcc_lo
	s_add_i32 s38, s38, 1
	s_cmp_lt_u32 s38, 14
	s_cbranch_scc1 .Lmyc_steady
	s_andn2_b64 vcc, exec, s[16:17]
	s_cbranch_vccnz .Lmyc_prelast_n
	v_readlane_b32 s98, v250, 0
	v_readlane_b32 s99, v250, 1
	v_readlane_b32 s100, v250, 2
	v_readlane_b32 s101, v250, 3
	s_waitcnt vmcnt(6) lgkmcnt(0)
	s_barrier
	v_add_u32_e32 v12, s12, v206
	v_add_u32_e32 v13, s12, v10
	v_add_u32_e32 v14, s12, v208
	v_add_u32_e32 v15, s12, v11
	v_readfirstlane_b32 vcc_lo, v6
	s_nop 0
	s_add_u32 vcc_lo, vcc_lo, s13
	s_mov_b32 m0, vcc_lo
	v_mfma_f32_16x16x32_bf16 v[108:111], v[160:163], v[144:147], v[108:111]
	ds_read_b128 v[112:115], v12
	global_load_lds_dwordx4 v0, s[98:99]
	s_add_u32 m0, m0, 0x2000
	v_mfma_f32_16x16x32_bf16 v[104:107], v[164:167], v[144:147], v[104:107]
	ds_read_b128 v[116:119], v12 offset:2048
	global_load_lds_dwordx4 v1, s[98:99]
	s_add_u32 m0, m0, 0x2000
	v_mfma_f32_16x16x32_bf16 v[100:103], v[216:219], v[144:147], v[100:103]
	ds_read_b128 v[120:123], v12 offset:4096
	global_load_lds_dwordx4 v2, s[98:99]
	s_add_u32 m0, m0, 0x2000
	v_mfma_f32_16x16x32_bf16 v[96:99], v[228:231], v[144:147], v[96:99]
	ds_read_b128 v[124:127], v12 offset:6144
	global_load_lds_dwordx4 v3, s[98:99]
	s_add_u32 m0, vcc_lo, 0x8000
	v_mfma_f32_16x16x32_bf16 v[92:95], v[160:163], v[148:151], v[92:95]
	ds_read_b128 v[128:131], v13
	global_load_lds_dwordx4 v4, s[100:101]
	s_add_u32 m0, m0, 0x2000
	v_mfma_f32_16x16x32_bf16 v[88:91], v[164:167], v[148:151], v[88:91]
	ds_read_b128 v[132:135], v13 offset:2048
	global_load_lds_dwordx4 v5, s[100:101]
	v_mfma_f32_16x16x32_bf16 v[84:87], v[216:219], v[148:151], v[84:87]
	ds_read_b128 v[136:139], v13 offset:4096
	s_add_u32 s98, s98, 0x80
	s_addc_u32 s99, s99, 0
	s_add_u32 s100, s100, 0x80
	s_addc_u32 s101, s101, 0
	v_mfma_f32_16x16x32_bf16 v[80:83], v[228:231], v[148:151], v[80:83]
	ds_read_b128 v[140:143], v13 offset:6144
	v_mfma_f32_16x16x32_bf16 v[76:79], v[160:163], v[152:155], v[76:79]
	v_mfma_f32_16x16x32_bf16 v[72:75], v[164:167], v[152:155], v[72:75]
	v_mfma_f32_16x16x32_bf16 v[68:71], v[216:219], v[152:155], v[68:71]
	v_mfma_f32_16x16x32_bf16 v[64:67], v[228:231], v[152:155], v[64:67]
	v_mfma_f32_16x16x32_bf16 v[60:63], v[160:163], v[156:159], v[60:63]
	v_mfma_f32_16x16x32_bf16 v[56:59], v[164:167], v[156:159], v[56:59]
	v_mfma_f32_16x16x32_bf16 v[52:55], v[216:219], v[156:159], v[52:55]
	v_mfma_f32_16x16x32_bf16 v[48:51], v[228:231], v[156:159], v[48:51]
	s_waitcnt lgkmcnt(0)
	v_mfma_f32_16x16x32_bf16 v[108:111], v[128:131], v[112:115], v[108:111]
	ds_read_b128 v[144:147], v14
	v_mfma_f32_16x16x32_bf16 v[104:107], v[132:135], v[112:115], v[104:107]
	ds_read_b128 v[148:151], v14 offset:2048
	v_mfma_f32_16x16x32_bf16 v[100:103], v[136:139], v[112:115], v[100:103]
	ds_read_b128 v[152:155], v14 offset:4096
	v_mfma_f32_16x16x32_bf16 v[96:99], v[140:143], v[112:115], v[96:99]
	ds_read_b128 v[156:159], v14 offset:6144
	v_mfma_f32_16x16x32_bf16 v[92:95], v[128:131], v[116:119], v[92:95]
	ds_read_b128 v[160:163], v15
	v_mfma_f32_16x16x32_bf16 v[88:91], v[132:135], v[116:119], v[88:91]
	ds_read_b128 v[164:167], v15 offset:2048
	v_mfma_f32_16x16x32_bf16 v[84:87], v[136:139], v[116:119], v[84:87]
	ds_read_b128 v[216:219], v15 offset:4096
	v_mfma_f32_16x16x32_bf16 v[80:83], v[140:143], v[116:119], v[80:83]
	ds_read_b128 v[228:231], v15 offset:6144
	v_mfma_f32_16x16x32_bf16 v[76:79], v[128:131], v[120:123], v[76:79]
	v_mfma_f32_16x16x32_bf16 v[72:75], v[132:135], v[120:123], v[72:75]
	v_mfma_f32_16x16x32_bf16 v[68:71], v[136:139], v[120:123], v[68:71]
	v_mfma_f32_16x16x32_bf16 v[64:67], v[140:143], v[120:123], v[64:67]
	v_mfma_f32_16x16x32_bf16 v[60:63], v[128:131], v[124:127], v[60:63]
	v_mfma_f32_16x16x32_bf16 v[56:59], v[132:135], v[124:127], v[56:59]
	v_mfma_f32_16x16x32_bf16 v[52:55], v[136:139], v[124:127], v[52:55]
	v_mfma_f32_16x16x32_bf16 v[48:51], v[140:143], v[124:127], v[48:51]
	s_mov_b32 s13, s12
	s_add_u32 s12, s12, 0xc000
	s_sub_u32 vcc_lo, s12, 0x24000
	s_cselect_b32 s12, s12, vcc_lo
	s_waitcnt vmcnt(6) lgkmcnt(0)
	s_barrier
	v_add_u32_e32 v12, s12, v206
	v_add_u32_e32 v13, s12, v10
	v_add_u32_e32 v14, s12, v208
	v_add_u32_e32 v15, s12, v11
	v_readfirstlane_b32 vcc_lo, v6
	s_nop 0
	s_add_u32 vcc_lo, vcc_lo, s13
	s_mov_b32 m0, vcc_lo
	v_mfma_f32_16x16x32_bf16 v[108:111], v[160:163], v[144:147], v[108:111]
	ds_read_b128 v[112:115], v12
	global_load_lds_dwordx4 v0, s[98:99]
	s_add_u32 m0, m0, 0x2000
	v_mfma_f32_16x16x32_bf16 v[104:107], v[164:167], v[144:147], v[104:107]
	ds_read_b128 v[116:119], v12 offset:2048
	global_load_lds_dwordx4 v1, s[98:99]
	s_add_u32 m0, m0, 0x2000
	v_mfma_f32_16x16x32_bf16 v[100:103], v[216:219], v[144:147], v[100:103]
	ds_read_b128 v[120:123], v12 offset:4096
	global_load_lds_dwordx4 v2, s[98:99]
	s_add_u32 m0, m0, 0x2000
	v_mfma_f32_16x16x32_bf16 v[96:99], v[228:231], v[144:147], v[96:99]
	ds_read_b128 v[124:127], v12 offset:6144
	global_load_lds_dwordx4 v3, s[98:99]
	s_add_u32 m0, vcc_lo, 0x8000
	v_mfma_f32_16x16x32_bf16 v[92:95], v[160:163], v[148:151], v[92:95]
	ds_read_b128 v[128:131], v13
	global_load_lds_dwordx4 v4, s[100:101]
	s_add_u32 m0, m0, 0x2000
	v_mfma_f32_16x16x32_bf16 v[88:91], v[164:167], v[148:151], v[88:91]
	ds_read_b128 v[132:135], v13 offset:2048
	global_load_lds_dwordx4 v5, s[100:101]
	v_mfma_f32_16x16x32_bf16 v[84:87], v[216:219], v[148:151], v[84:87]
	ds_read_b128 v[136:139], v13 offset:4096
	s_add_u32 s98, s98, 0x80
	s_addc_u32 s99, s99, 0
	s_add_u32 s100, s100, 0x80
	s_addc_u32 s101, s101, 0
	v_mfma_f32_16x16x32_bf16 v[80:83], v[228:231], v[148:151], v[80:83]
	ds_read_b128 v[140:143], v13 offset:6144
	v_mfma_f32_16x16x32_bf16 v[76:79], v[160:163], v[152:155], v[76:79]
	v_mfma_f32_16x16x32_bf16 v[72:75], v[164:167], v[152:155], v[72:75]
	v_mfma_f32_16x16x32_bf16 v[68:71], v[216:219], v[152:155], v[68:71]
	v_mfma_f32_16x16x32_bf16 v[64:67], v[228:231], v[152:155], v[64:67]
	v_mfma_f32_16x16x32_bf16 v[60:63], v[160:163], v[156:159], v[60:63]
	v_mfma_f32_16x16x32_bf16 v[56:59], v[164:167], v[156:159], v[56:59]
	v_mfma_f32_16x16x32_bf16 v[52:55], v[216:219], v[156:159], v[52:55]
	v_mfma_f32_16x16x32_bf16 v[48:51], v[228:231], v[156:159], v[48:51]
	s_waitcnt lgkmcnt(0)
	v_mfma_f32_16x16x32_bf16 v[108:111], v[128:131], v[112:115], v[108:111]
	ds_read_b128 v[144:147], v14
	v_mfma_f32_16x16x32_bf16 v[104:107], v[132:135], v[112:115], v[104:107]
	ds_read_b128 v[148:151], v14 offset:2048
	v_mfma_f32_16x16x32_bf16 v[100:103], v[136:139], v[112:115], v[100:103]
	ds_read_b128 v[152:155], v14 offset:4096
	v_mfma_f32_16x16x32_bf16 v[96:99], v[140:143], v[112:115], v[96:99]
	ds_read_b128 v[156:159], v14 offset:6144
	v_mfma_f32_16x16x32_bf16 v[92:95], v[128:131], v[116:119], v[92:95]
	ds_read_b128 v[160:163], v15
	v_mfma_f32_16x16x32_bf16 v[88:91], v[132:135], v[116:119], v[88:91]
	ds_read_b128 v[164:167], v15 offset:2048
	v_mfma_f32_16x16x32_bf16 v[84:87], v[136:139], v[116:119], v[84:87]
	ds_read_b128 v[216:219], v15 offset:4096
	v_mfma_f32_16x16x32_bf16 v[80:83], v[140:143], v[116:119], v[80:83]
	ds_read_b128 v[228:231], v15 offset:6144
	v_mfma_f32_16x16x32_bf16 v[76:79], v[128:131], v[120:123], v[76:79]
	v_mfma_f32_16x16x32_bf16 v[72:75], v[132:135], v[120:123], v[72:75]
	v_mfma_f32_16x16x32_bf16 v[68:71], v[136:139], v[120:123], v[68:71]
	v_mfma_f32_16x16x32_bf16 v[64:67], v[140:143], v[120:123], v[64:67]
	v_mfma_f32_16x16x32_bf16 v[60:63], v[128:131], v[124:127], v[60:63]
	v_mfma_f32_16x16x32_bf16 v[56:59], v[132:135], v[124:127], v[56:59]
	v_mfma_f32_16x16x32_bf16 v[52:55], v[136:139], v[124:127], v[52:55]
	v_mfma_f32_16x16x32_bf16 v[48:51], v[140:143], v[124:127], v[48:51]
	s_mov_b32 s13, s12
	s_add_u32 s12, s12, 0xc000
	s_sub_u32 vcc_lo, s12, 0x24000
	s_cselect_b32 s12, s12, vcc_lo
	s_waitcnt lgkmcnt(0)
	v_mfma_f32_16x16x32_bf16 v[108:111], v[160:163], v[144:147], v[108:111]
	v_mfma_f32_16x16x32_bf16 v[104:107], v[164:167], v[144:147], v[104:107]
	v_mfma_f32_16x16x32_bf16 v[100:103], v[216:219], v[144:147], v[100:103]
	v_mfma_f32_16x16x32_bf16 v[96:99], v[228:231], v[144:147], v[96:99]
	v_mfma_f32_16x16x32_bf16 v[92:95], v[160:163], v[148:151], v[92:95]
	v_mfma_f32_16x16x32_bf16 v[88:91], v[164:167], v[148:151], v[88:91]
	v_mfma_f32_16x16x32_bf16 v[84:87], v[216:219], v[148:151], v[84:87]
	v_mfma_f32_16x16x32_bf16 v[80:83], v[228:231], v[148:151], v[80:83]
	v_mfma_f32_16x16x32_bf16 v[76:79], v[160:163], v[152:155], v[76:79]
	v_mfma_f32_16x16x32_bf16 v[72:75], v[164:167], v[152:155], v[72:75]
	v_mfma_f32_16x16x32_bf16 v[68:71], v[216:219], v[152:155], v[68:71]
	v_mfma_f32_16x16x32_bf16 v[64:67], v[228:231], v[152:155], v[64:67]
	v_mfma_f32_16x16x32_bf16 v[60:63], v[160:163], v[156:159], v[60:63]
	v_mfma_f32_16x16x32_bf16 v[56:59], v[164:167], v[156:159], v[56:59]
	v_mfma_f32_16x16x32_bf16 v[52:55], v[216:219], v[156:159], v[52:55]
	v_mfma_f32_16x16x32_bf16 v[48:51], v[228:231], v[156:159], v[48:51]
	s_and_b64 vcc, exec, s[18:19]
	s_nop 7
	s_branch .LBB0_769
.Lmyc_prelast_n:
	s_waitcnt vmcnt(6) lgkmcnt(0)
	s_barrier
	v_add_u32_e32 v12, s12, v206
	v_add_u32_e32 v13, s12, v10
	v_add_u32_e32 v14, s12, v208
	v_add_u32_e32 v15, s12, v11
	v_mfma_f32_16x16x32_bf16 v[108:111], v[160:163], v[144:147], v[108:111]
	ds_read_b128 v[112:115], v12
	v_mfma_f32_16x16x32_bf16 v[104:107], v[164:167], v[144:147], v[104:107]
	ds_read_b128 v[116:119], v12 offset:2048
	v_mfma_f32_16x16x32_bf16 v[100:103], v[216:219], v[144:147], v[100:103]
	ds_read_b128 v[120:123], v12 offset:4096
	v_mfma_f32_16x16x32_bf16 v[96:99], v[228:231], v[144:147], v[96:99]
	ds_read_b128 v[124:127], v12 offset:6144
	v_mfma_f32_16x16x32_bf16 v[92:95], v[160:163], v[148:151], v[92:95]
	ds_read_b128 v[128:131], v13
	v_mfma_f32_16x16x32_bf16 v[88:91], v[164:167], v[148:151], v[88:91]
	ds_read_b128 v[132:135], v13 offset:2048
	v_mfma_f32_16x16x32_bf16 v[84:87], v[216:219], v[148:151], v[84:87]
	ds_read_b128 v[136:139], v13 offset:4096
	v_mfma_f32_16x16x32_bf16 v[80:83], v[228:231], v[148:151], v[80:83]
	ds_read_b128 v[140:143], v13 offset:6144
	v_mfma_f32_16x16x32_bf16 v[76:79], v[160:163], v[152:155], v[76:79]
	v_mfma_f32_16x16x32_bf16 v[72:75], v[164:167], v[152:155], v[72:75]
	v_mfma_f32_16x16x32_bf16 v[68:71], v[216:219], v[152:155], v[68:71]
	v_mfma_f32_16x16x32_bf16 v[64:67], v[228:231], v[152:155], v[64:67]
	v_mfma_f32_16x16x32_bf16 v[60:63], v[160:163], v[156:159], v[60:63]
	v_mfma_f32_16x16x32_bf16 v[56:59], v[164:167], v[156:159], v[56:59]
	v_mfma_f32_16x16x32_bf16 v[52:55], v[216:219], v[156:159], v[52:55]
	v_mfma_f32_16x16x32_bf16 v[48:51], v[228:231], v[156:159], v[48:51]
	s_waitcnt lgkmcnt(0)
	v_mfma_f32_16x16x32_bf16 v[108:111], v[128:131], v[112:115], v[108:111]
	ds_read_b128 v[144:147], v14
	v_mfma_f32_16x16x32_bf16 v[104:107], v[132:135], v[112:115], v[104:107]
	ds_read_b128 v[148:151], v14 offset:2048
	v_mfma_f32_16x16x32_bf16 v[100:103], v[136:139], v[112:115], v[100:103]
	ds_read_b128 v[152:155], v14 offset:4096
	v_mfma_f32_16x16x32_bf16 v[96:99], v[140:143], v[112:115], v[96:99]
	ds_read_b128 v[156:159], v14 offset:6144
	v_mfma_f32_16x16x32_bf16 v[92:95], v[128:131], v[116:119], v[92:95]
	ds_read_b128 v[160:163], v15
	v_mfma_f32_16x16x32_bf16 v[88:91], v[132:135], v[116:119], v[88:91]
	ds_read_b128 v[164:167], v15 offset:2048
	v_mfma_f32_16x16x32_bf16 v[84:87], v[136:139], v[116:119], v[84:87]
	ds_read_b128 v[216:219], v15 offset:4096
	v_mfma_f32_16x16x32_bf16 v[80:83], v[140:143], v[116:119], v[80:83]
	ds_read_b128 v[228:231], v15 offset:6144
	v_mfma_f32_16x16x32_bf16 v[76:79], v[128:131], v[120:123], v[76:79]
	v_mfma_f32_16x16x32_bf16 v[72:75], v[132:135], v[120:123], v[72:75]
	v_mfma_f32_16x16x32_bf16 v[68:71], v[136:139], v[120:123], v[68:71]
	v_mfma_f32_16x16x32_bf16 v[64:67], v[140:143], v[120:123], v[64:67]
	v_mfma_f32_16x16x32_bf16 v[60:63], v[128:131], v[124:127], v[60:63]
	v_mfma_f32_16x16x32_bf16 v[56:59], v[132:135], v[124:127], v[56:59]
	v_mfma_f32_16x16x32_bf16 v[52:55], v[136:139], v[124:127], v[52:55]
	v_mfma_f32_16x16x32_bf16 v[48:51], v[140:143], v[124:127], v[48:51]
	s_mov_b32 s13, s12
	s_add_u32 s12, s12, 0xc000
	s_sub_u32 vcc_lo, s12, 0x24000
	s_cselect_b32 s12, s12, vcc_lo
	s_waitcnt vmcnt(0) lgkmcnt(0)
	s_barrier
	v_add_u32_e32 v12, s12, v206
	v_add_u32_e32 v13, s12, v10
	v_add_u32_e32 v14, s12, v208
	v_add_u32_e32 v15, s12, v11
	v_mfma_f32_16x16x32_bf16 v[108:111], v[160:163], v[144:147], v[108:111]
	ds_read_b128 v[112:115], v12
	v_mfma_f32_16x16x32_bf16 v[104:107], v[164:167], v[144:147], v[104:107]
	ds_read_b128 v[116:119], v12 offset:2048
	v_mfma_f32_16x16x32_bf16 v[100:103], v[216:219], v[144:147], v[100:103]
	ds_read_b128 v[120:123], v12 offset:4096
	v_mfma_f32_16x16x32_bf16 v[96:99], v[228:231], v[144:147], v[96:99]
	ds_read_b128 v[124:127], v12 offset:6144
	v_mfma_f32_16x16x32_bf16 v[92:95], v[160:163], v[148:151], v[92:95]
	ds_read_b128 v[128:131], v13
	v_mfma_f32_16x16x32_bf16 v[88:91], v[164:167], v[148:151], v[88:91]
	ds_read_b128 v[132:135], v13 offset:2048
	v_mfma_f32_16x16x32_bf16 v[84:87], v[216:219], v[148:151], v[84:87]
	ds_read_b128 v[136:139], v13 offset:4096
	v_mfma_f32_16x16x32_bf16 v[80:83], v[228:231], v[148:151], v[80:83]
	ds_read_b128 v[140:143], v13 offset:6144
	v_mfma_f32_16x16x32_bf16 v[76:79], v[160:163], v[152:155], v[76:79]
	v_mfma_f32_16x16x32_bf16 v[72:75], v[164:167], v[152:155], v[72:75]
	v_mfma_f32_16x16x32_bf16 v[68:71], v[216:219], v[152:155], v[68:71]
	v_mfma_f32_16x16x32_bf16 v[64:67], v[228:231], v[152:155], v[64:67]
	v_mfma_f32_16x16x32_bf16 v[60:63], v[160:163], v[156:159], v[60:63]
	v_mfma_f32_16x16x32_bf16 v[56:59], v[164:167], v[156:159], v[56:59]
	v_mfma_f32_16x16x32_bf16 v[52:55], v[216:219], v[156:159], v[52:55]
	v_mfma_f32_16x16x32_bf16 v[48:51], v[228:231], v[156:159], v[48:51]
	s_waitcnt lgkmcnt(0)
	v_mfma_f32_16x16x32_bf16 v[108:111], v[128:131], v[112:115], v[108:111]
	ds_read_b128 v[144:147], v14
	v_mfma_f32_16x16x32_bf16 v[104:107], v[132:135], v[112:115], v[104:107]
	ds_read_b128 v[148:151], v14 offset:2048
	v_mfma_f32_16x16x32_bf16 v[100:103], v[136:139], v[112:115], v[100:103]
	ds_read_b128 v[152:155], v14 offset:4096
	v_mfma_f32_16x16x32_bf16 v[96:99], v[140:143], v[112:115], v[96:99]
	ds_read_b128 v[156:159], v14 offset:6144
	v_mfma_f32_16x16x32_bf16 v[92:95], v[128:131], v[116:119], v[92:95]
	ds_read_b128 v[160:163], v15
	v_mfma_f32_16x16x32_bf16 v[88:91], v[132:135], v[116:119], v[88:91]
	ds_read_b128 v[164:167], v15 offset:2048
	v_mfma_f32_16x16x32_bf16 v[84:87], v[136:139], v[116:119], v[84:87]
	ds_read_b128 v[216:219], v15 offset:4096
	v_mfma_f32_16x16x32_bf16 v[80:83], v[140:143], v[116:119], v[80:83]
	ds_read_b128 v[228:231], v15 offset:6144
	v_mfma_f32_16x16x32_bf16 v[76:79], v[128:131], v[120:123], v[76:79]
	v_mfma_f32_16x16x32_bf16 v[72:75], v[132:135], v[120:123], v[72:75]
	v_mfma_f32_16x16x32_bf16 v[68:71], v[136:139], v[120:123], v[68:71]
	v_mfma_f32_16x16x32_bf16 v[64:67], v[140:143], v[120:123], v[64:67]
	v_mfma_f32_16x16x32_bf16 v[60:63], v[128:131], v[124:127], v[60:63]
	v_mfma_f32_16x16x32_bf16 v[56:59], v[132:135], v[124:127], v[56:59]
	v_mfma_f32_16x16x32_bf16 v[52:55], v[136:139], v[124:127], v[52:55]
	v_mfma_f32_16x16x32_bf16 v[48:51], v[140:143], v[124:127], v[48:51]
	s_mov_b32 s13, s12
	s_add_u32 s12, s12, 0xc000
	s_sub_u32 vcc_lo, s12, 0x24000
	s_cselect_b32 s12, s12, vcc_lo
	s_waitcnt lgkmcnt(0)
	v_mfma_f32_16x16x32_bf16 v[108:111], v[160:163], v[144:147], v[108:111]
	v_mfma_f32_16x16x32_bf16 v[104:107], v[164:167], v[144:147], v[104:107]
	v_mfma_f32_16x16x32_bf16 v[100:103], v[216:219], v[144:147], v[100:103]
	v_mfma_f32_16x16x32_bf16 v[96:99], v[228:231], v[144:147], v[96:99]
	v_mfma_f32_16x16x32_bf16 v[92:95], v[160:163], v[148:151], v[92:95]
	v_mfma_f32_16x16x32_bf16 v[88:91], v[164:167], v[148:151], v[88:91]
	v_mfma_f32_16x16x32_bf16 v[84:87], v[216:219], v[148:151], v[84:87]
	v_mfma_f32_16x16x32_bf16 v[80:83], v[228:231], v[148:151], v[80:83]
	v_mfma_f32_16x16x32_bf16 v[76:79], v[160:163], v[152:155], v[76:79]
	v_mfma_f32_16x16x32_bf16 v[72:75], v[164:167], v[152:155], v[72:75]
	v_mfma_f32_16x16x32_bf16 v[68:71], v[216:219], v[152:155], v[68:71]
	v_mfma_f32_16x16x32_bf16 v[64:67], v[228:231], v[152:155], v[64:67]
	v_mfma_f32_16x16x32_bf16 v[60:63], v[160:163], v[156:159], v[60:63]
	v_mfma_f32_16x16x32_bf16 v[56:59], v[164:167], v[156:159], v[56:59]
	v_mfma_f32_16x16x32_bf16 v[52:55], v[216:219], v[156:159], v[52:55]
	v_mfma_f32_16x16x32_bf16 v[48:51], v[228:231], v[156:159], v[48:51]
	s_and_b64 vcc, exec, s[18:19]
	s_nop 7
	s_branch .LBB0_769

.LBB0_1485:
	s_or_b64 exec, exec, s[0:1]
	v_readlane_b32 s0, v252, 21
	s_waitcnt lgkmcnt(0)
	v_mov_b32_e32 v0, v170
	s_cmpk_gt_u32 s0, 0x7ff
	s_barrier
	v_readlane_b32 s1, v252, 22
	s_cbranch_scc1 .LBB0_1505
	v_lshlrev_b32_e32 v2, 4, v0
	v_readlane_b32 s0, v252, 13
	v_and_b32_e32 v174, 0x70, v2
	v_mov_b32_e32 v175, 0
	v_readlane_b32 s1, v252, 14
	v_lshl_add_u64 v[2:3], s[76:77], 0, v[174:175]
	v_and_b32_e32 v4, 15, v0
	v_lshl_add_u64 v[176:177], s[0:1], 0, v[174:175]
	s_mov_b64 s[0:1], 0x1800000
	v_lshl_add_u64 v[178:179], v[2:3], 0, s[0:1]
	v_lshrrev_b32_e32 v2, 4, v0
	v_xor_b32_e32 v2, v2, v0
	v_ashrrev_i32_e32 v171, 3, v0
	v_bfe_u32 v5, v0, 6, 1
	v_ashrrev_i32_e32 v6, 7, v0
	v_lshlrev_b32_e32 v2, 4, v2
	v_lshlrev_b32_e32 v4, 7, v4
	v_lshlrev_b32_e32 v3, 7, v171
	v_and_b32_e32 v2, 0x70, v2
	v_readlane_b32 s0, v252, 29
	v_lshl_or_b32 v7, v6, 13, v4
	v_lshl_or_b32 v4, v5, 13, v4
	v_readlane_b32 s2, v252, 16
	v_bfe_u32 v1, v0, 4, 2
	v_add3_u32 v214, s0, v3, v2
	v_add_u32_e32 v8, s0, v4
	v_bfe_u32 v9, v0, 1, 3
	v_readlane_b32 s0, v252, 30
	v_add3_u32 v173, 16, v3, v2
	v_xor_b32_e32 v10, v1, v9
	v_bitop3_b32 v1, v1, v9, 4 bitop3:0x36
	v_add3_u32 v219, s0, v3, v2
	v_add_u32_e32 v2, s0, v4
	s_lshl_b32 s0, s2, 15
	v_readlane_b32 s1, v253, 24
	v_and_b32_e32 v169, 63, v0
	v_add_u32_e32 v7, 16, v7
	v_lshlrev_b32_e32 v9, 4, v10
	v_lshlrev_b32_e32 v1, 4, v1
	v_and_b32_e32 v0, 7, v0
	s_add_i32 s15, s0, s1
	s_lshl_b32 s0, s2, 11
	s_lshl_b32 s1, s62, 3
	s_lshl_b32 s14, s2, 8
	v_add_u32_e32 v215, v7, v9
	v_add_u32_e32 v216, v8, v9
	v_add_u32_e32 v217, v7, v1
	v_add_u32_e32 v218, v8, v1
	v_add_u32_e32 v220, v2, v9
	v_add_u32_e32 v221, v2, v1
	v_lshlrev_b32_e32 v222, 6, v6
	v_lshlrev_b32_e32 v223, 6, v5
	v_lshlrev_b32_e32 v180, 4, v0
	v_mov_b32_e32 v181, v175
	s_add_i32 s16, s0, s1
	s_lshl_b32 s17, s51, 3
	s_mov_b64 s[8:9], 0
	s_mov_b64 s[0:1], 0x20080
	s_mov_b64 s[2:3], 0x20000
	s_mov_b64 s[4:5], 0x100
	s_movk_i32 s18, 0x7fff
	s_mov_b32 s19, s62
	s_mov_b32 s4, 0
	s_mov_b32 s5, 0x18000
	s_branch .LBB0_1488

.LBB0_1488:
	s_add_i32 s6, s19, s14
	s_mov_b32 s100, s6
	s_lshr_b32 s98, s100, 7
	s_lshl_b32 s98, s98, 10
	s_and_b32 s99, s100, 3
	s_lshl_b32 s99, s99, 8
	s_or_b32 s20, s98, s99
	s_lshl_b32 s98, s100, 5
	s_and_b32 s21, s98, 0xf80
	v_add_u32_e32 v48, s20, v171
	v_add_u32_e32 v50, s21, v171
	v_ashrrev_i32_e32 v49, 31, v48
	v_ashrrev_i32_e32 v51, 31, v50
	v_lshlrev_b64 v[48:49], 11, v[48:49]
	v_lshlrev_b64 v[50:51], 11, v[50:51]
	v_lshl_add_u64 v[48:49], v[176:177], 0, v[48:49]
	v_lshl_add_u64 v[50:51], v[178:179], 0, v[50:51]
	v_writelane_b32 v250, s8, 4
	s_and_b64 vcc, exec, s[8:9]
	s_cbranch_vccnz .LBB0_1490
	v_add_co_u32_e32 v4, vcc, 0x20000, v48
	s_nop 1
	v_addc_co_u32_e32 v5, vcc, 0, v49, vcc
	v_add_co_u32_e32 v8, vcc, 0x40000, v48
	s_nop 1
	v_addc_co_u32_e32 v9, vcc, 0, v49, vcc
	v_add_co_u32_e32 v12, vcc, 0x60000, v48
	s_nop 1
	v_addc_co_u32_e32 v13, vcc, 0, v49, vcc
	v_add_co_u32_e32 v24, vcc, 0x20000, v50
	s_nop 1
	v_addc_co_u32_e32 v25, vcc, 0, v51, vcc
	s_nop 0
	s_nop 0
	s_nop 0
	s_nop 0
	s_nop 0
	s_nop 0
	s_nop 0
.LBB0_1490:
	s_mov_b32 s6, s21
	v_add_u32_e32 v52, s6, v171
	v_ashrrev_i32_e32 v53, 31, v52
	s_mov_b32 s6, s20
	s_add_i32 s19, s19, s51
	v_lshlrev_b64 v[52:53], 11, v[52:53]
	s_cmpk_gt_u32 s19, 0xff
	v_lshl_add_u64 v[182:183], s[76:77], 0, v[52:53]
	v_add_u32_e32 v52, s6, v171
	s_cselect_b64 s[6:7], -1, 0
	s_add_i32 s12, s19, s14
	s_cmpk_lt_u32 s19, 0x100
	s_cselect_b64 s[8:9], -1, 0
	s_and_b64 s[10:11], s[8:9], exec
	s_cselect_b32 s10, s12, 0
	s_mov_b32 s100, s10
	s_lshr_b32 s98, s100, 7
	s_lshl_b32 s98, s98, 10
	s_and_b32 s99, s100, 3
	s_lshl_b32 s99, s99, 8
	s_or_b32 s11, s98, s99
	s_lshl_b32 s98, s100, 5
	s_and_b32 s10, s98, 0xf80
	s_lshl_b32 s98, s11, 11
	s_add_u32 s98, s76, s98
	s_addc_u32 s99, s77, 0
	s_add_u32 s98, s98, 0x2800000
	s_addc_u32 s99, s99, 0
	s_lshl_b32 s100, s10, 11
	s_add_u32 s100, s76, s100
	s_addc_u32 s101, s77, 0
	s_add_u32 s100, s100, 0x1800000
	s_addc_u32 s101, s101, 0
	v_writelane_b32 v250, s98, 0
	v_writelane_b32 v250, s99, 1
	v_writelane_b32 v250, s100, 2
	v_writelane_b32 v250, s101, 3
	v_add_u32_e32 v54, s10, v171
	s_mov_b32 s10, 0x20000
	v_add_co_u32_e32 v20, vcc, s10, v50
	v_ashrrev_i32_e32 v53, 31, v52
	s_nop 0
	v_addc_co_u32_e32 v21, vcc, 0, v51, vcc
	v_add_co_u32_e32 v32, vcc, 0x60000, v48
	s_nop 0
	v_addc_co_u32_e32 v33, vcc, 0, v49, vcc
	v_add_co_u32_e32 v32, vcc, 0x40000, v48
	v_lshlrev_b64 v[52:53], 11, v[52:53]
	s_nop 0
	v_addc_co_u32_e32 v33, vcc, 0, v49, vcc
	v_add_co_u32_e32 v36, vcc, 0x20000, v48
	s_nop 0
	v_addc_co_u32_e32 v37, vcc, 0, v49, vcc
	s_nop 0
	v_lshl_add_u64 v[184:185], s[76:77], 0, v[52:53]
	v_add_u32_e32 v52, s11, v171
	v_ashrrev_i32_e32 v53, 31, v52
	v_lshlrev_b64 v[52:53], 11, v[52:53]
	v_lshl_add_u64 v[186:187], v[176:177], 0, v[52:53]
	s_mov_b64 s[10:11], 0x40080
	v_ashrrev_i32_e32 v55, 31, v54
	v_lshl_add_u64 v[192:193], v[186:187], 0, s[10:11]
	s_mov_b64 s[10:11], 0x60080
	v_lshlrev_b64 v[54:55], 11, v[54:55]
	v_lshl_add_u64 v[194:195], v[186:187], 0, s[10:11]
	s_mov_b64 s[10:11], 0x40000
	v_lshl_add_u64 v[188:189], v[178:179], 0, v[54:55]
	v_lshl_add_u64 v[200:201], v[186:187], 0, s[10:11]
	s_mov_b64 s[10:11], 0x60000
	v_mov_b32_e32 v48, 0
	s_mov_b32 s22, 0
	v_lshl_add_u64 v[190:191], v[186:187], 0, s[0:1]
	v_lshl_add_u64 v[196:197], v[188:189], 0, s[0:1]
	v_lshl_add_u64 v[198:199], v[186:187], 0, s[2:3]
	v_lshl_add_u64 v[202:203], v[186:187], 0, s[10:11]
	v_lshl_add_u64 v[204:205], v[188:189], 0, s[2:3]
	v_mov_b32_e32 v49, v48
	v_mov_b32_e32 v50, v48
	v_mov_b32_e32 v51, v48
	v_mov_b32_e32 v52, v48
	v_mov_b32_e32 v53, v48
	v_mov_b32_e32 v54, v48
	v_mov_b32_e32 v55, v48
	v_mov_b32_e32 v56, v48
	v_mov_b32_e32 v57, v48
	v_mov_b32_e32 v58, v48
	v_mov_b32_e32 v59, v48
	v_mov_b32_e32 v60, v48
	v_mov_b32_e32 v61, v48
	v_mov_b32_e32 v62, v48
	v_mov_b32_e32 v63, v48
	v_mov_b32_e32 v64, v48
	v_mov_b32_e32 v65, v48
	v_mov_b32_e32 v66, v48
	v_mov_b32_e32 v67, v48
	v_mov_b32_e32 v68, v48
	v_mov_b32_e32 v69, v48
	v_mov_b32_e32 v70, v48
	v_mov_b32_e32 v71, v48
	v_mov_b32_e32 v72, v48
	v_mov_b32_e32 v73, v48
	v_mov_b32_e32 v74, v48
	v_mov_b32_e32 v75, v48
	v_mov_b32_e32 v76, v48
	v_mov_b32_e32 v77, v48
	v_mov_b32_e32 v78, v48
	v_mov_b32_e32 v79, v48
	v_mov_b32_e32 v80, v48
	v_mov_b32_e32 v81, v48
	v_mov_b32_e32 v82, v48
	v_mov_b32_e32 v83, v48
	v_mov_b32_e32 v84, v48
	v_mov_b32_e32 v85, v48
	v_mov_b32_e32 v86, v48
	v_mov_b32_e32 v87, v48
	v_mov_b32_e32 v88, v48
	v_mov_b32_e32 v89, v48
	v_mov_b32_e32 v90, v48
	v_mov_b32_e32 v91, v48
	v_mov_b32_e32 v92, v48
	v_mov_b32_e32 v93, v48
	v_mov_b32_e32 v94, v48
	v_mov_b32_e32 v95, v48
	v_mov_b32_e32 v96, v48
	v_mov_b32_e32 v97, v48
	v_mov_b32_e32 v98, v48
	v_mov_b32_e32 v99, v48
	v_mov_b32_e32 v100, v48
	v_mov_b32_e32 v101, v48
	v_mov_b32_e32 v102, v48
	v_mov_b32_e32 v103, v48
	v_mov_b32_e32 v104, v48
	v_mov_b32_e32 v105, v48
	v_mov_b32_e32 v106, v48
	v_mov_b32_e32 v107, v48
	v_mov_b32_e32 v108, v48
	v_mov_b32_e32 v109, v48
	v_mov_b32_e32 v110, v48
	v_mov_b32_e32 v111, v48
	v_lshrrev_b32_e32 v7, 1, v171
	v_lshrrev_b32_e32 v6, 4, v180
	v_xor_b32_e32 v7, v7, v6
	v_and_b32_e32 v7, 7, v7
	v_lshlrev_b32_e32 v7, 4, v7
	v_lshl_add_u32 v0, v171, 11, v7
	v_add_u32_e32 v1, 0x20000, v0
	v_add_u32_e32 v2, 0x40000, v0
	v_add_u32_e32 v3, 0x60000, v0
	v_and_b32_e32 v4, 15, v171
	v_lshlrev_b32_e32 v4, 2, v4
	v_lshrrev_b32_e32 v5, 4, v171
	v_add_u32_e32 v4, v4, v5
	v_lshl_add_u32 v4, v4, 11, v7
	v_add_u32_e32 v5, 0x20000, v4
	v_lshrrev_b32_e32 v6, 3, v171
	v_lshl_add_u32 v6, v6, 10, 16
	v_add_u32_e32 v10, 0xffff8000, v216
	v_add_u32_e32 v11, 0xffff8000, v218
	v_readlane_b32 vcc_hi, v250, 4
	s_lshl_b32 s98, s20, 11
	s_add_u32 s98, s76, s98
	s_addc_u32 s99, s77, 0
	s_add_u32 s98, s98, 0x2800000
	s_addc_u32 s99, s99, 0
	s_lshl_b32 s100, s21, 11
	s_add_u32 s100, s76, s100
	s_addc_u32 s101, s77, 0
	s_add_u32 s100, s100, 0x1800000
	s_addc_u32 s101, s101, 0
	s_cmp_lg_u32 vcc_hi, 0
	s_cbranch_scc1 .Lmyf_primed
	v_readfirstlane_b32 vcc_lo, v6
	s_nop 0
	s_add_u32 vcc_lo, vcc_lo, s4
	s_mov_b32 m0, vcc_lo
	s_nop 0
	global_load_lds_dwordx4 v0, s[98:99]
	s_add_u32 m0, m0, 0x2000
	s_nop 0
	global_load_lds_dwordx4 v1, s[98:99]
	s_add_u32 m0, m0, 0x2000
	s_nop 0
	global_load_lds_dwordx4 v2, s[98:99]
	s_add_u32 m0, m0, 0x2000
	s_nop 0
	global_load_lds_dwordx4 v3, s[98:99]
	s_add_u32 m0, vcc_lo, 0x8000
	s_nop 0
	global_load_lds_dwordx4 v4, s[100:101]
	s_add_u32 m0, m0, 0x2000
	s_nop 0
	global_load_lds_dwordx4 v5, s[100:101]
	s_add_u32 s98, s98, 0x80
	s_addc_u32 s99, s99, 0
	s_add_u32 s100, s100, 0x80
	s_addc_u32 s101, s101, 0
	s_add_u32 vcc_hi, s4, 0xc000
	s_sub_u32 vcc_lo, vcc_hi, 0x24000
	s_cselect_b32 vcc_hi, vcc_hi, vcc_lo
	v_readfirstlane_b32 vcc_lo, v6
	s_nop 0
	s_add_u32 vcc_lo, vcc_lo, vcc_hi
	s_mov_b32 m0, vcc_lo
	s_nop 0
	global_load_lds_dwordx4 v0, s[98:99]
	s_add_u32 m0, m0, 0x2000
	s_nop 0
	global_load_lds_dwordx4 v1, s[98:99]
	s_add_u32 m0, m0, 0x2000
	s_nop 0
	global_load_lds_dwordx4 v2, s[98:99]
	s_add_u32 m0, m0, 0x2000
	s_nop 0
	global_load_lds_dwordx4 v3, s[98:99]
	s_add_u32 m0, vcc_lo, 0x8000
	s_nop 0
	global_load_lds_dwordx4 v4, s[100:101]
	s_add_u32 m0, m0, 0x2000
	s_nop 0
	global_load_lds_dwordx4 v5, s[100:101]
	s_add_u32 s98, s98, 0x80
	s_addc_u32 s99, s99, 0
	s_add_u32 s100, s100, 0x80
	s_addc_u32 s101, s101, 0
	s_branch .LBB0_1492

.LBB0_1492:
	s_waitcnt vmcnt(6) lgkmcnt(0)
	s_barrier
	v_add_u32_e32 v12, s4, v215
	v_add_u32_e32 v13, s4, v10
	v_add_u32_e32 v14, s4, v217
	v_add_u32_e32 v15, s4, v11
	v_readfirstlane_b32 vcc_lo, v6
	s_nop 0
	s_add_u32 vcc_lo, vcc_lo, s5
	ds_read_b128 v[112:115], v12
	ds_read_b128 v[116:119], v12 offset:2048
	ds_read_b128 v[120:123], v12 offset:4096
	ds_read_b128 v[124:127], v12 offset:6144
	ds_read_b128 v[128:131], v13
	ds_read_b128 v[132:135], v13 offset:2048
	ds_read_b128 v[136:139], v13 offset:4096
	ds_read_b128 v[140:143], v13 offset:6144
	s_mov_b32 m0, vcc_lo
	s_nop 0
	global_load_lds_dwordx4 v0, s[98:99]
	s_add_u32 m0, m0, 0x2000
	s_nop 0
	global_load_lds_dwordx4 v1, s[98:99]
	s_add_u32 m0, m0, 0x2000
	s_nop 0
	global_load_lds_dwordx4 v2, s[98:99]
	s_add_u32 m0, m0, 0x2000
	s_nop 0
	global_load_lds_dwordx4 v3, s[98:99]
	s_add_u32 m0, vcc_lo, 0x8000
	s_nop 0
	global_load_lds_dwordx4 v4, s[100:101]
	s_add_u32 m0, m0, 0x2000
	s_nop 0
	global_load_lds_dwordx4 v5, s[100:101]
	s_add_u32 s98, s98, 0x80
	s_addc_u32 s99, s99, 0
	s_add_u32 s100, s100, 0x80
	s_addc_u32 s101, s101, 0
	s_waitcnt lgkmcnt(0)
	v_mfma_f32_16x16x32_bf16 v[108:111], v[128:131], v[112:115], v[108:111]
	ds_read_b128 v[144:147], v14
	v_mfma_f32_16x16x32_bf16 v[104:107], v[132:135], v[112:115], v[104:107]
	ds_read_b128 v[148:151], v14 offset:2048
	v_mfma_f32_16x16x32_bf16 v[100:103], v[136:139], v[112:115], v[100:103]
	ds_read_b128 v[152:155], v14 offset:4096
	v_mfma_f32_16x16x32_bf16 v[96:99], v[140:143], v[112:115], v[96:99]
	ds_read_b128 v[156:159], v14 offset:6144
	v_mfma_f32_16x16x32_bf16 v[92:95], v[128:131], v[116:119], v[92:95]
	ds_read_b128 v[160:163], v15
	v_mfma_f32_16x16x32_bf16 v[88:91], v[132:135], v[116:119], v[88:91]
	ds_read_b128 v[164:167], v15 offset:2048
	v_mfma_f32_16x16x32_bf16 v[84:87], v[136:139], v[116:119], v[84:87]
	ds_read_b128 v[224:227], v15 offset:4096
	v_mfma_f32_16x16x32_bf16 v[80:83], v[140:143], v[116:119], v[80:83]
	ds_read_b128 v[228:231], v15 offset:6144
	v_mfma_f32_16x16x32_bf16 v[76:79], v[128:131], v[120:123], v[76:79]
	v_mfma_f32_16x16x32_bf16 v[72:75], v[132:135], v[120:123], v[72:75]
	v_mfma_f32_16x16x32_bf16 v[68:71], v[136:139], v[120:123], v[68:71]
	v_mfma_f32_16x16x32_bf16 v[64:67], v[140:143], v[120:123], v[64:67]
	v_mfma_f32_16x16x32_bf16 v[60:63], v[128:131], v[124:127], v[60:63]
	v_mfma_f32_16x16x32_bf16 v[56:59], v[132:135], v[124:127], v[56:59]
	v_mfma_f32_16x16x32_bf16 v[52:55], v[136:139], v[124:127], v[52:55]
	v_mfma_f32_16x16x32_bf16 v[48:51], v[140:143], v[124:127], v[48:51]
	s_mov_b32 s5, s4
	s_add_u32 s4, s4, 0xc000
	s_sub_u32 vcc_lo, s4, 0x24000
	s_cselect_b32 s4, s4, vcc_lo
	s_mov_b32 s22, 1
.Lmyf_steady:
	s_waitcnt vmcnt(6) lgkmcnt(0)
	s_barrier
	v_add_u32_e32 v12, s4, v215
	v_add_u32_e32 v13, s4, v10
	v_add_u32_e32 v14, s4, v217
	v_add_u32_e32 v15, s4, v11
	v_readfirstlane_b32 vcc_lo, v6
	s_nop 0
	s_add_u32 vcc_lo, vcc_lo, s5
	s_mov_b32 m0, vcc_lo
	v_mfma_f32_16x16x32_bf16 v[108:111], v[160:163], v[144:147], v[108:111]
	ds_read_b128 v[112:115], v12
	global_load_lds_dwordx4 v0, s[98:99]
	s_add_u32 m0, m0, 0x2000
	v_mfma_f32_16x16x32_bf16 v[104:107], v[164:167], v[144:147], v[104:107]
	ds_read_b128 v[116:119], v12 offset:2048
	global_load_lds_dwordx4 v1, s[98:99]
	s_add_u32 m0, m0, 0x2000
	v_mfma_f32_16x16x32_bf16 v[100:103], v[224:227], v[144:147], v[100:103]
	ds_read_b128 v[120:123], v12 offset:4096
	global_load_lds_dwordx4 v2, s[98:99]
	s_add_u32 m0, m0, 0x2000
	v_mfma_f32_16x16x32_bf16 v[96:99], v[228:231], v[144:147], v[96:99]
	ds_read_b128 v[124:127], v12 offset:6144
	global_load_lds_dwordx4 v3, s[98:99]
	s_add_u32 m0, vcc_lo, 0x8000
	v_mfma_f32_16x16x32_bf16 v[92:95], v[160:163], v[148:151], v[92:95]
	ds_read_b128 v[128:131], v13
	global_load_lds_dwordx4 v4, s[100:101]
	s_add_u32 m0, m0, 0x2000
	v_mfma_f32_16x16x32_bf16 v[88:91], v[164:167], v[148:151], v[88:91]
	ds_read_b128 v[132:135], v13 offset:2048
	global_load_lds_dwordx4 v5, s[100:101]
	v_mfma_f32_16x16x32_bf16 v[84:87], v[224:227], v[148:151], v[84:87]
	ds_read_b128 v[136:139], v13 offset:4096
	s_add_u32 s98, s98, 0x80
	s_addc_u32 s99, s99, 0
	s_add_u32 s100, s100, 0x80
	s_addc_u32 s101, s101, 0
	v_mfma_f32_16x16x32_bf16 v[80:83], v[228:231], v[148:151], v[80:83]
	ds_read_b128 v[140:143], v13 offset:6144
	v_mfma_f32_16x16x32_bf16 v[76:79], v[160:163], v[152:155], v[76:79]
	v_mfma_f32_16x16x32_bf16 v[72:75], v[164:167], v[152:155], v[72:75]
	v_mfma_f32_16x16x32_bf16 v[68:71], v[224:227], v[152:155], v[68:71]
	v_mfma_f32_16x16x32_bf16 v[64:67], v[228:231], v[152:155], v[64:67]
	v_mfma_f32_16x16x32_bf16 v[60:63], v[160:163], v[156:159], v[60:63]
	v_mfma_f32_16x16x32_bf16 v[56:59], v[164:167], v[156:159], v[56:59]
	v_mfma_f32_16x16x32_bf16 v[52:55], v[224:227], v[156:159], v[52:55]
	v_mfma_f32_16x16x32_bf16 v[48:51], v[228:231], v[156:159], v[48:51]
	s_waitcnt lgkmcnt(0)
	v_mfma_f32_16x16x32_bf16 v[108:111], v[128:131], v[112:115], v[108:111]
	ds_read_b128 v[144:147], v14
	v_mfma_f32_16x16x32_bf16 v[104:107], v[132:135], v[112:115], v[104:107]
	ds_read_b128 v[148:151], v14 offset:2048
	v_mfma_f32_16x16x32_bf16 v[100:103], v[136:139], v[112:115], v[100:103]
	ds_read_b128 v[152:155], v14 offset:4096
	v_mfma_f32_16x16x32_bf16 v[96:99], v[140:143], v[112:115], v[96:99]
	ds_read_b128 v[156:159], v14 offset:6144
	v_mfma_f32_16x16x32_bf16 v[92:95], v[128:131], v[116:119], v[92:95]
	ds_read_b128 v[160:163], v15
	v_mfma_f32_16x16x32_bf16 v[88:91], v[132:135], v[116:119], v[88:91]
	ds_read_b128 v[164:167], v15 offset:2048
	v_mfma_f32_16x16x32_bf16 v[84:87], v[136:139], v[116:119], v[84:87]
	ds_read_b128 v[224:227], v15 offset:4096
	v_mfma_f32_16x16x32_bf16 v[80:83], v[140:143], v[116:119], v[80:83]
	ds_read_b128 v[228:231], v15 offset:6144
	v_mfma_f32_16x16x32_bf16 v[76:79], v[128:131], v[120:123], v[76:79]
	v_mfma_f32_16x16x32_bf16 v[72:75], v[132:135], v[120:123], v[72:75]
	v_mfma_f32_16x16x32_bf16 v[68:71], v[136:139], v[120:123], v[68:71]
	v_mfma_f32_16x16x32_bf16 v[64:67], v[140:143], v[120:123], v[64:67]
	v_mfma_f32_16x16x32_bf16 v[60:63], v[128:131], v[124:127], v[60:63]
	v_mfma_f32_16x16x32_bf16 v[56:59], v[132:135], v[124:127], v[56:59]
	v_mfma_f32_16x16x32_bf16 v[52:55], v[136:139], v[124:127], v[52:55]
	v_mfma_f32_16x16x32_bf16 v[48:51], v[140:143], v[124:127], v[48:51]
	s_mov_b32 s5, s4
	s_add_u32 s4, s4, 0xc000
	s_sub_u32 vcc_lo, s4, 0x24000
	s_cselect_b32 s4, s4, vcc_lo
	s_add_i32 s22, s22, 1
	s_cmp_lt_u32 s22, 14
	s_cbranch_scc1 .Lmyf_steady
	s_andn2_b64 vcc, exec, s[8:9]
	s_cbranch_vccnz .Lmyf_prelast_n
	v_readlane_b32 s98, v250, 0
	v_readlane_b32 s99, v250, 1
	v_readlane_b32 s100, v250, 2
	v_readlane_b32 s101, v250, 3
	s_waitcnt vmcnt(6) lgkmcnt(0)
	s_barrier
	v_add_u32_e32 v12, s4, v215
	v_add_u32_e32 v13, s4, v10
	v_add_u32_e32 v14, s4, v217
	v_add_u32_e32 v15, s4, v11
	v_readfirstlane_b32 vcc_lo, v6
	s_nop 0
	s_add_u32 vcc_lo, vcc_lo, s5
	s_mov_b32 m0, vcc_lo
	v_mfma_f32_16x16x32_bf16 v[108:111], v[160:163], v[144:147], v[108:111]
	ds_read_b128 v[112:115], v12
	global_load_lds_dwordx4 v0, s[98:99]
	s_add_u32 m0, m0, 0x2000
	v_mfma_f32_16x16x32_bf16 v[104:107], v[164:167], v[144:147], v[104:107]
	ds_read_b128 v[116:119], v12 offset:2048
	global_load_lds_dwordx4 v1, s[98:99]
	s_add_u32 m0, m0, 0x2000
	v_mfma_f32_16x16x32_bf16 v[100:103], v[224:227], v[144:147], v[100:103]
	ds_read_b128 v[120:123], v12 offset:4096
	global_load_lds_dwordx4 v2, s[98:99]
	s_add_u32 m0, m0, 0x2000
	v_mfma_f32_16x16x32_bf16 v[96:99], v[228:231], v[144:147], v[96:99]
	ds_read_b128 v[124:127], v12 offset:6144
	global_load_lds_dwordx4 v3, s[98:99]
	s_add_u32 m0, vcc_lo, 0x8000
	v_mfma_f32_16x16x32_bf16 v[92:95], v[160:163], v[148:151], v[92:95]
	ds_read_b128 v[128:131], v13
	global_load_lds_dwordx4 v4, s[100:101]
	s_add_u32 m0, m0, 0x2000
	v_mfma_f32_16x16x32_bf16 v[88:91], v[164:167], v[148:151], v[88:91]
	ds_read_b128 v[132:135], v13 offset:2048
	global_load_lds_dwordx4 v5, s[100:101]
	v_mfma_f32_16x16x32_bf16 v[84:87], v[224:227], v[148:151], v[84:87]
	ds_read_b128 v[136:139], v13 offset:4096
	s_add_u32 s98, s98, 0x80
	s_addc_u32 s99, s99, 0
	s_add_u32 s100, s100, 0x80
	s_addc_u32 s101, s101, 0
	v_mfma_f32_16x16x32_bf16 v[80:83], v[228:231], v[148:151], v[80:83]
	ds_read_b128 v[140:143], v13 offset:6144
	v_mfma_f32_16x16x32_bf16 v[76:79], v[160:163], v[152:155], v[76:79]
	v_mfma_f32_16x16x32_bf16 v[72:75], v[164:167], v[152:155], v[72:75]
	v_mfma_f32_16x16x32_bf16 v[68:71], v[224:227], v[152:155], v[68:71]
	v_mfma_f32_16x16x32_bf16 v[64:67], v[228:231], v[152:155], v[64:67]
	v_mfma_f32_16x16x32_bf16 v[60:63], v[160:163], v[156:159], v[60:63]
	v_mfma_f32_16x16x32_bf16 v[56:59], v[164:167], v[156:159], v[56:59]
	v_mfma_f32_16x16x32_bf16 v[52:55], v[224:227], v[156:159], v[52:55]
	v_mfma_f32_16x16x32_bf16 v[48:51], v[228:231], v[156:159], v[48:51]
	s_waitcnt lgkmcnt(0)
	v_mfma_f32_16x16x32_bf16 v[108:111], v[128:131], v[112:115], v[108:111]
	ds_read_b128 v[144:147], v14
	v_mfma_f32_16x16x32_bf16 v[104:107], v[132:135], v[112:115], v[104:107]
	ds_read_b128 v[148:151], v14 offset:2048
	v_mfma_f32_16x16x32_bf16 v[100:103], v[136:139], v[112:115], v[100:103]
	ds_read_b128 v[152:155], v14 offset:4096
	v_mfma_f32_16x16x32_bf16 v[96:99], v[140:143], v[112:115], v[96:99]
	ds_read_b128 v[156:159], v14 offset:6144
	v_mfma_f32_16x16x32_bf16 v[92:95], v[128:131], v[116:119], v[92:95]
	ds_read_b128 v[160:163], v15
	v_mfma_f32_16x16x32_bf16 v[88:91], v[132:135], v[116:119], v[88:91]
	ds_read_b128 v[164:167], v15 offset:2048
	v_mfma_f32_16x16x32_bf16 v[84:87], v[136:139], v[116:119], v[84:87]
	ds_read_b128 v[224:227], v15 offset:4096
	v_mfma_f32_16x16x32_bf16 v[80:83], v[140:143], v[116:119], v[80:83]
	ds_read_b128 v[228:231], v15 offset:6144
	v_mfma_f32_16x16x32_bf16 v[76:79], v[128:131], v[120:123], v[76:79]
	v_mfma_f32_16x16x32_bf16 v[72:75], v[132:135], v[120:123], v[72:75]
	v_mfma_f32_16x16x32_bf16 v[68:71], v[136:139], v[120:123], v[68:71]
	v_mfma_f32_16x16x32_bf16 v[64:67], v[140:143], v[120:123], v[64:67]
	v_mfma_f32_16x16x32_bf16 v[60:63], v[128:131], v[124:127], v[60:63]
	v_mfma_f32_16x16x32_bf16 v[56:59], v[132:135], v[124:127], v[56:59]
	v_mfma_f32_16x16x32_bf16 v[52:55], v[136:139], v[124:127], v[52:55]
	v_mfma_f32_16x16x32_bf16 v[48:51], v[140:143], v[124:127], v[48:51]
	s_mov_b32 s5, s4
	s_add_u32 s4, s4, 0xc000
	s_sub_u32 vcc_lo, s4, 0x24000
	s_cselect_b32 s4, s4, vcc_lo
	s_waitcnt vmcnt(6) lgkmcnt(0)
	s_barrier
	v_add_u32_e32 v12, s4, v215
	v_add_u32_e32 v13, s4, v10
	v_add_u32_e32 v14, s4, v217
	v_add_u32_e32 v15, s4, v11
	v_readfirstlane_b32 vcc_lo, v6
	s_nop 0
	s_add_u32 vcc_lo, vcc_lo, s5
	s_mov_b32 m0, vcc_lo
	v_mfma_f32_16x16x32_bf16 v[108:111], v[160:163], v[144:147], v[108:111]
	ds_read_b128 v[112:115], v12
	global_load_lds_dwordx4 v0, s[98:99]
	s_add_u32 m0, m0, 0x2000
	v_mfma_f32_16x16x32_bf16 v[104:107], v[164:167], v[144:147], v[104:107]
	ds_read_b128 v[116:119], v12 offset:2048
	global_load_lds_dwordx4 v1, s[98:99]
	s_add_u32 m0, m0, 0x2000
	v_mfma_f32_16x16x32_bf16 v[100:103], v[224:227], v[144:147], v[100:103]
	ds_read_b128 v[120:123], v12 offset:4096
	global_load_lds_dwordx4 v2, s[98:99]
	s_add_u32 m0, m0, 0x2000
	v_mfma_f32_16x16x32_bf16 v[96:99], v[228:231], v[144:147], v[96:99]
	ds_read_b128 v[124:127], v12 offset:6144
	global_load_lds_dwordx4 v3, s[98:99]
	s_add_u32 m0, vcc_lo, 0x8000
	v_mfma_f32_16x16x32_bf16 v[92:95], v[160:163], v[148:151], v[92:95]
	ds_read_b128 v[128:131], v13
	global_load_lds_dwordx4 v4, s[100:101]
	s_add_u32 m0, m0, 0x2000
	v_mfma_f32_16x16x32_bf16 v[88:91], v[164:167], v[148:151], v[88:91]
	ds_read_b128 v[132:135], v13 offset:2048
	global_load_lds_dwordx4 v5, s[100:101]
	v_mfma_f32_16x16x32_bf16 v[84:87], v[224:227], v[148:151], v[84:87]
	ds_read_b128 v[136:139], v13 offset:4096
	s_add_u32 s98, s98, 0x80
	s_addc_u32 s99, s99, 0
	s_add_u32 s100, s100, 0x80
	s_addc_u32 s101, s101, 0
	v_mfma_f32_16x16x32_bf16 v[80:83], v[228:231], v[148:151], v[80:83]
	ds_read_b128 v[140:143], v13 offset:6144
	v_mfma_f32_16x16x32_bf16 v[76:79], v[160:163], v[152:155], v[76:79]
	v_mfma_f32_16x16x32_bf16 v[72:75], v[164:167], v[152:155], v[72:75]
	v_mfma_f32_16x16x32_bf16 v[68:71], v[224:227], v[152:155], v[68:71]
	v_mfma_f32_16x16x32_bf16 v[64:67], v[228:231], v[152:155], v[64:67]
	v_mfma_f32_16x16x32_bf16 v[60:63], v[160:163], v[156:159], v[60:63]
	v_mfma_f32_16x16x32_bf16 v[56:59], v[164:167], v[156:159], v[56:59]
	v_mfma_f32_16x16x32_bf16 v[52:55], v[224:227], v[156:159], v[52:55]
	v_mfma_f32_16x16x32_bf16 v[48:51], v[228:231], v[156:159], v[48:51]
	s_waitcnt lgkmcnt(0)
	v_mfma_f32_16x16x32_bf16 v[108:111], v[128:131], v[112:115], v[108:111]
	ds_read_b128 v[144:147], v14
	v_mfma_f32_16x16x32_bf16 v[104:107], v[132:135], v[112:115], v[104:107]
	ds_read_b128 v[148:151], v14 offset:2048
	v_mfma_f32_16x16x32_bf16 v[100:103], v[136:139], v[112:115], v[100:103]
	ds_read_b128 v[152:155], v14 offset:4096
	v_mfma_f32_16x16x32_bf16 v[96:99], v[140:143], v[112:115], v[96:99]
	ds_read_b128 v[156:159], v14 offset:6144
	v_mfma_f32_16x16x32_bf16 v[92:95], v[128:131], v[116:119], v[92:95]
	ds_read_b128 v[160:163], v15
	v_mfma_f32_16x16x32_bf16 v[88:91], v[132:135], v[116:119], v[88:91]
	ds_read_b128 v[164:167], v15 offset:2048
	v_mfma_f32_16x16x32_bf16 v[84:87], v[136:139], v[116:119], v[84:87]
	ds_read_b128 v[224:227], v15 offset:4096
	v_mfma_f32_16x16x32_bf16 v[80:83], v[140:143], v[116:119], v[80:83]
	ds_read_b128 v[228:231], v15 offset:6144
	v_mfma_f32_16x16x32_bf16 v[76:79], v[128:131], v[120:123], v[76:79]
	v_mfma_f32_16x16x32_bf16 v[72:75], v[132:135], v[120:123], v[72:75]
	v_mfma_f32_16x16x32_bf16 v[68:71], v[136:139], v[120:123], v[68:71]
	v_mfma_f32_16x16x32_bf16 v[64:67], v[140:143], v[120:123], v[64:67]
	v_mfma_f32_16x16x32_bf16 v[60:63], v[128:131], v[124:127], v[60:63]
	v_mfma_f32_16x16x32_bf16 v[56:59], v[132:135], v[124:127], v[56:59]
	v_mfma_f32_16x16x32_bf16 v[52:55], v[136:139], v[124:127], v[52:55]
	v_mfma_f32_16x16x32_bf16 v[48:51], v[140:143], v[124:127], v[48:51]
	s_mov_b32 s5, s4
	s_add_u32 s4, s4, 0xc000
	s_sub_u32 vcc_lo, s4, 0x24000
	s_cselect_b32 s4, s4, vcc_lo
	s_waitcnt lgkmcnt(0)
	v_mfma_f32_16x16x32_bf16 v[108:111], v[160:163], v[144:147], v[108:111]
	v_mfma_f32_16x16x32_bf16 v[104:107], v[164:167], v[144:147], v[104:107]
	v_mfma_f32_16x16x32_bf16 v[100:103], v[224:227], v[144:147], v[100:103]
	v_mfma_f32_16x16x32_bf16 v[96:99], v[228:231], v[144:147], v[96:99]
	v_mfma_f32_16x16x32_bf16 v[92:95], v[160:163], v[148:151], v[92:95]
	v_mfma_f32_16x16x32_bf16 v[88:91], v[164:167], v[148:151], v[88:91]
	v_mfma_f32_16x16x32_bf16 v[84:87], v[224:227], v[148:151], v[84:87]
	v_mfma_f32_16x16x32_bf16 v[80:83], v[228:231], v[148:151], v[80:83]
	v_mfma_f32_16x16x32_bf16 v[76:79], v[160:163], v[152:155], v[76:79]
	v_mfma_f32_16x16x32_bf16 v[72:75], v[164:167], v[152:155], v[72:75]
	v_mfma_f32_16x16x32_bf16 v[68:71], v[224:227], v[152:155], v[68:71]
	v_mfma_f32_16x16x32_bf16 v[64:67], v[228:231], v[152:155], v[64:67]
	v_mfma_f32_16x16x32_bf16 v[60:63], v[160:163], v[156:159], v[60:63]
	v_mfma_f32_16x16x32_bf16 v[56:59], v[164:167], v[156:159], v[56:59]
	v_mfma_f32_16x16x32_bf16 v[52:55], v[224:227], v[156:159], v[52:55]
	v_mfma_f32_16x16x32_bf16 v[48:51], v[228:231], v[156:159], v[48:51]
	s_and_b64 vcc, exec, s[10:11]
	s_nop 7
	s_branch .LBB0_1487
.Lmyf_prelast_n:
	s_waitcnt vmcnt(6) lgkmcnt(0)
	s_barrier
	v_add_u32_e32 v12, s4, v215
	v_add_u32_e32 v13, s4, v10
	v_add_u32_e32 v14, s4, v217
	v_add_u32_e32 v15, s4, v11
	v_mfma_f32_16x16x32_bf16 v[108:111], v[160:163], v[144:147], v[108:111]
	ds_read_b128 v[112:115], v12
	v_mfma_f32_16x16x32_bf16 v[104:107], v[164:167], v[144:147], v[104:107]
	ds_read_b128 v[116:119], v12 offset:2048
	v_mfma_f32_16x16x32_bf16 v[100:103], v[224:227], v[144:147], v[100:103]
	ds_read_b128 v[120:123], v12 offset:4096
	v_mfma_f32_16x16x32_bf16 v[96:99], v[228:231], v[144:147], v[96:99]
	ds_read_b128 v[124:127], v12 offset:6144
	v_mfma_f32_16x16x32_bf16 v[92:95], v[160:163], v[148:151], v[92:95]
	ds_read_b128 v[128:131], v13
	v_mfma_f32_16x16x32_bf16 v[88:91], v[164:167], v[148:151], v[88:91]
	ds_read_b128 v[132:135], v13 offset:2048
	v_mfma_f32_16x16x32_bf16 v[84:87], v[224:227], v[148:151], v[84:87]
	ds_read_b128 v[136:139], v13 offset:4096
	v_mfma_f32_16x16x32_bf16 v[80:83], v[228:231], v[148:151], v[80:83]
	ds_read_b128 v[140:143], v13 offset:6144
	v_mfma_f32_16x16x32_bf16 v[76:79], v[160:163], v[152:155], v[76:79]
	v_mfma_f32_16x16x32_bf16 v[72:75], v[164:167], v[152:155], v[72:75]
	v_mfma_f32_16x16x32_bf16 v[68:71], v[224:227], v[152:155], v[68:71]
	v_mfma_f32_16x16x32_bf16 v[64:67], v[228:231], v[152:155], v[64:67]
	v_mfma_f32_16x16x32_bf16 v[60:63], v[160:163], v[156:159], v[60:63]
	v_mfma_f32_16x16x32_bf16 v[56:59], v[164:167], v[156:159], v[56:59]
	v_mfma_f32_16x16x32_bf16 v[52:55], v[224:227], v[156:159], v[52:55]
	v_mfma_f32_16x16x32_bf16 v[48:51], v[228:231], v[156:159], v[48:51]
	s_waitcnt lgkmcnt(0)
	v_mfma_f32_16x16x32_bf16 v[108:111], v[128:131], v[112:115], v[108:111]
	ds_read_b128 v[144:147], v14
	v_mfma_f32_16x16x32_bf16 v[104:107], v[132:135], v[112:115], v[104:107]
	ds_read_b128 v[148:151], v14 offset:2048
	v_mfma_f32_16x16x32_bf16 v[100:103], v[136:139], v[112:115], v[100:103]
	ds_read_b128 v[152:155], v14 offset:4096
	v_mfma_f32_16x16x32_bf16 v[96:99], v[140:143], v[112:115], v[96:99]
	ds_read_b128 v[156:159], v14 offset:6144
	v_mfma_f32_16x16x32_bf16 v[92:95], v[128:131], v[116:119], v[92:95]
	ds_read_b128 v[160:163], v15
	v_mfma_f32_16x16x32_bf16 v[88:91], v[132:135], v[116:119], v[88:91]
	ds_read_b128 v[164:167], v15 offset:2048
	v_mfma_f32_16x16x32_bf16 v[84:87], v[136:139], v[116:119], v[84:87]
	ds_read_b128 v[224:227], v15 offset:4096
	v_mfma_f32_16x16x32_bf16 v[80:83], v[140:143], v[116:119], v[80:83]
	ds_read_b128 v[228:231], v15 offset:6144
	v_mfma_f32_16x16x32_bf16 v[76:79], v[128:131], v[120:123], v[76:79]
	v_mfma_f32_16x16x32_bf16 v[72:75], v[132:135], v[120:123], v[72:75]
	v_mfma_f32_16x16x32_bf16 v[68:71], v[136:139], v[120:123], v[68:71]
	v_mfma_f32_16x16x32_bf16 v[64:67], v[140:143], v[120:123], v[64:67]
	v_mfma_f32_16x16x32_bf16 v[60:63], v[128:131], v[124:127], v[60:63]
	v_mfma_f32_16x16x32_bf16 v[56:59], v[132:135], v[124:127], v[56:59]
	v_mfma_f32_16x16x32_bf16 v[52:55], v[136:139], v[124:127], v[52:55]
	v_mfma_f32_16x16x32_bf16 v[48:51], v[140:143], v[124:127], v[48:51]
	s_mov_b32 s5, s4
	s_add_u32 s4, s4, 0xc000
	s_sub_u32 vcc_lo, s4, 0x24000
	s_cselect_b32 s4, s4, vcc_lo
	s_waitcnt vmcnt(0) lgkmcnt(0)
	s_barrier
	v_add_u32_e32 v12, s4, v215
	v_add_u32_e32 v13, s4, v10
	v_add_u32_e32 v14, s4, v217
	v_add_u32_e32 v15, s4, v11
	v_mfma_f32_16x16x32_bf16 v[108:111], v[160:163], v[144:147], v[108:111]
	ds_read_b128 v[112:115], v12
	v_mfma_f32_16x16x32_bf16 v[104:107], v[164:167], v[144:147], v[104:107]
	ds_read_b128 v[116:119], v12 offset:2048
	v_mfma_f32_16x16x32_bf16 v[100:103], v[224:227], v[144:147], v[100:103]
	ds_read_b128 v[120:123], v12 offset:4096
	v_mfma_f32_16x16x32_bf16 v[96:99], v[228:231], v[144:147], v[96:99]
	ds_read_b128 v[124:127], v12 offset:6144
	v_mfma_f32_16x16x32_bf16 v[92:95], v[160:163], v[148:151], v[92:95]
	ds_read_b128 v[128:131], v13
	v_mfma_f32_16x16x32_bf16 v[88:91], v[164:167], v[148:151], v[88:91]
	ds_read_b128 v[132:135], v13 offset:2048
	v_mfma_f32_16x16x32_bf16 v[84:87], v[224:227], v[148:151], v[84:87]
	ds_read_b128 v[136:139], v13 offset:4096
	v_mfma_f32_16x16x32_bf16 v[80:83], v[228:231], v[148:151], v[80:83]
	ds_read_b128 v[140:143], v13 offset:6144
	v_mfma_f32_16x16x32_bf16 v[76:79], v[160:163], v[152:155], v[76:79]
	v_mfma_f32_16x16x32_bf16 v[72:75], v[164:167], v[152:155], v[72:75]
	v_mfma_f32_16x16x32_bf16 v[68:71], v[224:227], v[152:155], v[68:71]
	v_mfma_f32_16x16x32_bf16 v[64:67], v[228:231], v[152:155], v[64:67]
	v_mfma_f32_16x16x32_bf16 v[60:63], v[160:163], v[156:159], v[60:63]
	v_mfma_f32_16x16x32_bf16 v[56:59], v[164:167], v[156:159], v[56:59]
	v_mfma_f32_16x16x32_bf16 v[52:55], v[224:227], v[156:159], v[52:55]
	v_mfma_f32_16x16x32_bf16 v[48:51], v[228:231], v[156:159], v[48:51]
	s_waitcnt lgkmcnt(0)
	v_mfma_f32_16x16x32_bf16 v[108:111], v[128:131], v[112:115], v[108:111]
	ds_read_b128 v[144:147], v14
	v_mfma_f32_16x16x32_bf16 v[104:107], v[132:135], v[112:115], v[104:107]
	ds_read_b128 v[148:151], v14 offset:2048
	v_mfma_f32_16x16x32_bf16 v[100:103], v[136:139], v[112:115], v[100:103]
	ds_read_b128 v[152:155], v14 offset:4096
	v_mfma_f32_16x16x32_bf16 v[96:99], v[140:143], v[112:115], v[96:99]
	ds_read_b128 v[156:159], v14 offset:6144
	v_mfma_f32_16x16x32_bf16 v[92:95], v[128:131], v[116:119], v[92:95]
	ds_read_b128 v[160:163], v15
	v_mfma_f32_16x16x32_bf16 v[88:91], v[132:135], v[116:119], v[88:91]
	ds_read_b128 v[164:167], v15 offset:2048
	v_mfma_f32_16x16x32_bf16 v[84:87], v[136:139], v[116:119], v[84:87]
	ds_read_b128 v[224:227], v15 offset:4096
	v_mfma_f32_16x16x32_bf16 v[80:83], v[140:143], v[116:119], v[80:83]
	ds_read_b128 v[228:231], v15 offset:6144
	v_mfma_f32_16x16x32_bf16 v[76:79], v[128:131], v[120:123], v[76:79]
	v_mfma_f32_16x16x32_bf16 v[72:75], v[132:135], v[120:123], v[72:75]
	v_mfma_f32_16x16x32_bf16 v[68:71], v[136:139], v[120:123], v[68:71]
	v_mfma_f32_16x16x32_bf16 v[64:67], v[140:143], v[120:123], v[64:67]
	v_mfma_f32_16x16x32_bf16 v[60:63], v[128:131], v[124:127], v[60:63]
	v_mfma_f32_16x16x32_bf16 v[56:59], v[132:135], v[124:127], v[56:59]
	v_mfma_f32_16x16x32_bf16 v[52:55], v[136:139], v[124:127], v[52:55]
	v_mfma_f32_16x16x32_bf16 v[48:51], v[140:143], v[124:127], v[48:51]
	s_mov_b32 s5, s4
	s_add_u32 s4, s4, 0xc000
	s_sub_u32 vcc_lo, s4, 0x24000
	s_cselect_b32 s4, s4, vcc_lo
	s_waitcnt lgkmcnt(0)
	v_mfma_f32_16x16x32_bf16 v[108:111], v[160:163], v[144:147], v[108:111]
	v_mfma_f32_16x16x32_bf16 v[104:107], v[164:167], v[144:147], v[104:107]
	v_mfma_f32_16x16x32_bf16 v[100:103], v[224:227], v[144:147], v[100:103]
	v_mfma_f32_16x16x32_bf16 v[96:99], v[228:231], v[144:147], v[96:99]
	v_mfma_f32_16x16x32_bf16 v[92:95], v[160:163], v[148:151], v[92:95]
	v_mfma_f32_16x16x32_bf16 v[88:91], v[164:167], v[148:151], v[88:91]
	v_mfma_f32_16x16x32_bf16 v[84:87], v[224:227], v[148:151], v[84:87]
	v_mfma_f32_16x16x32_bf16 v[80:83], v[228:231], v[148:151], v[80:83]
	v_mfma_f32_16x16x32_bf16 v[76:79], v[160:163], v[152:155], v[76:79]
	v_mfma_f32_16x16x32_bf16 v[72:75], v[164:167], v[152:155], v[72:75]
	v_mfma_f32_16x16x32_bf16 v[68:71], v[224:227], v[152:155], v[68:71]
	v_mfma_f32_16x16x32_bf16 v[64:67], v[228:231], v[152:155], v[64:67]
	v_mfma_f32_16x16x32_bf16 v[60:63], v[160:163], v[156:159], v[60:63]
	v_mfma_f32_16x16x32_bf16 v[56:59], v[164:167], v[156:159], v[56:59]
	v_mfma_f32_16x16x32_bf16 v[52:55], v[224:227], v[156:159], v[52:55]
	v_mfma_f32_16x16x32_bf16 v[48:51], v[228:231], v[156:159], v[48:51]
	s_and_b64 vcc, exec, s[10:11]
	s_nop 7
	s_branch .LBB0_1487

.LBB0_1557:
	s_or_b64 exec, exec, s[0:1]
	v_readlane_b32 s0, v252, 21
	s_cmpk_gt_u32 s0, 0x1ff
	s_waitcnt lgkmcnt(0)
	s_barrier
	v_readlane_b32 s1, v252, 22
	s_cbranch_scc1 .LBB0_1577
	v_lshlrev_b32_e32 v0, 4, v170
	v_readlane_b32 s0, v251, 56
	v_and_b32_e32 v174, 0x70, v0
	v_mov_b32_e32 v175, 0
	v_readlane_b32 s1, v251, 57
	v_lshl_add_u64 v[0:1], s[76:77], 0, v[174:175]
	v_and_b32_e32 v3, 15, v170
	v_lshl_add_u64 v[176:177], s[0:1], 0, v[174:175]
	s_mov_b64 s[0:1], 0x2000000
	v_lshl_add_u64 v[178:179], v[0:1], 0, s[0:1]
	v_lshrrev_b32_e32 v0, 4, v170
	v_xor_b32_e32 v0, v0, v170
	v_ashrrev_i32_e32 v173, 3, v170
	v_bfe_u32 v4, v170, 6, 1
	v_ashrrev_i32_e32 v5, 7, v170
	v_lshlrev_b32_e32 v0, 4, v0
	v_lshlrev_b32_e32 v3, 7, v3
	v_bfe_u32 v2, v170, 4, 2
	v_lshlrev_b32_e32 v1, 7, v173
	v_and_b32_e32 v0, 0x70, v0
	v_readlane_b32 s0, v252, 29
	v_lshl_or_b32 v6, v5, 13, v3
	v_lshl_or_b32 v3, v4, 13, v3
	v_bfe_u32 v8, v170, 1, 3
	v_readlane_b32 s2, v252, 16
	v_add3_u32 v205, s0, v1, v0
	v_add_u32_e32 v7, s0, v3
	v_xor_b32_e32 v9, v2, v8
	v_bitop3_b32 v2, v2, v8, 4 bitop3:0x36
	v_readlane_b32 s0, v252, 30
	v_add3_u32 v204, 16, v1, v0
	v_lshlrev_b32_e32 v8, 4, v9
	v_lshlrev_b32_e32 v2, 4, v2
	v_add3_u32 v218, s0, v1, v0
	v_add_u32_e32 v0, s0, v3
	s_lshl_b32 s0, s2, 13
	v_readlane_b32 s1, v253, 24
	v_add_u32_e32 v6, 16, v6
	v_add_u32_e32 v219, v0, v8
	v_add_u32_e32 v220, v0, v2
	v_and_b32_e32 v0, 7, v170
	s_add_i32 s15, s0, s1
	s_lshl_b32 s0, s2, 11
	v_readlane_b32 s1, v253, 26
	v_and_b32_e32 v169, 63, v170
	s_lshl_b32 s14, s2, 6
	v_add_u32_e32 v214, v6, v8
	v_add_u32_e32 v215, v7, v8
	v_add_u32_e32 v216, v6, v2
	v_add_u32_e32 v217, v7, v2
	v_lshlrev_b32_e32 v221, 6, v5
	v_lshlrev_b32_e32 v222, 6, v4
	v_lshlrev_b32_e32 v170, 4, v0
	v_mov_b32_e32 v171, v175
	s_add_i32 s16, s0, s1
	s_mov_b64 s[8:9], 0
	s_mov_b64 s[0:1], 0x80080
	s_mov_b64 s[2:3], 0x80000
	s_mov_b64 s[4:5], 0x100
	s_mov_b32 s4, 0
	s_mov_b32 s5, 0x18000
	s_branch .LBB0_1560

.LBB0_1560:
	s_add_i32 s6, s62, s14
	s_lshl_b32 s7, s6, 5
	s_and_b32 s17, s7, 0x7fffff00
	s_lshl_b32 s6, s6, 7
	v_add_u32_e32 v48, s17, v173
	s_and_b32 s18, s6, 0x380
	v_ashrrev_i32_e32 v49, 31, v48
	v_add_u32_e32 v52, s18, v173
	v_ashrrev_i32_e32 v53, 31, v52
	v_lshlrev_b64 v[48:49], 13, v[48:49]
	v_lshl_add_u64 v[50:51], v[176:177], 0, v[48:49]
	v_lshlrev_b64 v[48:49], 13, v[52:53]
	v_lshl_add_u64 v[48:49], v[178:179], 0, v[48:49]
	v_writelane_b32 v250, s8, 4
	s_and_b64 vcc, exec, s[8:9]
	s_cbranch_vccnz .LBB0_1562
	v_add_co_u32_e32 v8, vcc, 0x80000, v50
	s_nop 1
	v_addc_co_u32_e32 v9, vcc, 0, v51, vcc
	v_add_co_u32_e32 v16, vcc, 0x100000, v50
	s_nop 1
	v_addc_co_u32_e32 v17, vcc, 0, v51, vcc
	v_add_co_u32_e32 v20, vcc, 0x180000, v50
	s_nop 1
	v_addc_co_u32_e32 v21, vcc, 0, v51, vcc
	v_add_co_u32_e32 v32, vcc, 0x80000, v48
	s_nop 1
	v_addc_co_u32_e32 v33, vcc, 0, v49, vcc
	s_nop 0
	s_nop 0
	s_nop 0
	s_nop 0
	s_nop 0
	s_nop 0
	s_nop 0
.LBB0_1562:
	s_and_b32 s6, s15, 0x380
	v_add_u32_e32 v52, s6, v173
	v_ashrrev_i32_e32 v53, 31, v52
	s_and_b32 s6, s16, 0x7fffff00
	s_add_i32 s62, s62, s51
	v_lshlrev_b64 v[52:53], 13, v[52:53]
	s_cmp_gt_u32 s62, 63
	v_lshl_add_u64 v[180:181], s[76:77], 0, v[52:53]
	v_add_u32_e32 v52, s6, v173
	s_cselect_b64 s[6:7], -1, 0
	s_add_i32 s12, s62, s14
	s_cmp_lt_u32 s62, 64
	s_cselect_b64 s[8:9], -1, 0
	s_and_b64 s[10:11], s[8:9], exec
	s_cselect_b32 s10, s12, 0
	s_lshl_b32 s98, s10, 5
	s_and_b32 s98, s98, 0x7fffff00
	s_lshl_b32 s100, s10, 7
	s_and_b32 s100, s100, 0x380
	s_lshl_b32 s98, s98, 13
	s_add_u32 s98, s76, s98
	s_addc_u32 s99, s77, 0
	s_add_u32 s98, s98, 0x4900000
	s_addc_u32 s99, s99, 0
	s_lshl_b32 s100, s100, 13
	s_add_u32 s100, s76, s100
	s_addc_u32 s101, s77, 0
	s_add_u32 s100, s100, 0x2000000
	s_addc_u32 s101, s101, 0
	v_writelane_b32 v250, s98, 0
	v_writelane_b32 v250, s99, 1
	v_writelane_b32 v250, s100, 2
	v_writelane_b32 v250, s101, 3
	s_lshl_b32 s11, s10, 5
	s_lshl_b32 s10, s10, 7
	s_and_b32 s10, s10, 0x380
	v_add_u32_e32 v54, s10, v173
	s_mov_b32 s10, 0x80000
	v_add_co_u32_e32 v12, vcc, s10, v50
	s_nop 0
	v_addc_co_u32_e32 v13, vcc, 0, v51, vcc
	v_add_co_u32_e32 v28, vcc, 0x100000, v50
	s_nop 0
	v_addc_co_u32_e32 v29, vcc, 0, v51, vcc
	v_add_co_u32_e32 v36, vcc, 0x180000, v50
	s_nop 0
	v_addc_co_u32_e32 v37, vcc, 0, v51, vcc
	v_add_co_u32_e32 v44, vcc, 0x80000, v48
	s_nop 0
	v_addc_co_u32_e32 v45, vcc, 0, v49, vcc
	v_ashrrev_i32_e32 v53, 31, v52
	v_lshlrev_b64 v[52:53], 13, v[52:53]
	s_and_b32 s11, s11, 0x7fffff00
	v_lshl_add_u64 v[182:183], s[76:77], 0, v[52:53]
	v_add_u32_e32 v52, s11, v173
	v_ashrrev_i32_e32 v53, 31, v52
	v_lshlrev_b64 v[52:53], 13, v[52:53]
	v_lshl_add_u64 v[184:185], v[176:177], 0, v[52:53]
	s_mov_b64 s[10:11], 0x100080
	v_ashrrev_i32_e32 v55, 31, v54
	v_lshl_add_u64 v[190:191], v[184:185], 0, s[10:11]
	s_mov_b64 s[10:11], 0x180080
	v_lshlrev_b64 v[52:53], 13, v[54:55]
	v_lshl_add_u64 v[192:193], v[184:185], 0, s[10:11]
	s_mov_b64 s[10:11], 0x100000
	v_lshl_add_u64 v[186:187], v[178:179], 0, v[52:53]
	v_lshl_add_u64 v[198:199], v[184:185], 0, s[10:11]
	s_mov_b64 s[10:11], 0x180000
	v_mov_b32_e32 v48, 0
	s_mov_b32 s19, 0
	v_lshl_add_u64 v[188:189], v[184:185], 0, s[0:1]
	v_lshl_add_u64 v[194:195], v[186:187], 0, s[0:1]
	v_lshl_add_u64 v[196:197], v[184:185], 0, s[2:3]
	v_lshl_add_u64 v[200:201], v[184:185], 0, s[10:11]
	v_lshl_add_u64 v[202:203], v[186:187], 0, s[2:3]
	v_mov_b32_e32 v49, v48
	v_mov_b32_e32 v50, v48
	v_mov_b32_e32 v51, v48
	v_mov_b32_e32 v52, v48
	v_mov_b32_e32 v53, v48
	v_mov_b32_e32 v54, v48
	v_mov_b32_e32 v55, v48
	v_mov_b32_e32 v56, v48
	v_mov_b32_e32 v57, v48
	v_mov_b32_e32 v58, v48
	v_mov_b32_e32 v59, v48
	v_mov_b32_e32 v60, v48
	v_mov_b32_e32 v61, v48
	v_mov_b32_e32 v62, v48
	v_mov_b32_e32 v63, v48
	v_mov_b32_e32 v64, v48
	v_mov_b32_e32 v65, v48
	v_mov_b32_e32 v66, v48
	v_mov_b32_e32 v67, v48
	v_mov_b32_e32 v68, v48
	v_mov_b32_e32 v69, v48
	v_mov_b32_e32 v70, v48
	v_mov_b32_e32 v71, v48
	v_mov_b32_e32 v72, v48
	v_mov_b32_e32 v73, v48
	v_mov_b32_e32 v74, v48
	v_mov_b32_e32 v75, v48
	v_mov_b32_e32 v76, v48
	v_mov_b32_e32 v77, v48
	v_mov_b32_e32 v78, v48
	v_mov_b32_e32 v79, v48
	v_mov_b32_e32 v80, v48
	v_mov_b32_e32 v81, v48
	v_mov_b32_e32 v82, v48
	v_mov_b32_e32 v83, v48
	v_mov_b32_e32 v84, v48
	v_mov_b32_e32 v85, v48
	v_mov_b32_e32 v86, v48
	v_mov_b32_e32 v87, v48
	v_mov_b32_e32 v88, v48
	v_mov_b32_e32 v89, v48
	v_mov_b32_e32 v90, v48
	v_mov_b32_e32 v91, v48
	v_mov_b32_e32 v92, v48
	v_mov_b32_e32 v93, v48
	v_mov_b32_e32 v94, v48
	v_mov_b32_e32 v95, v48
	v_mov_b32_e32 v96, v48
	v_mov_b32_e32 v97, v48
	v_mov_b32_e32 v98, v48
	v_mov_b32_e32 v99, v48
	v_mov_b32_e32 v100, v48
	v_mov_b32_e32 v101, v48
	v_mov_b32_e32 v102, v48
	v_mov_b32_e32 v103, v48
	v_mov_b32_e32 v104, v48
	v_mov_b32_e32 v105, v48
	v_mov_b32_e32 v106, v48
	v_mov_b32_e32 v107, v48
	v_mov_b32_e32 v108, v48
	v_mov_b32_e32 v109, v48
	v_mov_b32_e32 v110, v48
	v_mov_b32_e32 v111, v48
	v_lshrrev_b32_e32 v7, 1, v173
	v_lshrrev_b32_e32 v6, 4, v170
	v_xor_b32_e32 v7, v7, v6
	v_and_b32_e32 v7, 7, v7
	v_lshlrev_b32_e32 v7, 4, v7
	v_lshl_add_u32 v0, v173, 13, v7
	v_add_u32_e32 v1, 0x80000, v0
	v_add_u32_e32 v2, 0x100000, v0
	v_add_u32_e32 v3, 0x180000, v0
	v_mov_b32_e32 v4, v0
	v_add_u32_e32 v5, 0x80000, v4
	v_lshrrev_b32_e32 v6, 3, v173
	v_lshl_add_u32 v6, v6, 10, 16
	v_add_u32_e32 v10, 0xffff8000, v215
	v_add_u32_e32 v11, 0xffff8000, v217
	v_readlane_b32 vcc_hi, v250, 4
	s_lshl_b32 s98, s17, 13
	s_add_u32 s98, s76, s98
	s_addc_u32 s99, s77, 0
	s_add_u32 s98, s98, 0x4900000
	s_addc_u32 s99, s99, 0
	s_lshl_b32 s100, s18, 13
	s_add_u32 s100, s76, s100
	s_addc_u32 s101, s77, 0
	s_add_u32 s100, s100, 0x2000000
	s_addc_u32 s101, s101, 0
	s_cmp_lg_u32 vcc_hi, 0
	s_cbranch_scc1 .Lmyg_primed
	v_readfirstlane_b32 vcc_lo, v6
	s_nop 0
	s_add_u32 vcc_lo, vcc_lo, s4
	s_mov_b32 m0, vcc_lo
	s_nop 0
	global_load_lds_dwordx4 v0, s[98:99]
	s_add_u32 m0, m0, 0x2000
	s_nop 0
	global_load_lds_dwordx4 v1, s[98:99]
	s_add_u32 m0, m0, 0x2000
	s_nop 0
	global_load_lds_dwordx4 v2, s[98:99]
	s_add_u32 m0, m0, 0x2000
	s_nop 0
	global_load_lds_dwordx4 v3, s[98:99]
	s_add_u32 m0, vcc_lo, 0x8000
	s_nop 0
	global_load_lds_dwordx4 v4, s[100:101]
	s_add_u32 m0, m0, 0x2000
	s_nop 0
	global_load_lds_dwordx4 v5, s[100:101]
	s_add_u32 s98, s98, 0x80
	s_addc_u32 s99, s99, 0
	s_add_u32 s100, s100, 0x80
	s_addc_u32 s101, s101, 0
	s_add_u32 vcc_hi, s4, 0xc000
	s_sub_u32 vcc_lo, vcc_hi, 0x24000
	s_cselect_b32 vcc_hi, vcc_hi, vcc_lo
	v_readfirstlane_b32 vcc_lo, v6
	s_nop 0
	s_add_u32 vcc_lo, vcc_lo, vcc_hi
	s_mov_b32 m0, vcc_lo
	s_nop 0
	global_load_lds_dwordx4 v0, s[98:99]
	s_add_u32 m0, m0, 0x2000
	s_nop 0
	global_load_lds_dwordx4 v1, s[98:99]
	s_add_u32 m0, m0, 0x2000
	s_nop 0
	global_load_lds_dwordx4 v2, s[98:99]
	s_add_u32 m0, m0, 0x2000
	s_nop 0
	global_load_lds_dwordx4 v3, s[98:99]
	s_add_u32 m0, vcc_lo, 0x8000
	s_nop 0
	global_load_lds_dwordx4 v4, s[100:101]
	s_add_u32 m0, m0, 0x2000
	s_nop 0
	global_load_lds_dwordx4 v5, s[100:101]
	s_add_u32 s98, s98, 0x80
	s_addc_u32 s99, s99, 0
	s_add_u32 s100, s100, 0x80
	s_addc_u32 s101, s101, 0
	s_branch .LBB0_1564

.LBB0_1564:
	s_waitcnt vmcnt(6) lgkmcnt(0)
	s_barrier
	v_add_u32_e32 v12, s4, v214
	v_add_u32_e32 v13, s4, v10
	v_add_u32_e32 v14, s4, v216
	v_add_u32_e32 v15, s4, v11
	v_readfirstlane_b32 vcc_lo, v6
	s_nop 0
	s_add_u32 vcc_lo, vcc_lo, s5
	ds_read_b128 v[112:115], v12
	ds_read_b128 v[116:119], v12 offset:2048
	ds_read_b128 v[120:123], v12 offset:4096
	ds_read_b128 v[124:127], v12 offset:6144
	ds_read_b128 v[128:131], v13
	ds_read_b128 v[132:135], v13 offset:2048
	ds_read_b128 v[136:139], v13 offset:4096
	ds_read_b128 v[140:143], v13 offset:6144
	s_mov_b32 m0, vcc_lo
	s_nop 0
	global_load_lds_dwordx4 v0, s[98:99]
	s_add_u32 m0, m0, 0x2000
	s_nop 0
	global_load_lds_dwordx4 v1, s[98:99]
	s_add_u32 m0, m0, 0x2000
	s_nop 0
	global_load_lds_dwordx4 v2, s[98:99]
	s_add_u32 m0, m0, 0x2000
	s_nop 0
	global_load_lds_dwordx4 v3, s[98:99]
	s_add_u32 m0, vcc_lo, 0x8000
	s_nop 0
	global_load_lds_dwordx4 v4, s[100:101]
	s_add_u32 m0, m0, 0x2000
	s_nop 0
	global_load_lds_dwordx4 v5, s[100:101]
	s_add_u32 s98, s98, 0x80
	s_addc_u32 s99, s99, 0
	s_add_u32 s100, s100, 0x80
	s_addc_u32 s101, s101, 0
	s_waitcnt lgkmcnt(0)
	v_mfma_f32_16x16x32_bf16 v[108:111], v[112:115], v[128:131], v[108:111]
	ds_read_b128 v[144:147], v14
	v_mfma_f32_16x16x32_bf16 v[104:107], v[112:115], v[132:135], v[104:107]
	ds_read_b128 v[148:151], v14 offset:2048
	v_mfma_f32_16x16x32_bf16 v[100:103], v[112:115], v[136:139], v[100:103]
	ds_read_b128 v[152:155], v14 offset:4096
	v_mfma_f32_16x16x32_bf16 v[96:99], v[112:115], v[140:143], v[96:99]
	ds_read_b128 v[156:159], v14 offset:6144
	v_mfma_f32_16x16x32_bf16 v[92:95], v[116:119], v[128:131], v[92:95]
	ds_read_b128 v[160:163], v15
	v_mfma_f32_16x16x32_bf16 v[88:91], v[116:119], v[132:135], v[88:91]
	ds_read_b128 v[164:167], v15 offset:2048
	v_mfma_f32_16x16x32_bf16 v[84:87], v[116:119], v[136:139], v[84:87]
	ds_read_b128 v[224:227], v15 offset:4096
	v_mfma_f32_16x16x32_bf16 v[80:83], v[116:119], v[140:143], v[80:83]
	ds_read_b128 v[228:231], v15 offset:6144
	v_mfma_f32_16x16x32_bf16 v[76:79], v[120:123], v[128:131], v[76:79]
	v_mfma_f32_16x16x32_bf16 v[72:75], v[120:123], v[132:135], v[72:75]
	v_mfma_f32_16x16x32_bf16 v[68:71], v[120:123], v[136:139], v[68:71]
	v_mfma_f32_16x16x32_bf16 v[64:67], v[120:123], v[140:143], v[64:67]
	v_mfma_f32_16x16x32_bf16 v[60:63], v[124:127], v[128:131], v[60:63]
	v_mfma_f32_16x16x32_bf16 v[56:59], v[124:127], v[132:135], v[56:59]
	v_mfma_f32_16x16x32_bf16 v[52:55], v[124:127], v[136:139], v[52:55]
	v_mfma_f32_16x16x32_bf16 v[48:51], v[124:127], v[140:143], v[48:51]
	s_mov_b32 s5, s4
	s_add_u32 s4, s4, 0xc000
	s_sub_u32 vcc_lo, s4, 0x24000
	s_cselect_b32 s4, s4, vcc_lo
	s_mov_b32 s19, 1
.Lmyg_steady:
	s_waitcnt vmcnt(6) lgkmcnt(0)
	s_barrier
	v_add_u32_e32 v12, s4, v214
	v_add_u32_e32 v13, s4, v10
	v_add_u32_e32 v14, s4, v216
	v_add_u32_e32 v15, s4, v11
	v_readfirstlane_b32 vcc_lo, v6
	s_nop 0
	s_add_u32 vcc_lo, vcc_lo, s5
	s_mov_b32 m0, vcc_lo
	v_mfma_f32_16x16x32_bf16 v[108:111], v[144:147], v[160:163], v[108:111]
	ds_read_b128 v[112:115], v12
	global_load_lds_dwordx4 v0, s[98:99]
	s_add_u32 m0, m0, 0x2000
	v_mfma_f32_16x16x32_bf16 v[104:107], v[144:147], v[164:167], v[104:107]
	ds_read_b128 v[116:119], v12 offset:2048
	global_load_lds_dwordx4 v1, s[98:99]
	s_add_u32 m0, m0, 0x2000
	v_mfma_f32_16x16x32_bf16 v[100:103], v[144:147], v[224:227], v[100:103]
	ds_read_b128 v[120:123], v12 offset:4096
	global_load_lds_dwordx4 v2, s[98:99]
	s_add_u32 m0, m0, 0x2000
	v_mfma_f32_16x16x32_bf16 v[96:99], v[144:147], v[228:231], v[96:99]
	ds_read_b128 v[124:127], v12 offset:6144
	global_load_lds_dwordx4 v3, s[98:99]
	s_add_u32 m0, vcc_lo, 0x8000
	v_mfma_f32_16x16x32_bf16 v[92:95], v[148:151], v[160:163], v[92:95]
	ds_read_b128 v[128:131], v13
	global_load_lds_dwordx4 v4, s[100:101]
	s_add_u32 m0, m0, 0x2000
	v_mfma_f32_16x16x32_bf16 v[88:91], v[148:151], v[164:167], v[88:91]
	ds_read_b128 v[132:135], v13 offset:2048
	global_load_lds_dwordx4 v5, s[100:101]
	v_mfma_f32_16x16x32_bf16 v[84:87], v[148:151], v[224:227], v[84:87]
	ds_read_b128 v[136:139], v13 offset:4096
	s_add_u32 s98, s98, 0x80
	s_addc_u32 s99, s99, 0
	s_add_u32 s100, s100, 0x80
	s_addc_u32 s101, s101, 0
	v_mfma_f32_16x16x32_bf16 v[80:83], v[148:151], v[228:231], v[80:83]
	ds_read_b128 v[140:143], v13 offset:6144
	v_mfma_f32_16x16x32_bf16 v[76:79], v[152:155], v[160:163], v[76:79]
	v_mfma_f32_16x16x32_bf16 v[72:75], v[152:155], v[164:167], v[72:75]
	v_mfma_f32_16x16x32_bf16 v[68:71], v[152:155], v[224:227], v[68:71]
	v_mfma_f32_16x16x32_bf16 v[64:67], v[152:155], v[228:231], v[64:67]
	v_mfma_f32_16x16x32_bf16 v[60:63], v[156:159], v[160:163], v[60:63]
	v_mfma_f32_16x16x32_bf16 v[56:59], v[156:159], v[164:167], v[56:59]
	v_mfma_f32_16x16x32_bf16 v[52:55], v[156:159], v[224:227], v[52:55]
	v_mfma_f32_16x16x32_bf16 v[48:51], v[156:159], v[228:231], v[48:51]
	s_waitcnt lgkmcnt(0)
	v_mfma_f32_16x16x32_bf16 v[108:111], v[112:115], v[128:131], v[108:111]
	ds_read_b128 v[144:147], v14
	v_mfma_f32_16x16x32_bf16 v[104:107], v[112:115], v[132:135], v[104:107]
	ds_read_b128 v[148:151], v14 offset:2048
	v_mfma_f32_16x16x32_bf16 v[100:103], v[112:115], v[136:139], v[100:103]
	ds_read_b128 v[152:155], v14 offset:4096
	v_mfma_f32_16x16x32_bf16 v[96:99], v[112:115], v[140:143], v[96:99]
	ds_read_b128 v[156:159], v14 offset:6144
	v_mfma_f32_16x16x32_bf16 v[92:95], v[116:119], v[128:131], v[92:95]
	ds_read_b128 v[160:163], v15
	v_mfma_f32_16x16x32_bf16 v[88:91], v[116:119], v[132:135], v[88:91]
	ds_read_b128 v[164:167], v15 offset:2048
	v_mfma_f32_16x16x32_bf16 v[84:87], v[116:119], v[136:139], v[84:87]
	ds_read_b128 v[224:227], v15 offset:4096
	v_mfma_f32_16x16x32_bf16 v[80:83], v[116:119], v[140:143], v[80:83]
	ds_read_b128 v[228:231], v15 offset:6144
	v_mfma_f32_16x16x32_bf16 v[76:79], v[120:123], v[128:131], v[76:79]
	v_mfma_f32_16x16x32_bf16 v[72:75], v[120:123], v[132:135], v[72:75]
	v_mfma_f32_16x16x32_bf16 v[68:71], v[120:123], v[136:139], v[68:71]
	v_mfma_f32_16x16x32_bf16 v[64:67], v[120:123], v[140:143], v[64:67]
	v_mfma_f32_16x16x32_bf16 v[60:63], v[124:127], v[128:131], v[60:63]
	v_mfma_f32_16x16x32_bf16 v[56:59], v[124:127], v[132:135], v[56:59]
	v_mfma_f32_16x16x32_bf16 v[52:55], v[124:127], v[136:139], v[52:55]
	v_mfma_f32_16x16x32_bf16 v[48:51], v[124:127], v[140:143], v[48:51]
	s_mov_b32 s5, s4
	s_add_u32 s4, s4, 0xc000
	s_sub_u32 vcc_lo, s4, 0x24000
	s_cselect_b32 s4, s4, vcc_lo
	s_add_i32 s19, s19, 1
	s_cmp_lt_u32 s19, 62
	s_cbranch_scc1 .Lmyg_steady
	s_andn2_b64 vcc, exec, s[8:9]
	s_cbranch_vccnz .Lmyg_prelast_n
	v_readlane_b32 s98, v250, 0
	v_readlane_b32 s99, v250, 1
	v_readlane_b32 s100, v250, 2
	v_readlane_b32 s101, v250, 3
	s_waitcnt vmcnt(6) lgkmcnt(0)
	s_barrier
	v_add_u32_e32 v12, s4, v214
	v_add_u32_e32 v13, s4, v10
	v_add_u32_e32 v14, s4, v216
	v_add_u32_e32 v15, s4, v11
	v_readfirstlane_b32 vcc_lo, v6
	s_nop 0
	s_add_u32 vcc_lo, vcc_lo, s5
	s_mov_b32 m0, vcc_lo
	v_mfma_f32_16x16x32_bf16 v[108:111], v[144:147], v[160:163], v[108:111]
	ds_read_b128 v[112:115], v12
	global_load_lds_dwordx4 v0, s[98:99]
	s_add_u32 m0, m0, 0x2000
	v_mfma_f32_16x16x32_bf16 v[104:107], v[144:147], v[164:167], v[104:107]
	ds_read_b128 v[116:119], v12 offset:2048
	global_load_lds_dwordx4 v1, s[98:99]
	s_add_u32 m0, m0, 0x2000
	v_mfma_f32_16x16x32_bf16 v[100:103], v[144:147], v[224:227], v[100:103]
	ds_read_b128 v[120:123], v12 offset:4096
	global_load_lds_dwordx4 v2, s[98:99]
	s_add_u32 m0, m0, 0x2000
	v_mfma_f32_16x16x32_bf16 v[96:99], v[144:147], v[228:231], v[96:99]
	ds_read_b128 v[124:127], v12 offset:6144
	global_load_lds_dwordx4 v3, s[98:99]
	s_add_u32 m0, vcc_lo, 0x8000
	v_mfma_f32_16x16x32_bf16 v[92:95], v[148:151], v[160:163], v[92:95]
	ds_read_b128 v[128:131], v13
	global_load_lds_dwordx4 v4, s[100:101]
	s_add_u32 m0, m0, 0x2000
	v_mfma_f32_16x16x32_bf16 v[88:91], v[148:151], v[164:167], v[88:91]
	ds_read_b128 v[132:135], v13 offset:2048
	global_load_lds_dwordx4 v5, s[100:101]
	v_mfma_f32_16x16x32_bf16 v[84:87], v[148:151], v[224:227], v[84:87]
	ds_read_b128 v[136:139], v13 offset:4096
	s_add_u32 s98, s98, 0x80
	s_addc_u32 s99, s99, 0
	s_add_u32 s100, s100, 0x80
	s_addc_u32 s101, s101, 0
	v_mfma_f32_16x16x32_bf16 v[80:83], v[148:151], v[228:231], v[80:83]
	ds_read_b128 v[140:143], v13 offset:6144
	v_mfma_f32_16x16x32_bf16 v[76:79], v[152:155], v[160:163], v[76:79]
	v_mfma_f32_16x16x32_bf16 v[72:75], v[152:155], v[164:167], v[72:75]
	v_mfma_f32_16x16x32_bf16 v[68:71], v[152:155], v[224:227], v[68:71]
	v_mfma_f32_16x16x32_bf16 v[64:67], v[152:155], v[228:231], v[64:67]
	v_mfma_f32_16x16x32_bf16 v[60:63], v[156:159], v[160:163], v[60:63]
	v_mfma_f32_16x16x32_bf16 v[56:59], v[156:159], v[164:167], v[56:59]
	v_mfma_f32_16x16x32_bf16 v[52:55], v[156:159], v[224:227], v[52:55]
	v_mfma_f32_16x16x32_bf16 v[48:51], v[156:159], v[228:231], v[48:51]
	s_waitcnt lgkmcnt(0)
	v_mfma_f32_16x16x32_bf16 v[108:111], v[112:115], v[128:131], v[108:111]
	ds_read_b128 v[144:147], v14
	v_mfma_f32_16x16x32_bf16 v[104:107], v[112:115], v[132:135], v[104:107]
	ds_read_b128 v[148:151], v14 offset:2048
	v_mfma_f32_16x16x32_bf16 v[100:103], v[112:115], v[136:139], v[100:103]
	ds_read_b128 v[152:155], v14 offset:4096
	v_mfma_f32_16x16x32_bf16 v[96:99], v[112:115], v[140:143], v[96:99]
	ds_read_b128 v[156:159], v14 offset:6144
	v_mfma_f32_16x16x32_bf16 v[92:95], v[116:119], v[128:131], v[92:95]
	ds_read_b128 v[160:163], v15
	v_mfma_f32_16x16x32_bf16 v[88:91], v[116:119], v[132:135], v[88:91]
	ds_read_b128 v[164:167], v15 offset:2048
	v_mfma_f32_16x16x32_bf16 v[84:87], v[116:119], v[136:139], v[84:87]
	ds_read_b128 v[224:227], v15 offset:4096
	v_mfma_f32_16x16x32_bf16 v[80:83], v[116:119], v[140:143], v[80:83]
	ds_read_b128 v[228:231], v15 offset:6144
	v_mfma_f32_16x16x32_bf16 v[76:79], v[120:123], v[128:131], v[76:79]
	v_mfma_f32_16x16x32_bf16 v[72:75], v[120:123], v[132:135], v[72:75]
	v_mfma_f32_16x16x32_bf16 v[68:71], v[120:123], v[136:139], v[68:71]
	v_mfma_f32_16x16x32_bf16 v[64:67], v[120:123], v[140:143], v[64:67]
	v_mfma_f32_16x16x32_bf16 v[60:63], v[124:127], v[128:131], v[60:63]
	v_mfma_f32_16x16x32_bf16 v[56:59], v[124:127], v[132:135], v[56:59]
	v_mfma_f32_16x16x32_bf16 v[52:55], v[124:127], v[136:139], v[52:55]
	v_mfma_f32_16x16x32_bf16 v[48:51], v[124:127], v[140:143], v[48:51]
	s_mov_b32 s5, s4
	s_add_u32 s4, s4, 0xc000
	s_sub_u32 vcc_lo, s4, 0x24000
	s_cselect_b32 s4, s4, vcc_lo
	s_waitcnt vmcnt(6) lgkmcnt(0)
	s_barrier
	v_add_u32_e32 v12, s4, v214
	v_add_u32_e32 v13, s4, v10
	v_add_u32_e32 v14, s4, v216
	v_add_u32_e32 v15, s4, v11
	v_readfirstlane_b32 vcc_lo, v6
	s_nop 0
	s_add_u32 vcc_lo, vcc_lo, s5
	s_mov_b32 m0, vcc_lo
	v_mfma_f32_16x16x32_bf16 v[108:111], v[144:147], v[160:163], v[108:111]
	ds_read_b128 v[112:115], v12
	global_load_lds_dwordx4 v0, s[98:99]
	s_add_u32 m0, m0, 0x2000
	v_mfma_f32_16x16x32_bf16 v[104:107], v[144:147], v[164:167], v[104:107]
	ds_read_b128 v[116:119], v12 offset:2048
	global_load_lds_dwordx4 v1, s[98:99]
	s_add_u32 m0, m0, 0x2000
	v_mfma_f32_16x16x32_bf16 v[100:103], v[144:147], v[224:227], v[100:103]
	ds_read_b128 v[120:123], v12 offset:4096
	global_load_lds_dwordx4 v2, s[98:99]
	s_add_u32 m0, m0, 0x2000
	v_mfma_f32_16x16x32_bf16 v[96:99], v[144:147], v[228:231], v[96:99]
	ds_read_b128 v[124:127], v12 offset:6144
	global_load_lds_dwordx4 v3, s[98:99]
	s_add_u32 m0, vcc_lo, 0x8000
	v_mfma_f32_16x16x32_bf16 v[92:95], v[148:151], v[160:163], v[92:95]
	ds_read_b128 v[128:131], v13
	global_load_lds_dwordx4 v4, s[100:101]
	s_add_u32 m0, m0, 0x2000
	v_mfma_f32_16x16x32_bf16 v[88:91], v[148:151], v[164:167], v[88:91]
	ds_read_b128 v[132:135], v13 offset:2048
	global_load_lds_dwordx4 v5, s[100:101]
	v_mfma_f32_16x16x32_bf16 v[84:87], v[148:151], v[224:227], v[84:87]
	ds_read_b128 v[136:139], v13 offset:4096
	s_add_u32 s98, s98, 0x80
	s_addc_u32 s99, s99, 0
	s_add_u32 s100, s100, 0x80
	s_addc_u32 s101, s101, 0
	v_mfma_f32_16x16x32_bf16 v[80:83], v[148:151], v[228:231], v[80:83]
	ds_read_b128 v[140:143], v13 offset:6144
	v_mfma_f32_16x16x32_bf16 v[76:79], v[152:155], v[160:163], v[76:79]
	v_mfma_f32_16x16x32_bf16 v[72:75], v[152:155], v[164:167], v[72:75]
	v_mfma_f32_16x16x32_bf16 v[68:71], v[152:155], v[224:227], v[68:71]
	v_mfma_f32_16x16x32_bf16 v[64:67], v[152:155], v[228:231], v[64:67]
	v_mfma_f32_16x16x32_bf16 v[60:63], v[156:159], v[160:163], v[60:63]
	v_mfma_f32_16x16x32_bf16 v[56:59], v[156:159], v[164:167], v[56:59]
	v_mfma_f32_16x16x32_bf16 v[52:55], v[156:159], v[224:227], v[52:55]
	v_mfma_f32_16x16x32_bf16 v[48:51], v[156:159], v[228:231], v[48:51]
	s_waitcnt lgkmcnt(0)
	v_mfma_f32_16x16x32_bf16 v[108:111], v[112:115], v[128:131], v[108:111]
	ds_read_b128 v[144:147], v14
	v_mfma_f32_16x16x32_bf16 v[104:107], v[112:115], v[132:135], v[104:107]
	ds_read_b128 v[148:151], v14 offset:2048
	v_mfma_f32_16x16x32_bf16 v[100:103], v[112:115], v[136:139], v[100:103]
	ds_read_b128 v[152:155], v14 offset:4096
	v_mfma_f32_16x16x32_bf16 v[96:99], v[112:115], v[140:143], v[96:99]
	ds_read_b128 v[156:159], v14 offset:6144
	v_mfma_f32_16x16x32_bf16 v[92:95], v[116:119], v[128:131], v[92:95]
	ds_read_b128 v[160:163], v15
	v_mfma_f32_16x16x32_bf16 v[88:91], v[116:119], v[132:135], v[88:91]
	ds_read_b128 v[164:167], v15 offset:2048
	v_mfma_f32_16x16x32_bf16 v[84:87], v[116:119], v[136:139], v[84:87]
	ds_read_b128 v[224:227], v15 offset:4096
	v_mfma_f32_16x16x32_bf16 v[80:83], v[116:119], v[140:143], v[80:83]
	ds_read_b128 v[228:231], v15 offset:6144
	v_mfma_f32_16x16x32_bf16 v[76:79], v[120:123], v[128:131], v[76:79]
	v_mfma_f32_16x16x32_bf16 v[72:75], v[120:123], v[132:135], v[72:75]
	v_mfma_f32_16x16x32_bf16 v[68:71], v[120:123], v[136:139], v[68:71]
	v_mfma_f32_16x16x32_bf16 v[64:67], v[120:123], v[140:143], v[64:67]
	v_mfma_f32_16x16x32_bf16 v[60:63], v[124:127], v[128:131], v[60:63]
	v_mfma_f32_16x16x32_bf16 v[56:59], v[124:127], v[132:135], v[56:59]
	v_mfma_f32_16x16x32_bf16 v[52:55], v[124:127], v[136:139], v[52:55]
	v_mfma_f32_16x16x32_bf16 v[48:51], v[124:127], v[140:143], v[48:51]
	s_mov_b32 s5, s4
	s_add_u32 s4, s4, 0xc000
	s_sub_u32 vcc_lo, s4, 0x24000
	s_cselect_b32 s4, s4, vcc_lo
	s_waitcnt lgkmcnt(0)
	v_mfma_f32_16x16x32_bf16 v[108:111], v[144:147], v[160:163], v[108:111]
	v_mfma_f32_16x16x32_bf16 v[104:107], v[144:147], v[164:167], v[104:107]
	v_mfma_f32_16x16x32_bf16 v[100:103], v[144:147], v[224:227], v[100:103]
	v_mfma_f32_16x16x32_bf16 v[96:99], v[144:147], v[228:231], v[96:99]
	v_mfma_f32_16x16x32_bf16 v[92:95], v[148:151], v[160:163], v[92:95]
	v_mfma_f32_16x16x32_bf16 v[88:91], v[148:151], v[164:167], v[88:91]
	v_mfma_f32_16x16x32_bf16 v[84:87], v[148:151], v[224:227], v[84:87]
	v_mfma_f32_16x16x32_bf16 v[80:83], v[148:151], v[228:231], v[80:83]
	v_mfma_f32_16x16x32_bf16 v[76:79], v[152:155], v[160:163], v[76:79]
	v_mfma_f32_16x16x32_bf16 v[72:75], v[152:155], v[164:167], v[72:75]
	v_mfma_f32_16x16x32_bf16 v[68:71], v[152:155], v[224:227], v[68:71]
	v_mfma_f32_16x16x32_bf16 v[64:67], v[152:155], v[228:231], v[64:67]
	v_mfma_f32_16x16x32_bf16 v[60:63], v[156:159], v[160:163], v[60:63]
	v_mfma_f32_16x16x32_bf16 v[56:59], v[156:159], v[164:167], v[56:59]
	v_mfma_f32_16x16x32_bf16 v[52:55], v[156:159], v[224:227], v[52:55]
	v_mfma_f32_16x16x32_bf16 v[48:51], v[156:159], v[228:231], v[48:51]
	s_and_b64 vcc, exec, s[10:11]
	s_nop 7
	s_branch .LBB0_1559
.Lmyg_prelast_n:
	s_waitcnt vmcnt(6) lgkmcnt(0)
	s_barrier
	v_add_u32_e32 v12, s4, v214
	v_add_u32_e32 v13, s4, v10
	v_add_u32_e32 v14, s4, v216
	v_add_u32_e32 v15, s4, v11
	v_mfma_f32_16x16x32_bf16 v[108:111], v[144:147], v[160:163], v[108:111]
	ds_read_b128 v[112:115], v12
	v_mfma_f32_16x16x32_bf16 v[104:107], v[144:147], v[164:167], v[104:107]
	ds_read_b128 v[116:119], v12 offset:2048
	v_mfma_f32_16x16x32_bf16 v[100:103], v[144:147], v[224:227], v[100:103]
	ds_read_b128 v[120:123], v12 offset:4096
	v_mfma_f32_16x16x32_bf16 v[96:99], v[144:147], v[228:231], v[96:99]
	ds_read_b128 v[124:127], v12 offset:6144
	v_mfma_f32_16x16x32_bf16 v[92:95], v[148:151], v[160:163], v[92:95]
	ds_read_b128 v[128:131], v13
	v_mfma_f32_16x16x32_bf16 v[88:91], v[148:151], v[164:167], v[88:91]
	ds_read_b128 v[132:135], v13 offset:2048
	v_mfma_f32_16x16x32_bf16 v[84:87], v[148:151], v[224:227], v[84:87]
	ds_read_b128 v[136:139], v13 offset:4096
	v_mfma_f32_16x16x32_bf16 v[80:83], v[148:151], v[228:231], v[80:83]
	ds_read_b128 v[140:143], v13 offset:6144
	v_mfma_f32_16x16x32_bf16 v[76:79], v[152:155], v[160:163], v[76:79]
	v_mfma_f32_16x16x32_bf16 v[72:75], v[152:155], v[164:167], v[72:75]
	v_mfma_f32_16x16x32_bf16 v[68:71], v[152:155], v[224:227], v[68:71]
	v_mfma_f32_16x16x32_bf16 v[64:67], v[152:155], v[228:231], v[64:67]
	v_mfma_f32_16x16x32_bf16 v[60:63], v[156:159], v[160:163], v[60:63]
	v_mfma_f32_16x16x32_bf16 v[56:59], v[156:159], v[164:167], v[56:59]
	v_mfma_f32_16x16x32_bf16 v[52:55], v[156:159], v[224:227], v[52:55]
	v_mfma_f32_16x16x32_bf16 v[48:51], v[156:159], v[228:231], v[48:51]
	s_waitcnt lgkmcnt(0)
	v_mfma_f32_16x16x32_bf16 v[108:111], v[112:115], v[128:131], v[108:111]
	ds_read_b128 v[144:147], v14
	v_mfma_f32_16x16x32_bf16 v[104:107], v[112:115], v[132:135], v[104:107]
	ds_read_b128 v[148:151], v14 offset:2048
	v_mfma_f32_16x16x32_bf16 v[100:103], v[112:115], v[136:139], v[100:103]
	ds_read_b128 v[152:155], v14 offset:4096
	v_mfma_f32_16x16x32_bf16 v[96:99], v[112:115], v[140:143], v[96:99]
	ds_read_b128 v[156:159], v14 offset:6144
	v_mfma_f32_16x16x32_bf16 v[92:95], v[116:119], v[128:131], v[92:95]
	ds_read_b128 v[160:163], v15
	v_mfma_f32_16x16x32_bf16 v[88:91], v[116:119], v[132:135], v[88:91]
	ds_read_b128 v[164:167], v15 offset:2048
	v_mfma_f32_16x16x32_bf16 v[84:87], v[116:119], v[136:139], v[84:87]
	ds_read_b128 v[224:227], v15 offset:4096
	v_mfma_f32_16x16x32_bf16 v[80:83], v[116:119], v[140:143], v[80:83]
	ds_read_b128 v[228:231], v15 offset:6144
	v_mfma_f32_16x16x32_bf16 v[76:79], v[120:123], v[128:131], v[76:79]
	v_mfma_f32_16x16x32_bf16 v[72:75], v[120:123], v[132:135], v[72:75]
	v_mfma_f32_16x16x32_bf16 v[68:71], v[120:123], v[136:139], v[68:71]
	v_mfma_f32_16x16x32_bf16 v[64:67], v[120:123], v[140:143], v[64:67]
	v_mfma_f32_16x16x32_bf16 v[60:63], v[124:127], v[128:131], v[60:63]
	v_mfma_f32_16x16x32_bf16 v[56:59], v[124:127], v[132:135], v[56:59]
	v_mfma_f32_16x16x32_bf16 v[52:55], v[124:127], v[136:139], v[52:55]
	v_mfma_f32_16x16x32_bf16 v[48:51], v[124:127], v[140:143], v[48:51]
	s_mov_b32 s5, s4
	s_add_u32 s4, s4, 0xc000
	s_sub_u32 vcc_lo, s4, 0x24000
	s_cselect_b32 s4, s4, vcc_lo
	s_waitcnt vmcnt(0) lgkmcnt(0)
	s_barrier
	v_add_u32_e32 v12, s4, v214
	v_add_u32_e32 v13, s4, v10
	v_add_u32_e32 v14, s4, v216
	v_add_u32_e32 v15, s4, v11
	v_mfma_f32_16x16x32_bf16 v[108:111], v[144:147], v[160:163], v[108:111]
	ds_read_b128 v[112:115], v12
	v_mfma_f32_16x16x32_bf16 v[104:107], v[144:147], v[164:167], v[104:107]
	ds_read_b128 v[116:119], v12 offset:2048
	v_mfma_f32_16x16x32_bf16 v[100:103], v[144:147], v[224:227], v[100:103]
	ds_read_b128 v[120:123], v12 offset:4096
	v_mfma_f32_16x16x32_bf16 v[96:99], v[144:147], v[228:231], v[96:99]
	ds_read_b128 v[124:127], v12 offset:6144
	v_mfma_f32_16x16x32_bf16 v[92:95], v[148:151], v[160:163], v[92:95]
	ds_read_b128 v[128:131], v13
	v_mfma_f32_16x16x32_bf16 v[88:91], v[148:151], v[164:167], v[88:91]
	ds_read_b128 v[132:135], v13 offset:2048
	v_mfma_f32_16x16x32_bf16 v[84:87], v[148:151], v[224:227], v[84:87]
	ds_read_b128 v[136:139], v13 offset:4096
	v_mfma_f32_16x16x32_bf16 v[80:83], v[148:151], v[228:231], v[80:83]
	ds_read_b128 v[140:143], v13 offset:6144
	v_mfma_f32_16x16x32_bf16 v[76:79], v[152:155], v[160:163], v[76:79]
	v_mfma_f32_16x16x32_bf16 v[72:75], v[152:155], v[164:167], v[72:75]
	v_mfma_f32_16x16x32_bf16 v[68:71], v[152:155], v[224:227], v[68:71]
	v_mfma_f32_16x16x32_bf16 v[64:67], v[152:155], v[228:231], v[64:67]
	v_mfma_f32_16x16x32_bf16 v[60:63], v[156:159], v[160:163], v[60:63]
	v_mfma_f32_16x16x32_bf16 v[56:59], v[156:159], v[164:167], v[56:59]
	v_mfma_f32_16x16x32_bf16 v[52:55], v[156:159], v[224:227], v[52:55]
	v_mfma_f32_16x16x32_bf16 v[48:51], v[156:159], v[228:231], v[48:51]
	s_waitcnt lgkmcnt(0)
	v_mfma_f32_16x16x32_bf16 v[108:111], v[112:115], v[128:131], v[108:111]
	ds_read_b128 v[144:147], v14
	v_mfma_f32_16x16x32_bf16 v[104:107], v[112:115], v[132:135], v[104:107]
	ds_read_b128 v[148:151], v14 offset:2048
	v_mfma_f32_16x16x32_bf16 v[100:103], v[112:115], v[136:139], v[100:103]
	ds_read_b128 v[152:155], v14 offset:4096
	v_mfma_f32_16x16x32_bf16 v[96:99], v[112:115], v[140:143], v[96:99]
	ds_read_b128 v[156:159], v14 offset:6144
	v_mfma_f32_16x16x32_bf16 v[92:95], v[116:119], v[128:131], v[92:95]
	ds_read_b128 v[160:163], v15
	v_mfma_f32_16x16x32_bf16 v[88:91], v[116:119], v[132:135], v[88:91]
	ds_read_b128 v[164:167], v15 offset:2048
	v_mfma_f32_16x16x32_bf16 v[84:87], v[116:119], v[136:139], v[84:87]
	ds_read_b128 v[224:227], v15 offset:4096
	v_mfma_f32_16x16x32_bf16 v[80:83], v[116:119], v[140:143], v[80:83]
	ds_read_b128 v[228:231], v15 offset:6144
	v_mfma_f32_16x16x32_bf16 v[76:79], v[120:123], v[128:131], v[76:79]
	v_mfma_f32_16x16x32_bf16 v[72:75], v[120:123], v[132:135], v[72:75]
	v_mfma_f32_16x16x32_bf16 v[68:71], v[120:123], v[136:139], v[68:71]
	v_mfma_f32_16x16x32_bf16 v[64:67], v[120:123], v[140:143], v[64:67]
	v_mfma_f32_16x16x32_bf16 v[60:63], v[124:127], v[128:131], v[60:63]
	v_mfma_f32_16x16x32_bf16 v[56:59], v[124:127], v[132:135], v[56:59]
	v_mfma_f32_16x16x32_bf16 v[52:55], v[124:127], v[136:139], v[52:55]
	v_mfma_f32_16x16x32_bf16 v[48:51], v[124:127], v[140:143], v[48:51]
	s_mov_b32 s5, s4
	s_add_u32 s4, s4, 0xc000
	s_sub_u32 vcc_lo, s4, 0x24000
	s_cselect_b32 s4, s4, vcc_lo
	s_waitcnt lgkmcnt(0)
	v_mfma_f32_16x16x32_bf16 v[108:111], v[144:147], v[160:163], v[108:111]
	v_mfma_f32_16x16x32_bf16 v[104:107], v[144:147], v[164:167], v[104:107]
	v_mfma_f32_16x16x32_bf16 v[100:103], v[144:147], v[224:227], v[100:103]
	v_mfma_f32_16x16x32_bf16 v[96:99], v[144:147], v[228:231], v[96:99]
	v_mfma_f32_16x16x32_bf16 v[92:95], v[148:151], v[160:163], v[92:95]
	v_mfma_f32_16x16x32_bf16 v[88:91], v[148:151], v[164:167], v[88:91]
	v_mfma_f32_16x16x32_bf16 v[84:87], v[148:151], v[224:227], v[84:87]
	v_mfma_f32_16x16x32_bf16 v[80:83], v[148:151], v[228:231], v[80:83]
	v_mfma_f32_16x16x32_bf16 v[76:79], v[152:155], v[160:163], v[76:79]
	v_mfma_f32_16x16x32_bf16 v[72:75], v[152:155], v[164:167], v[72:75]
	v_mfma_f32_16x16x32_bf16 v[68:71], v[152:155], v[224:227], v[68:71]
	v_mfma_f32_16x16x32_bf16 v[64:67], v[152:155], v[228:231], v[64:67]
	v_mfma_f32_16x16x32_bf16 v[60:63], v[156:159], v[160:163], v[60:63]
	v_mfma_f32_16x16x32_bf16 v[56:59], v[156:159], v[164:167], v[56:59]
	v_mfma_f32_16x16x32_bf16 v[52:55], v[156:159], v[224:227], v[52:55]
	v_mfma_f32_16x16x32_bf16 v[48:51], v[156:159], v[228:231], v[48:51]
	s_and_b64 vcc, exec, s[10:11]
	s_nop 7
	s_branch .LBB0_1559

	.amdhsa_kernel _Z14fwd_megakernel6Params
		.amdhsa_group_segment_fixed_size 8208
		.amdhsa_private_segment_fixed_size 0
		.amdhsa_kernarg_size 488
		.amdhsa_user_sgpr_count 2
		.amdhsa_user_sgpr_dispatch_ptr 0
		.amdhsa_user_sgpr_queue_ptr 0
		.amdhsa_user_sgpr_kernarg_segment_ptr 1
		.amdhsa_user_sgpr_dispatch_id 0
		.amdhsa_user_sgpr_kernarg_preload_length 0
		.amdhsa_user_sgpr_kernarg_preload_offset 0
		.amdhsa_user_sgpr_private_segment_size 0
		.amdhsa_uses_dynamic_stack 0
		.amdhsa_enable_private_segment 0
		.amdhsa_system_sgpr_workgroup_id_x 1
		.amdhsa_system_sgpr_workgroup_id_y 0
		.amdhsa_system_sgpr_workgroup_id_z 0
		.amdhsa_system_sgpr_workgroup_info 0
		.amdhsa_system_vgpr_workitem_id 2
		.amdhsa_next_free_vgpr 256
		.amdhsa_next_free_sgpr 102
		.amdhsa_accum_offset 256
		.amdhsa_reserve_vcc 1
		.amdhsa_float_round_mode_32 0
		.amdhsa_float_round_mode_16_64 0
		.amdhsa_float_denorm_mode_32 3
		.amdhsa_float_denorm_mode_16_64 3
		.amdhsa_dx10_clamp 1
		.amdhsa_ieee_mode 1
		.amdhsa_fp16_overflow 0
		.amdhsa_tg_split 0
		.amdhsa_exception_fp_ieee_invalid_op 0
		.amdhsa_exception_fp_denorm_src 0
		.amdhsa_exception_fp_ieee_div_zero 0
		.amdhsa_exception_fp_ieee_overflow 0
		.amdhsa_exception_fp_ieee_underflow 0
		.amdhsa_exception_fp_ieee_inexact 0
		.amdhsa_exception_int_div_zero 0
	.end_amdhsa_kernel

amdhsa.kernels:
  - .agpr_count:     0
    .args:
      - .offset:         0
        .size:           232
        .value_kind:     by_value
      - .offset:         232
        .size:           4
        .value_kind:     hidden_block_count_x
      - .offset:         236
        .size:           4
        .value_kind:     hidden_block_count_y
      - .offset:         240
        .size:           4
        .value_kind:     hidden_block_count_z
      - .offset:         244
        .size:           2
        .value_kind:     hidden_group_size_x
      - .offset:         246
        .size:           2
        .value_kind:     hidden_group_size_y
      - .offset:         248
        .size:           2
        .value_kind:     hidden_group_size_z
      - .offset:         250
        .size:           2
        .value_kind:     hidden_remainder_x
      - .offset:         252
        .size:           2
        .value_kind:     hidden_remainder_y
      - .offset:         254
        .size:           2
        .value_kind:     hidden_remainder_z
      - .offset:         272
        .size:           8
        .value_kind:     hidden_global_offset_x
      - .offset:         280
        .size:           8
        .value_kind:     hidden_global_offset_y
      - .offset:         288
        .size:           8
        .value_kind:     hidden_global_offset_z
      - .offset:         296
        .size:           2
        .value_kind:     hidden_grid_dims
      - .offset:         320
        .size:           8
        .value_kind:     hidden_multigrid_sync_arg
      - .offset:         352
        .size:           4
        .value_kind:     hidden_dynamic_lds_size
    .group_segment_fixed_size: 8208
    .kernarg_segment_align: 8
    .kernarg_segment_size: 488
    .language:       OpenCL C
    .language_version:
      - 2
      - 0
    .max_flat_workgroup_size: 512
    .name:           _Z14fwd_megakernel6Params
    .private_segment_fixed_size: 0
    .sgpr_count:     108
    .sgpr_spill_count: 278
    .symbol:         _Z14fwd_megakernel6Params.kd
    .uniform_work_group_size: 1
    .uses_dynamic_stack: false
    .vgpr_count:     256
    .vgpr_spill_count: 0
    .wavefront_size: 64
